# v9 + GEMM tiles: accumulator zeroing (128 v_mov per tile) removed, first K-iteration peeled with srcC=0
# speedup vs baseline: 1.0056x; 1.0056x over previous
; #define PG8_STAGE(bufoff, gbase, voff) do { _Pragma("unroll") for (int _i = 0; _i < 2; ++_i) \
;         __builtin_amdgcn_global_load_lds((const unsigned*)((const char*)(gbase) + (voff)[_i]), (LAS unsigned*)(lds + (bufoff) + ldsw + _i * 8192), 16, 0, 0); } while (0)
; #define PG8_LDA(dst, b, h) do { _Pragma("unroll") for (int m = 0; m < 4; ++m) _Pragma("unroll") for (int k = 0; k < 2; ++k) dst[m][k] = *(const LAS bf16x8*)(lds + PG8_SA(b, h) + aoff + m * 2048 + k * 1024); } while (0)
; #define PG8_LDB(dst, b, h) do { _Pragma("unroll") for (int n = 0; n < 2; ++n) _Pragma("unroll") for (int k = 0; k < 2; ++k) dst[n][k] = *(const LAS bf16x8*)(lds + PG8_SB(b, h) + boff + n * 2048 + k * 1024); } while (0)
; #define PG8_WAIT_V(n) asm volatile("s_waitcnt vmcnt(" #n ")" ::: "memory")
; #define PG8_WAIT_L(n) asm volatile("s_waitcnt lgkmcnt(" #n ")" ::: "memory")
; template <class Epi, class Sched>
; __device__ __forceinline__ void gemm_phase(const int wv, LAS unsigned char* lds, const Gemm g, const Sched& S, const Epi& E) {
;     ...
;         for (int t = 0; t < nt; t += 2) {
;             const bool last = (t == nt - 2);
;             const char* a1 = cA + (size_t)(t + 1) * kstepA;
;             const char* a2 = last ? nA : cA + (size_t)(t + 2) * kstepA; const char* b2 = last ? nB : cB + (size_t)(t + 2) * kstep;
;             const char* a3 = a2 + kstepA; const char* b3 = b2 + kstep;
;             if (last && has_next) S.a_ready(nxt);
;             PG8_LDB(B0, 0, 0); PG8_SCHED; PG8_LDA(At, 0, 0); PG8_STAGE(PG8_SA(1, 1), a1 + hstepA, voffA);
;             PG8_WAIT_L(8); PG8_BAR; PG8_WAIT_L(0); PG8_MMA(0, 0, At, B0); PG8_BAR; PG8_SCHED;
;             PG8_LDB(B1, 0, 1); PG8_STAGE(PG8_SB(0, 0), b2, voffB);
;             PG8_BAR; PG8_WAIT_L(0); PG8_MMA(0, 1, At, B1); PG8_BAR;
;             PG8_LDA(At, 0, 1); PG8_STAGE(PG8_SA(0, 0), a2, voffA);
;             PG8_BAR; PG8_WAIT_L(0); PG8_MMA(1, 0, At, B0); PG8_BAR; PG8_SCHED;
;             PG8_STAGE(PG8_SB(0, 1), b2 + hstepB, voffB);
;             PG8_WAIT_V(6); PG8_BAR; PG8_MMA(1, 1, At, B1); PG8_BAR;
;     ...
; #pragma unroll
;         for (int a = 0; a < 2; ++a)
; #pragma unroll
;             for (int b = 0; b < 2; ++b)
; #pragma unroll
;                 for (int m = 0; m < 4; ++m)
; #pragma unroll
;                     for (int n = 0; n < 2; ++n) acc[a][b][m][n] = (f32x4){0.f, 0.f, 0.f, 0.f};
.LBB0_146:
	s_ashr_i32 s15, s14, 31
	s_xor_b64 s[18:19], s[26:27], -1
	s_lshl_b64 s[16:17], s[14:15], 19
	s_add_u32 s16, s42, s16
	s_addc_u32 s17, s43, s17
	s_and_b64 s[20:21], s[26:27], exec
	s_cselect_b32 s1, s17, s23
	s_cselect_b32 s3, s16, s22
	s_ashr_i32 s13, s12, 31
	s_lshl_b64 s[20:21], s[12:13], 19
	s_add_u32 s20, s6, s20
	s_addc_u32 s21, s7, s21
	s_and_b64 s[26:27], s[26:27], exec
	s_cselect_b32 s13, s21, s25
	s_cselect_b32 s15, s20, s24
	s_add_u32 s22, s22, 0x40080
	s_addc_u32 s23, s23, 0
	s_add_u32 s28, s24, 0x100
	s_addc_u32 s29, s25, 0
	s_mov_b32 s30, -2
	s_add_u32 s24, s22, 0xfffc0080
	s_addc_u32 s25, s23, -1
	s_add_i32 s31, 0, 0x10000
	v_add_u32_e32 v150, s31, v152
	ds_read_b128 v[142:145], v150
	ds_read_b128 v[146:149], v150 offset:1024
	ds_read_b128 v[160:163], v150 offset:2048
	ds_read_b128 v[164:167], v150 offset:3072
	s_cmp_eq_u32 s30, 12
	s_cselect_b32 s27, s1, s25
	s_cselect_b32 s26, s3, s24
	s_cselect_b32 s25, s13, s29
	s_cselect_b32 s24, s15, s28
	v_lshl_add_u64 v[150:151], s[22:23], 0, v[138:139]
	s_add_i32 m0, s45, 0xc000
	ds_read_b128 v[168:171], v158
	ds_read_b128 v[172:175], v158 offset:1024
	ds_read_b128 v[180:183], v158 offset:2048
	ds_read_b128 v[192:195], v158 offset:3072
	ds_read_b128 v[196:199], v158 offset:4096
	ds_read_b128 v[200:203], v158 offset:5120
	ds_read_b128 v[204:207], v158 offset:6144
	ds_read_b128 v[208:211], v158 offset:7168
	global_load_lds_dwordx4 v[150:151], off
	v_lshl_add_u64 v[150:151], s[22:23], 0, v[140:141]
	s_add_i32 m0, s45, 0xe000
	s_nop 0
	global_load_lds_dwordx4 v[150:151], off
	s_waitcnt lgkmcnt(8)
	s_barrier
	s_waitcnt lgkmcnt(0)
	s_setprio 1
	s_waitcnt lgkmcnt(0)
	v_mfma_f32_16x16x32_bf16 v[126:129], v[142:145], v[168:171], 0
	v_mfma_f32_16x16x32_bf16 v[122:125], v[160:163], v[168:171], 0
	v_mfma_f32_16x16x32_bf16 v[110:113], v[142:145], v[180:183], 0
	v_mfma_f32_16x16x32_bf16 v[106:109], v[160:163], v[180:183], 0
	v_mfma_f32_16x16x32_bf16 v[94:97], v[142:145], v[196:199], 0
	v_mfma_f32_16x16x32_bf16 v[90:93], v[160:163], v[196:199], 0
	v_mfma_f32_16x16x32_bf16 v[78:81], v[142:145], v[204:207], 0
	v_mfma_f32_16x16x32_bf16 v[74:77], v[160:163], v[204:207], 0
	v_mfma_f32_16x16x32_bf16 v[126:129], v[146:149], v[172:175], v[126:129]
	v_mfma_f32_16x16x32_bf16 v[122:125], v[164:167], v[172:175], v[122:125]
	v_mfma_f32_16x16x32_bf16 v[110:113], v[146:149], v[192:195], v[110:113]
	v_mfma_f32_16x16x32_bf16 v[106:109], v[164:167], v[192:195], v[106:109]
	v_mfma_f32_16x16x32_bf16 v[94:97], v[146:149], v[200:203], v[94:97]
	v_mfma_f32_16x16x32_bf16 v[90:93], v[164:167], v[200:203], v[90:93]
	v_mfma_f32_16x16x32_bf16 v[78:81], v[146:149], v[208:211], v[78:81]
	v_mfma_f32_16x16x32_bf16 v[74:77], v[164:167], v[208:211], v[74:77]
	s_setprio 0
	s_barrier
	s_add_i32 s52, 0, 0x14000
	v_add_u32_e32 v150, s52, v152
	s_add_i32 s31, s31, s44
	ds_read_b128 v[212:215], v150
	ds_read_b128 v[216:219], v150 offset:1024
	ds_read_b128 v[220:223], v150 offset:2048
	ds_read_b128 v[224:227], v150 offset:3072
	v_lshl_add_u64 v[150:151], s[24:25], 0, v[132:133]
	s_mov_b32 m0, s31
	v_lshl_add_u64 v[176:177], s[24:25], 0, v[136:137]
	global_load_lds_dwordx4 v[150:151], off
	s_add_i32 m0, s31, 0x2000
	s_nop 0
	global_load_lds_dwordx4 v[176:177], off
	s_barrier
	s_waitcnt lgkmcnt(0)
	s_setprio 1
	s_waitcnt lgkmcnt(0)
	v_mfma_f32_16x16x32_bf16 v[118:121], v[212:215], v[168:171], 0
	v_mfma_f32_16x16x32_bf16 v[114:117], v[220:223], v[168:171], 0
	v_mfma_f32_16x16x32_bf16 v[102:105], v[212:215], v[180:183], 0
	v_mfma_f32_16x16x32_bf16 v[98:101], v[220:223], v[180:183], 0
	v_mfma_f32_16x16x32_bf16 v[86:89], v[212:215], v[196:199], 0
	v_mfma_f32_16x16x32_bf16 v[82:85], v[220:223], v[196:199], 0
	v_mfma_f32_16x16x32_bf16 v[70:73], v[212:215], v[204:207], 0
	v_mfma_f32_16x16x32_bf16 v[66:69], v[220:223], v[204:207], 0
	v_mfma_f32_16x16x32_bf16 v[118:121], v[216:219], v[172:175], v[118:121]
	v_mfma_f32_16x16x32_bf16 v[114:117], v[224:227], v[172:175], v[114:117]
	v_mfma_f32_16x16x32_bf16 v[102:105], v[216:219], v[192:195], v[102:105]
	v_mfma_f32_16x16x32_bf16 v[98:101], v[224:227], v[192:195], v[98:101]
	v_mfma_f32_16x16x32_bf16 v[86:89], v[216:219], v[200:203], v[86:89]
	v_mfma_f32_16x16x32_bf16 v[82:85], v[224:227], v[200:203], v[82:85]
	v_mfma_f32_16x16x32_bf16 v[70:73], v[216:219], v[208:211], v[70:73]
	v_mfma_f32_16x16x32_bf16 v[66:69], v[224:227], v[208:211], v[66:69]
	s_setprio 0
	s_mov_b32 m0, s45
	v_lshl_add_u64 v[228:229], s[26:27], 0, v[130:131]
	s_barrier
	ds_read_b128 v[168:171], v158 offset:16384
	ds_read_b128 v[172:175], v158 offset:17408
	ds_read_b128 v[180:183], v158 offset:18432
	ds_read_b128 v[192:195], v158 offset:19456
	ds_read_b128 v[196:199], v158 offset:20480
	ds_read_b128 v[200:203], v158 offset:21504
	ds_read_b128 v[204:207], v158 offset:22528
	ds_read_b128 v[208:211], v158 offset:23552
	global_load_lds_dwordx4 v[228:229], off
	v_lshl_add_u64 v[230:231], s[26:27], 0, v[134:135]
	s_mov_b32 m0, s46
	s_nop 0
	global_load_lds_dwordx4 v[230:231], off
	s_barrier
	s_waitcnt lgkmcnt(0)
	s_setprio 1
	s_waitcnt lgkmcnt(0)
	v_mfma_f32_16x16x32_bf16 v[62:65], v[142:145], v[168:171], 0
	v_mfma_f32_16x16x32_bf16 v[58:61], v[160:163], v[168:171], 0
	v_mfma_f32_16x16x32_bf16 v[46:49], v[142:145], v[180:183], 0
	v_mfma_f32_16x16x32_bf16 v[42:45], v[160:163], v[180:183], 0
	v_mfma_f32_16x16x32_bf16 v[30:33], v[142:145], v[196:199], 0
	v_mfma_f32_16x16x32_bf16 v[26:29], v[160:163], v[196:199], 0
	v_mfma_f32_16x16x32_bf16 v[14:17], v[142:145], v[204:207], 0
	v_mfma_f32_16x16x32_bf16 v[10:13], v[160:163], v[204:207], 0
	v_mfma_f32_16x16x32_bf16 v[62:65], v[146:149], v[172:175], v[62:65]
	v_mfma_f32_16x16x32_bf16 v[58:61], v[164:167], v[172:175], v[58:61]
	v_mfma_f32_16x16x32_bf16 v[46:49], v[146:149], v[192:195], v[46:49]
	v_mfma_f32_16x16x32_bf16 v[42:45], v[164:167], v[192:195], v[42:45]
	v_mfma_f32_16x16x32_bf16 v[30:33], v[146:149], v[200:203], v[30:33]
	v_mfma_f32_16x16x32_bf16 v[26:29], v[164:167], v[200:203], v[26:29]
	v_mfma_f32_16x16x32_bf16 v[14:17], v[146:149], v[208:211], v[14:17]
	v_mfma_f32_16x16x32_bf16 v[10:13], v[164:167], v[208:211], v[10:13]
	s_setprio 0
	s_barrier
; #define PG8_STAGE(bufoff, gbase, voff) do { _Pragma("unroll") for (int _i = 0; _i < 2; ++_i) \
;         __builtin_amdgcn_global_load_lds((const unsigned*)((const char*)(gbase) + (voff)[_i]), (LAS unsigned*)(lds + (bufoff) + ldsw + _i * 8192), 16, 0, 0); } while (0)
; #define PG8_LDA(dst, b, h) do { _Pragma("unroll") for (int m = 0; m < 4; ++m) _Pragma("unroll") for (int k = 0; k < 2; ++k) dst[m][k] = *(const LAS bf16x8*)(lds + PG8_SA(b, h) + aoff + m * 2048 + k * 1024); } while (0)
; #define PG8_LDB(dst, b, h) do { _Pragma("unroll") for (int n = 0; n < 2; ++n) _Pragma("unroll") for (int k = 0; k < 2; ++k) dst[n][k] = *(const LAS bf16x8*)(lds + PG8_SB(b, h) + boff + n * 2048 + k * 1024); } while (0)
; #define PG8_MMA(ai, bj, At, Bt) do { __builtin_amdgcn_s_setprio(1); _Pragma("unroll") for (int m = 0; m < 4; ++m) _Pragma("unroll") for (int n = 0; n < 2; ++n) _Pragma("unroll") for (int k = 0; k < 2; ++k) \
;         acc[ai][bj][m][n] = __builtin_amdgcn_mfma_f32_16x16x32_bf16(Bt[n][k], At[m][k], acc[ai][bj][m][n], 0, 0, 0); __builtin_amdgcn_s_setprio(0); } while (0)
; #define PG8_WAIT_V(n) asm volatile("s_waitcnt vmcnt(" #n ")" ::: "memory")
; #define PG8_WAIT_L(n) asm volatile("s_waitcnt lgkmcnt(" #n ")" ::: "memory")
; #define PG8_BAR __builtin_amdgcn_s_barrier()
; #define PG8_SCHED __builtin_amdgcn_sched_barrier(0)
; template <class Epi, class Sched>
; __device__ __forceinline__ void gemm_phase(const int wv, LAS unsigned char* lds, const Gemm g, const Sched& S, const Epi& E) {
;     ...
;             PG8_STAGE(PG8_SB(0, 1), b2 + hstepB, voffB);
;             PG8_WAIT_V(6); PG8_BAR; PG8_MMA(1, 1, At, B1); PG8_BAR;
;             PG8_LDB(B0, 1, 0); PG8_SCHED; PG8_LDA(At, 1, 0); PG8_STAGE(PG8_SA(0, 1), a2 + hstepA, voffA);
;             PG8_WAIT_L(8); PG8_BAR; PG8_WAIT_L(0); PG8_MMA(0, 0, At, B0); PG8_BAR; PG8_SCHED;
;             PG8_LDB(B1, 1, 1); PG8_STAGE(PG8_SB(1, 0), b3, voffB);
;             PG8_BAR; PG8_WAIT_L(0); PG8_MMA(0, 1, At, B1); PG8_BAR;
;             PG8_LDA(At, 1, 1); PG8_STAGE(PG8_SA(1, 0), a3, voffA);
;             PG8_BAR; PG8_WAIT_L(0); PG8_MMA(1, 0, At, B0); PG8_BAR; PG8_SCHED;
	s_add_u32 s34, s24, 0x40000
	s_addc_u32 s35, s25, 0
	s_add_i32 s31, s52, s44
	v_lshl_add_u64 v[142:143], s[34:35], 0, v[132:133]
	s_mov_b32 m0, s31
	s_nop 0
	global_load_lds_dwordx4 v[142:143], off
	v_lshl_add_u64 v[142:143], s[34:35], 0, v[136:137]
	s_add_i32 m0, s31, 0x2000
	s_nop 0
	global_load_lds_dwordx4 v[142:143], off
	s_waitcnt vmcnt(6)
	s_barrier
	s_setprio 1
	v_mfma_f32_16x16x32_bf16 v[54:57], v[212:215], v[168:171], 0
	v_mfma_f32_16x16x32_bf16 v[50:53], v[220:223], v[168:171], 0
	v_mfma_f32_16x16x32_bf16 v[38:41], v[212:215], v[180:183], 0
	v_mfma_f32_16x16x32_bf16 v[34:37], v[220:223], v[180:183], 0
	v_mfma_f32_16x16x32_bf16 v[22:25], v[212:215], v[196:199], 0
	v_mfma_f32_16x16x32_bf16 v[18:21], v[220:223], v[196:199], 0
	v_mfma_f32_16x16x32_bf16 v[6:9], v[212:215], v[204:207], 0
	v_mfma_f32_16x16x32_bf16 v[2:5], v[220:223], v[204:207], 0
	v_mfma_f32_16x16x32_bf16 v[54:57], v[216:219], v[172:175], v[54:57]
	v_mfma_f32_16x16x32_bf16 v[50:53], v[224:227], v[172:175], v[50:53]
	v_mfma_f32_16x16x32_bf16 v[38:41], v[216:219], v[192:195], v[38:41]
	v_mfma_f32_16x16x32_bf16 v[34:37], v[224:227], v[192:195], v[34:37]
	v_mfma_f32_16x16x32_bf16 v[22:25], v[216:219], v[200:203], v[22:25]
	v_mfma_f32_16x16x32_bf16 v[18:21], v[224:227], v[200:203], v[18:21]
	v_mfma_f32_16x16x32_bf16 v[6:9], v[216:219], v[208:211], v[6:9]
	v_mfma_f32_16x16x32_bf16 v[2:5], v[224:227], v[208:211], v[2:5]
	s_setprio 0
	s_add_i32 s31, 0, 0x18000
	v_add_u32_e32 v159, s31, v152
	s_barrier
	ds_read_b128 v[142:145], v159
	ds_read_b128 v[146:149], v159 offset:1024
	ds_read_b128 v[160:163], v159 offset:2048
	ds_read_b128 v[164:167], v159 offset:3072
	s_add_u32 s26, s26, 0x40000
	s_addc_u32 s27, s27, 0
	s_mov_b32 m0, s47
	v_lshl_add_u64 v[212:213], s[26:27], 0, v[130:131]
	ds_read_b128 v[168:171], v158 offset:32768
	ds_read_b128 v[172:175], v158 offset:33792
	ds_read_b128 v[180:183], v158 offset:34816
	ds_read_b128 v[192:195], v158 offset:35840
	ds_read_b128 v[196:199], v158 offset:36864
	ds_read_b128 v[200:203], v158 offset:37888
	ds_read_b128 v[204:207], v158 offset:38912
	ds_read_b128 v[208:211], v158 offset:39936
	global_load_lds_dwordx4 v[212:213], off
	v_lshl_add_u64 v[212:213], s[26:27], 0, v[134:135]
	s_mov_b32 m0, s48
	s_nop 0
	global_load_lds_dwordx4 v[212:213], off
	s_waitcnt lgkmcnt(8)
	s_barrier
	s_waitcnt lgkmcnt(0)
	s_setprio 1
	s_waitcnt lgkmcnt(0)
	v_mfma_f32_16x16x32_bf16 v[126:129], v[142:145], v[168:171], v[126:129]
	v_mfma_f32_16x16x32_bf16 v[122:125], v[160:163], v[168:171], v[122:125]
	v_mfma_f32_16x16x32_bf16 v[110:113], v[142:145], v[180:183], v[110:113]
	v_mfma_f32_16x16x32_bf16 v[106:109], v[160:163], v[180:183], v[106:109]
	v_mfma_f32_16x16x32_bf16 v[94:97], v[142:145], v[196:199], v[94:97]
	v_mfma_f32_16x16x32_bf16 v[90:93], v[160:163], v[196:199], v[90:93]
	v_mfma_f32_16x16x32_bf16 v[78:81], v[142:145], v[204:207], v[78:81]
	v_mfma_f32_16x16x32_bf16 v[74:77], v[160:163], v[204:207], v[74:77]
	v_mfma_f32_16x16x32_bf16 v[126:129], v[146:149], v[172:175], v[126:129]
	v_mfma_f32_16x16x32_bf16 v[122:125], v[164:167], v[172:175], v[122:125]
	v_mfma_f32_16x16x32_bf16 v[110:113], v[146:149], v[192:195], v[110:113]
	v_mfma_f32_16x16x32_bf16 v[106:109], v[164:167], v[192:195], v[106:109]
	v_mfma_f32_16x16x32_bf16 v[94:97], v[146:149], v[200:203], v[94:97]
	v_mfma_f32_16x16x32_bf16 v[90:93], v[164:167], v[200:203], v[90:93]
	v_mfma_f32_16x16x32_bf16 v[78:81], v[146:149], v[208:211], v[78:81]
	v_mfma_f32_16x16x32_bf16 v[74:77], v[164:167], v[208:211], v[74:77]
	s_setprio 0
	s_barrier
	s_add_i32 s26, 0, 0x1c000
	s_add_i32 s27, s31, s44
	v_add_u32_e32 v159, s26, v152
	v_lshl_add_u64 v[150:151], v[150:151], 0, s[88:89]
	s_mov_b32 m0, s27
	ds_read_b128 v[212:215], v159
	ds_read_b128 v[216:219], v159 offset:1024
	ds_read_b128 v[220:223], v159 offset:2048
	ds_read_b128 v[224:227], v159 offset:3072
	global_load_lds_dwordx4 v[150:151], off
	v_lshl_add_u64 v[150:151], v[176:177], 0, s[88:89]
	s_add_i32 m0, s27, 0x2000
	s_nop 0
	global_load_lds_dwordx4 v[150:151], off
	s_barrier
; #define PG8_STAGE(bufoff, gbase, voff) do { _Pragma("unroll") for (int _i = 0; _i < 2; ++_i) \
;         __builtin_amdgcn_global_load_lds((const unsigned*)((const char*)(gbase) + (voff)[_i]), (LAS unsigned*)(lds + (bufoff) + ldsw + _i * 8192), 16, 0, 0); } while (0)
; #define PG8_LDA(dst, b, h) do { _Pragma("unroll") for (int m = 0; m < 4; ++m) _Pragma("unroll") for (int k = 0; k < 2; ++k) dst[m][k] = *(const LAS bf16x8*)(lds + PG8_SA(b, h) + aoff + m * 2048 + k * 1024); } while (0)
; #define PG8_LDB(dst, b, h) do { _Pragma("unroll") for (int n = 0; n < 2; ++n) _Pragma("unroll") for (int k = 0; k < 2; ++k) dst[n][k] = *(const LAS bf16x8*)(lds + PG8_SB(b, h) + boff + n * 2048 + k * 1024); } while (0)
; #define PG8_MMA(ai, bj, At, Bt) do { __builtin_amdgcn_s_setprio(1); _Pragma("unroll") for (int m = 0; m < 4; ++m) _Pragma("unroll") for (int n = 0; n < 2; ++n) _Pragma("unroll") for (int k = 0; k < 2; ++k) \
;         acc[ai][bj][m][n] = __builtin_amdgcn_mfma_f32_16x16x32_bf16(Bt[n][k], At[m][k], acc[ai][bj][m][n], 0, 0, 0); __builtin_amdgcn_s_setprio(0); } while (0)
; #define PG8_WAIT_V(n) asm volatile("s_waitcnt vmcnt(" #n ")" ::: "memory")
; #define PG8_WAIT_L(n) asm volatile("s_waitcnt lgkmcnt(" #n ")" ::: "memory")
; #define PG8_BAR __builtin_amdgcn_s_barrier()
; #define PG8_SCHED __builtin_amdgcn_sched_barrier(0)
; template <class Epi, class Sched>
; __device__ __forceinline__ void gemm_phase(const int wv, LAS unsigned char* lds, const Gemm g, const Sched& S, const Epi& E) {
;     ...
;             PG8_WAIT_L(8); PG8_BAR; PG8_WAIT_L(0); PG8_MMA(0, 0, At, B0); PG8_BAR; PG8_SCHED;
;             PG8_LDB(B1, 1, 1); PG8_STAGE(PG8_SB(1, 0), b3, voffB);
;             PG8_BAR; PG8_WAIT_L(0); PG8_MMA(0, 1, At, B1); PG8_BAR;
;             PG8_LDA(At, 1, 1); PG8_STAGE(PG8_SA(1, 0), a3, voffA);
;             PG8_BAR; PG8_WAIT_L(0); PG8_MMA(1, 0, At, B0); PG8_BAR; PG8_SCHED;
;             PG8_STAGE(PG8_SB(1, 1), b3 + hstepB, voffB);
;             PG8_WAIT_V(6); PG8_BAR; PG8_MMA(1, 1, At, B1); PG8_BAR;
;         }
	s_waitcnt lgkmcnt(0)
	s_setprio 1
	s_waitcnt lgkmcnt(0)
	v_mfma_f32_16x16x32_bf16 v[118:121], v[212:215], v[168:171], v[118:121]
	v_mfma_f32_16x16x32_bf16 v[114:117], v[220:223], v[168:171], v[114:117]
	v_mfma_f32_16x16x32_bf16 v[102:105], v[212:215], v[180:183], v[102:105]
	v_mfma_f32_16x16x32_bf16 v[98:101], v[220:223], v[180:183], v[98:101]
	v_mfma_f32_16x16x32_bf16 v[86:89], v[212:215], v[196:199], v[86:89]
	v_mfma_f32_16x16x32_bf16 v[82:85], v[220:223], v[196:199], v[82:85]
	v_mfma_f32_16x16x32_bf16 v[70:73], v[212:215], v[204:207], v[70:73]
	v_mfma_f32_16x16x32_bf16 v[66:69], v[220:223], v[204:207], v[66:69]
	v_mfma_f32_16x16x32_bf16 v[118:121], v[216:219], v[172:175], v[118:121]
	v_mfma_f32_16x16x32_bf16 v[114:117], v[224:227], v[172:175], v[114:117]
	v_mfma_f32_16x16x32_bf16 v[102:105], v[216:219], v[192:195], v[102:105]
	v_mfma_f32_16x16x32_bf16 v[98:101], v[224:227], v[192:195], v[98:101]
	v_mfma_f32_16x16x32_bf16 v[86:89], v[216:219], v[200:203], v[86:89]
	v_mfma_f32_16x16x32_bf16 v[82:85], v[224:227], v[200:203], v[82:85]
	v_mfma_f32_16x16x32_bf16 v[70:73], v[216:219], v[208:211], v[70:73]
	v_mfma_f32_16x16x32_bf16 v[66:69], v[224:227], v[208:211], v[66:69]
	s_setprio 0
	s_mov_b32 m0, s49
	v_lshl_add_u64 v[150:151], v[228:229], 0, s[88:89]
	s_barrier
	ds_read_b128 v[168:171], v158 offset:49152
	ds_read_b128 v[172:175], v158 offset:50176
	ds_read_b128 v[180:183], v158 offset:51200
	ds_read_b128 v[192:195], v158 offset:52224
	ds_read_b128 v[196:199], v158 offset:53248
	ds_read_b128 v[200:203], v158 offset:54272
	ds_read_b128 v[204:207], v158 offset:55296
	ds_read_b128 v[208:211], v158 offset:56320
	global_load_lds_dwordx4 v[150:151], off
	v_lshl_add_u64 v[150:151], v[230:231], 0, s[88:89]
	s_mov_b32 m0, s50
	s_nop 0
	global_load_lds_dwordx4 v[150:151], off
	s_barrier
	s_waitcnt lgkmcnt(0)
	s_setprio 1
	s_waitcnt lgkmcnt(0)
	v_mfma_f32_16x16x32_bf16 v[62:65], v[142:145], v[168:171], v[62:65]
	v_mfma_f32_16x16x32_bf16 v[58:61], v[160:163], v[168:171], v[58:61]
	v_mfma_f32_16x16x32_bf16 v[46:49], v[142:145], v[180:183], v[46:49]
	v_mfma_f32_16x16x32_bf16 v[42:45], v[160:163], v[180:183], v[42:45]
	v_mfma_f32_16x16x32_bf16 v[30:33], v[142:145], v[196:199], v[30:33]
	v_mfma_f32_16x16x32_bf16 v[26:29], v[160:163], v[196:199], v[26:29]
	v_mfma_f32_16x16x32_bf16 v[14:17], v[142:145], v[204:207], v[14:17]
	v_mfma_f32_16x16x32_bf16 v[10:13], v[160:163], v[204:207], v[10:13]
	v_mfma_f32_16x16x32_bf16 v[62:65], v[146:149], v[172:175], v[62:65]
	v_mfma_f32_16x16x32_bf16 v[58:61], v[164:167], v[172:175], v[58:61]
	v_mfma_f32_16x16x32_bf16 v[46:49], v[146:149], v[192:195], v[46:49]
	v_mfma_f32_16x16x32_bf16 v[42:45], v[164:167], v[192:195], v[42:45]
	v_mfma_f32_16x16x32_bf16 v[30:33], v[146:149], v[200:203], v[30:33]
	v_mfma_f32_16x16x32_bf16 v[26:29], v[164:167], v[200:203], v[26:29]
	v_mfma_f32_16x16x32_bf16 v[14:17], v[146:149], v[208:211], v[14:17]
	v_mfma_f32_16x16x32_bf16 v[10:13], v[164:167], v[208:211], v[10:13]
	s_setprio 0
	s_barrier
	s_add_u32 s24, s24, 0x40080
	s_addc_u32 s25, s25, 0
	s_add_i32 s26, s26, s44
	v_lshl_add_u64 v[142:143], s[24:25], 0, v[132:133]
	s_mov_b32 m0, s26
	s_nop 0
	global_load_lds_dwordx4 v[142:143], off
	v_lshl_add_u64 v[142:143], s[24:25], 0, v[136:137]
	s_add_i32 m0, s26, 0x2000
	s_nop 0
	global_load_lds_dwordx4 v[142:143], off
	s_waitcnt vmcnt(6)
	s_barrier
	s_setprio 1
	v_mfma_f32_16x16x32_bf16 v[54:57], v[212:215], v[168:171], v[54:57]
	v_mfma_f32_16x16x32_bf16 v[50:53], v[220:223], v[168:171], v[50:53]
	v_mfma_f32_16x16x32_bf16 v[38:41], v[212:215], v[180:183], v[38:41]
	v_mfma_f32_16x16x32_bf16 v[34:37], v[220:223], v[180:183], v[34:37]
	v_mfma_f32_16x16x32_bf16 v[22:25], v[212:215], v[196:199], v[22:25]
	v_mfma_f32_16x16x32_bf16 v[18:21], v[220:223], v[196:199], v[18:21]
	v_mfma_f32_16x16x32_bf16 v[6:9], v[212:215], v[204:207], v[6:9]
	v_mfma_f32_16x16x32_bf16 v[2:5], v[220:223], v[204:207], v[2:5]
	v_mfma_f32_16x16x32_bf16 v[54:57], v[216:219], v[172:175], v[54:57]
	v_mfma_f32_16x16x32_bf16 v[50:53], v[224:227], v[172:175], v[50:53]
	v_mfma_f32_16x16x32_bf16 v[38:41], v[216:219], v[192:195], v[38:41]
	v_mfma_f32_16x16x32_bf16 v[34:37], v[224:227], v[192:195], v[34:37]
	v_mfma_f32_16x16x32_bf16 v[22:25], v[216:219], v[200:203], v[22:25]
	v_mfma_f32_16x16x32_bf16 v[18:21], v[224:227], v[200:203], v[18:21]
	v_mfma_f32_16x16x32_bf16 v[6:9], v[216:219], v[208:211], v[6:9]
	v_mfma_f32_16x16x32_bf16 v[2:5], v[224:227], v[208:211], v[2:5]
	s_setprio 0
	s_add_i32 s30, s30, 2
	s_add_u32 s22, s22, 0x100
	s_addc_u32 s23, s23, 0
	s_add_u32 s28, s28, 0x100
	s_addc_u32 s29, s29, 0
	s_cmp_gt_u32 s30, 13
	s_barrier
	s_cbranch_scc0 .LBB0_147
	s_branch .Lpeel_exit_t147

;     __device__ __forceinline__ void operator()(const f32x4 (&acc)[2][2][4][2], const Unit& u, int wr, int wc, int fr, int fq) const {
;         const int row0 = (u.pm >> 6) * TB + (u.pm & 63) * 256 + wr * 64 + fr; const int pn = u.pn;
;         bf16_t* base; int ld, colt, act;
;         if (pn < 34) { base = qkvr; ld = QKVR_LD; colt = pn * 256; act = 0; }
;         else if (pn < 42) { base = gr; ld = 2048; colt = (pn - 34) * 256; act = 1; }
;         else { base = gates; ld = 2048; colt = (pn - 42) * 256; act = 2; }
.Lpeel_exit_t147:
	s_cmp_gt_i32 s0, 33
	s_mov_b64 s[22:23], -1
	s_cbranch_scc0 .LBB0_153
	s_lshl_b32 s1, s0, 8
	s_cmp_gt_u32 s0, 41
	s_mov_b64 s[28:29], -1
	s_mov_b64 s[24:25], -1
	s_cbranch_scc0 .LBB0_151
	s_add_i32 s3, s1, 0xffffd600
	s_mov_b64 s[24:25], 0

; #define PG8_STAGE(bufoff, gbase, voff) do { _Pragma("unroll") for (int _i = 0; _i < 2; ++_i) \
;         __builtin_amdgcn_global_load_lds((const unsigned*)((const char*)(gbase) + (voff)[_i]), (LAS unsigned*)(lds + (bufoff) + ldsw + _i * 8192), 16, 0, 0); } while (0)
; #define PG8_LDA(dst, b, h) do { _Pragma("unroll") for (int m = 0; m < 4; ++m) _Pragma("unroll") for (int k = 0; k < 2; ++k) dst[m][k] = *(const LAS bf16x8*)(lds + PG8_SA(b, h) + aoff + m * 2048 + k * 1024); } while (0)
; #define PG8_LDB(dst, b, h) do { _Pragma("unroll") for (int n = 0; n < 2; ++n) _Pragma("unroll") for (int k = 0; k < 2; ++k) dst[n][k] = *(const LAS bf16x8*)(lds + PG8_SB(b, h) + boff + n * 2048 + k * 1024); } while (0)
; #define PG8_MMA(ai, bj, At, Bt) do { __builtin_amdgcn_s_setprio(1); _Pragma("unroll") for (int m = 0; m < 4; ++m) _Pragma("unroll") for (int n = 0; n < 2; ++n) _Pragma("unroll") for (int k = 0; k < 2; ++k) \
;         acc[ai][bj][m][n] = __builtin_amdgcn_mfma_f32_16x16x32_bf16(Bt[n][k], At[m][k], acc[ai][bj][m][n], 0, 0, 0); __builtin_amdgcn_s_setprio(0); } while (0)
; template <class Epi, class Sched>
; __device__ __forceinline__ void gemm_phase(const int wv, LAS unsigned char* lds, const Gemm g, const Sched& S, const Epi& E) {
;     ...
;         const bool has_next = S.next(ui + 1, nxt);
;         const char* nA = has_next ? (const char*)g.A + (size_t)nxt.pm * tstepA : cA; const char* nB = has_next ? (const char*)g.Bt + (size_t)nxt.pn * tstepB : cB;
;         for (int t = 0; t < nt; t += 2) {
;             const bool last = (t == nt - 2);
;             const char* a1 = cA + (size_t)(t + 1) * kstepA;
;             const char* a2 = last ? nA : cA + (size_t)(t + 2) * kstepA; const char* b2 = last ? nB : cB + (size_t)(t + 2) * kstep;
;             const char* a3 = a2 + kstepA; const char* b3 = b2 + kstep;
;             if (last && has_next) S.a_ready(nxt);
;             PG8_LDB(B0, 0, 0); PG8_SCHED; PG8_LDA(At, 0, 0); PG8_STAGE(PG8_SA(1, 1), a1 + hstepA, voffA);
;             PG8_WAIT_L(8); PG8_BAR; PG8_WAIT_L(0); PG8_MMA(0, 0, At, B0); PG8_BAR; PG8_SCHED;
;             PG8_LDB(B1, 0, 1); PG8_STAGE(PG8_SB(0, 0), b2, voffB);
;             PG8_BAR; PG8_WAIT_L(0); PG8_MMA(0, 1, At, B1); PG8_BAR;
;             PG8_LDA(At, 0, 1); PG8_STAGE(PG8_SA(0, 0), a2, voffA);
;             PG8_BAR; PG8_WAIT_L(0); PG8_MMA(1, 0, At, B0); PG8_BAR; PG8_SCHED;
.LBB0_576:
	s_ashr_i32 s13, s12, 31
	v_cmp_lt_i64_e32 vcc, s[14:15], v[140:141]
	s_lshl_b64 s[14:15], s[12:13], 18
	s_add_u32 s14, s27, s14
	s_addc_u32 s15, s28, s15
	s_and_b64 s[16:17], vcc, exec
	s_cselect_b32 s13, s15, s21
	s_cselect_b32 s42, s14, s20
	s_ashr_i32 s11, s10, 31
	s_lshl_b64 s[16:17], s[10:11], 18
	s_add_u32 s16, s29, s16
	s_addc_u32 s17, s30, s17
	s_and_b64 s[24:25], vcc, exec
	s_cselect_b32 s11, s17, s23
	s_cselect_b32 s43, s16, s22
	s_add_u32 s20, s20, 0x20080
	s_addc_u32 s21, s21, 0
	s_add_u32 s44, s22, 0x100
	s_addc_u32 s45, s23, 0
	s_mov_b32 s46, -2
	ds_read_b128 v[144:147], v151
	ds_read_b128 v[154:157], v151 offset:1024
	ds_read_b128 v[158:161], v151 offset:2048
	ds_read_b128 v[162:165], v151 offset:3072
	s_add_u32 s22, s20, 0xfffe0080
	s_addc_u32 s23, s21, -1
	s_cmp_eq_u32 s46, 4
	s_cselect_b32 s25, s13, s23
	s_cselect_b32 s24, s42, s22
	s_cselect_b32 s23, s11, s45
	s_cselect_b32 s22, s43, s44
	v_lshl_add_u64 v[200:201], s[20:21], 0, v[136:137]
	s_add_i32 m0, s19, 0xc000
	ds_read_b128 v[166:169], v152
	ds_read_b128 v[170:173], v152 offset:1024
	ds_read_b128 v[174:177], v152 offset:2048
	ds_read_b128 v[180:183], v152 offset:3072
	ds_read_b128 v[184:187], v152 offset:4096
	ds_read_b128 v[188:191], v152 offset:5120
	ds_read_b128 v[192:195], v152 offset:6144
	ds_read_b128 v[196:199], v152 offset:7168
	global_load_lds_dwordx4 v[200:201], off
	v_lshl_add_u64 v[200:201], s[20:21], 0, v[138:139]
	s_add_i32 m0, s19, 0xe000
	s_nop 0
	global_load_lds_dwordx4 v[200:201], off
	s_waitcnt lgkmcnt(8)
	s_barrier
	s_waitcnt lgkmcnt(0)
	s_setprio 1
	s_waitcnt lgkmcnt(0)
	v_mfma_f32_16x16x32_bf16 v[124:127], v[144:147], v[166:169], 0
	v_mfma_f32_16x16x32_bf16 v[120:123], v[158:161], v[166:169], 0
	v_mfma_f32_16x16x32_bf16 v[116:119], v[144:147], v[174:177], 0
	v_mfma_f32_16x16x32_bf16 v[104:107], v[158:161], v[174:177], 0
	v_mfma_f32_16x16x32_bf16 v[96:99], v[144:147], v[184:187], 0
	v_mfma_f32_16x16x32_bf16 v[88:91], v[158:161], v[184:187], 0
	v_mfma_f32_16x16x32_bf16 v[80:83], v[144:147], v[192:195], 0
	v_mfma_f32_16x16x32_bf16 v[72:75], v[158:161], v[192:195], 0
	v_mfma_f32_16x16x32_bf16 v[124:127], v[154:157], v[170:173], v[124:127]
	v_mfma_f32_16x16x32_bf16 v[120:123], v[162:165], v[170:173], v[120:123]
	v_mfma_f32_16x16x32_bf16 v[116:119], v[154:157], v[180:183], v[116:119]
	v_mfma_f32_16x16x32_bf16 v[104:107], v[162:165], v[180:183], v[104:107]
	v_mfma_f32_16x16x32_bf16 v[96:99], v[154:157], v[188:191], v[96:99]
	v_mfma_f32_16x16x32_bf16 v[88:91], v[162:165], v[188:191], v[88:91]
	v_mfma_f32_16x16x32_bf16 v[80:83], v[154:157], v[196:199], v[80:83]
	v_mfma_f32_16x16x32_bf16 v[72:75], v[162:165], v[196:199], v[72:75]
	s_setprio 0
	s_barrier
	s_add_i32 s47, s39, s31
	v_lshl_add_u64 v[216:217], s[22:23], 0, v[130:131]
	s_mov_b32 m0, s47
	ds_read_b128 v[200:203], v153
	ds_read_b128 v[204:207], v153 offset:1024
	ds_read_b128 v[208:211], v153 offset:2048
	ds_read_b128 v[212:215], v153 offset:3072
	global_load_lds_dwordx4 v[216:217], off
	v_lshl_add_u64 v[218:219], s[22:23], 0, v[134:135]
	s_add_i32 m0, s47, 0x2000
	s_nop 0
	global_load_lds_dwordx4 v[218:219], off
	s_barrier
	s_waitcnt lgkmcnt(0)
	s_setprio 1
	s_waitcnt lgkmcnt(0)
	v_mfma_f32_16x16x32_bf16 v[112:115], v[200:203], v[166:169], 0
	v_mfma_f32_16x16x32_bf16 v[108:111], v[208:211], v[166:169], 0
	v_mfma_f32_16x16x32_bf16 v[100:103], v[200:203], v[174:177], 0
	v_mfma_f32_16x16x32_bf16 v[92:95], v[208:211], v[174:177], 0
	v_mfma_f32_16x16x32_bf16 v[84:87], v[200:203], v[184:187], 0
	v_mfma_f32_16x16x32_bf16 v[76:79], v[208:211], v[184:187], 0
	v_mfma_f32_16x16x32_bf16 v[68:71], v[200:203], v[192:195], 0
	v_mfma_f32_16x16x32_bf16 v[64:67], v[208:211], v[192:195], 0
	v_mfma_f32_16x16x32_bf16 v[112:115], v[204:207], v[170:173], v[112:115]
	v_mfma_f32_16x16x32_bf16 v[108:111], v[212:215], v[170:173], v[108:111]
	v_mfma_f32_16x16x32_bf16 v[100:103], v[204:207], v[180:183], v[100:103]
	v_mfma_f32_16x16x32_bf16 v[92:95], v[212:215], v[180:183], v[92:95]
	v_mfma_f32_16x16x32_bf16 v[84:87], v[204:207], v[188:191], v[84:87]
	v_mfma_f32_16x16x32_bf16 v[76:79], v[212:215], v[188:191], v[76:79]
	v_mfma_f32_16x16x32_bf16 v[68:71], v[204:207], v[196:199], v[68:71]
	v_mfma_f32_16x16x32_bf16 v[64:67], v[212:215], v[196:199], v[64:67]
	s_setprio 0
	s_mov_b32 m0, s19
	v_lshl_add_u64 v[220:221], s[24:25], 0, v[128:129]
	s_barrier
	ds_read_b128 v[166:169], v152 offset:16384
	ds_read_b128 v[170:173], v152 offset:17408
	ds_read_b128 v[174:177], v152 offset:18432
	ds_read_b128 v[180:183], v152 offset:19456
	ds_read_b128 v[184:187], v152 offset:20480
	ds_read_b128 v[188:191], v152 offset:21504
	ds_read_b128 v[192:195], v152 offset:22528
	ds_read_b128 v[196:199], v152 offset:23552
	global_load_lds_dwordx4 v[220:221], off
	v_lshl_add_u64 v[222:223], s[24:25], 0, v[132:133]
	s_mov_b32 m0, s33
	s_nop 0
	global_load_lds_dwordx4 v[222:223], off
	s_barrier
	s_waitcnt lgkmcnt(0)
	s_setprio 1
	s_waitcnt lgkmcnt(0)
	v_mfma_f32_16x16x32_bf16 v[60:63], v[144:147], v[166:169], 0
	v_mfma_f32_16x16x32_bf16 v[56:59], v[158:161], v[166:169], 0
	v_mfma_f32_16x16x32_bf16 v[48:51], v[144:147], v[174:177], 0
	v_mfma_f32_16x16x32_bf16 v[40:43], v[158:161], v[174:177], 0
	v_mfma_f32_16x16x32_bf16 v[32:35], v[144:147], v[184:187], 0
	v_mfma_f32_16x16x32_bf16 v[24:27], v[158:161], v[184:187], 0
	v_mfma_f32_16x16x32_bf16 v[16:19], v[144:147], v[192:195], 0
	v_mfma_f32_16x16x32_bf16 v[8:11], v[158:161], v[192:195], 0
	v_mfma_f32_16x16x32_bf16 v[60:63], v[154:157], v[170:173], v[60:63]
	v_mfma_f32_16x16x32_bf16 v[56:59], v[162:165], v[170:173], v[56:59]
	v_mfma_f32_16x16x32_bf16 v[48:51], v[154:157], v[180:183], v[48:51]
	v_mfma_f32_16x16x32_bf16 v[40:43], v[162:165], v[180:183], v[40:43]
	v_mfma_f32_16x16x32_bf16 v[32:35], v[154:157], v[188:191], v[32:35]
	v_mfma_f32_16x16x32_bf16 v[24:27], v[162:165], v[188:191], v[24:27]
	v_mfma_f32_16x16x32_bf16 v[16:19], v[154:157], v[196:199], v[16:19]
	v_mfma_f32_16x16x32_bf16 v[8:11], v[162:165], v[196:199], v[8:11]
	s_setprio 0
	s_barrier
; #define PG8_STAGE(bufoff, gbase, voff) do { _Pragma("unroll") for (int _i = 0; _i < 2; ++_i) \
;         __builtin_amdgcn_global_load_lds((const unsigned*)((const char*)(gbase) + (voff)[_i]), (LAS unsigned*)(lds + (bufoff) + ldsw + _i * 8192), 16, 0, 0); } while (0)
; #define PG8_LDA(dst, b, h) do { _Pragma("unroll") for (int m = 0; m < 4; ++m) _Pragma("unroll") for (int k = 0; k < 2; ++k) dst[m][k] = *(const LAS bf16x8*)(lds + PG8_SA(b, h) + aoff + m * 2048 + k * 1024); } while (0)
; #define PG8_LDB(dst, b, h) do { _Pragma("unroll") for (int n = 0; n < 2; ++n) _Pragma("unroll") for (int k = 0; k < 2; ++k) dst[n][k] = *(const LAS bf16x8*)(lds + PG8_SB(b, h) + boff + n * 2048 + k * 1024); } while (0)
; #define PG8_MMA(ai, bj, At, Bt) do { __builtin_amdgcn_s_setprio(1); _Pragma("unroll") for (int m = 0; m < 4; ++m) _Pragma("unroll") for (int n = 0; n < 2; ++n) _Pragma("unroll") for (int k = 0; k < 2; ++k) \
;         acc[ai][bj][m][n] = __builtin_amdgcn_mfma_f32_16x16x32_bf16(Bt[n][k], At[m][k], acc[ai][bj][m][n], 0, 0, 0); __builtin_amdgcn_s_setprio(0); } while (0)
; #define PG8_WAIT_V(n) asm volatile("s_waitcnt vmcnt(" #n ")" ::: "memory")
; #define PG8_WAIT_L(n) asm volatile("s_waitcnt lgkmcnt(" #n ")" ::: "memory")
; #define PG8_BAR __builtin_amdgcn_s_barrier()
; #define PG8_SCHED __builtin_amdgcn_sched_barrier(0)
; template <class Epi, class Sched>
; __device__ __forceinline__ void gemm_phase(const int wv, LAS unsigned char* lds, const Gemm g, const Sched& S, const Epi& E) {
;     ...
;             PG8_STAGE(PG8_SB(0, 1), b2 + hstepB, voffB);
;             PG8_WAIT_V(6); PG8_BAR; PG8_MMA(1, 1, At, B1); PG8_BAR;
;             PG8_LDB(B0, 1, 0); PG8_SCHED; PG8_LDA(At, 1, 0); PG8_STAGE(PG8_SA(0, 1), a2 + hstepA, voffA);
;             PG8_WAIT_L(8); PG8_BAR; PG8_WAIT_L(0); PG8_MMA(0, 0, At, B0); PG8_BAR; PG8_SCHED;
;             PG8_LDB(B1, 1, 1); PG8_STAGE(PG8_SB(1, 0), b3, voffB);
;             PG8_BAR; PG8_WAIT_L(0); PG8_MMA(0, 1, At, B1); PG8_BAR;
	s_add_u32 s48, s22, 0x20000
	s_addc_u32 s49, s23, 0
	s_add_i32 s47, s40, s31
	v_lshl_add_u64 v[144:145], s[48:49], 0, v[130:131]
	s_mov_b32 m0, s47
	s_nop 0
	global_load_lds_dwordx4 v[144:145], off
	v_lshl_add_u64 v[144:145], s[48:49], 0, v[134:135]
	s_add_i32 m0, s47, 0x2000
	s_nop 0
	global_load_lds_dwordx4 v[144:145], off
	s_waitcnt vmcnt(6)
	s_barrier
	s_setprio 1
	v_mfma_f32_16x16x32_bf16 v[52:55], v[200:203], v[166:169], 0
	v_mfma_f32_16x16x32_bf16 v[44:47], v[208:211], v[166:169], 0
	v_mfma_f32_16x16x32_bf16 v[36:39], v[200:203], v[174:177], 0
	v_mfma_f32_16x16x32_bf16 v[28:31], v[208:211], v[174:177], 0
	v_mfma_f32_16x16x32_bf16 v[20:23], v[200:203], v[184:187], 0
	v_mfma_f32_16x16x32_bf16 v[12:15], v[208:211], v[184:187], 0
	v_mfma_f32_16x16x32_bf16 v[4:7], v[200:203], v[192:195], 0
	v_mfma_f32_16x16x32_bf16 v[0:3], v[208:211], v[192:195], 0
	v_mfma_f32_16x16x32_bf16 v[52:55], v[204:207], v[170:173], v[52:55]
	v_mfma_f32_16x16x32_bf16 v[44:47], v[212:215], v[170:173], v[44:47]
	v_mfma_f32_16x16x32_bf16 v[36:39], v[204:207], v[180:183], v[36:39]
	v_mfma_f32_16x16x32_bf16 v[28:31], v[212:215], v[180:183], v[28:31]
	v_mfma_f32_16x16x32_bf16 v[20:23], v[204:207], v[188:191], v[20:23]
	v_mfma_f32_16x16x32_bf16 v[12:15], v[212:215], v[188:191], v[12:15]
	v_mfma_f32_16x16x32_bf16 v[4:7], v[204:207], v[196:199], v[4:7]
	v_mfma_f32_16x16x32_bf16 v[0:3], v[212:215], v[196:199], v[0:3]
	s_setprio 0
	s_add_i32 s47, 0, 0x18000
	v_add_u32_e32 v162, s47, v149
	s_barrier
	ds_read_b128 v[144:147], v162
	ds_read_b128 v[154:157], v162 offset:1024
	ds_read_b128 v[158:161], v162 offset:2048
	ds_read_b128 v[162:165], v162 offset:3072
	s_add_u32 s24, s24, 0x20000
	s_addc_u32 s25, s25, 0
	s_mov_b32 m0, s34
	v_lshl_add_u64 v[200:201], s[24:25], 0, v[128:129]
	ds_read_b128 v[166:169], v152 offset:32768
	ds_read_b128 v[170:173], v152 offset:33792
	ds_read_b128 v[174:177], v152 offset:34816
	ds_read_b128 v[180:183], v152 offset:35840
	ds_read_b128 v[184:187], v152 offset:36864
	ds_read_b128 v[188:191], v152 offset:37888
	ds_read_b128 v[192:195], v152 offset:38912
	ds_read_b128 v[196:199], v152 offset:39936
	global_load_lds_dwordx4 v[200:201], off
	v_lshl_add_u64 v[200:201], s[24:25], 0, v[132:133]
	s_mov_b32 m0, s35
	s_nop 0
	global_load_lds_dwordx4 v[200:201], off
	s_waitcnt lgkmcnt(8)
	s_barrier
	s_waitcnt lgkmcnt(0)
	s_setprio 1
	s_waitcnt lgkmcnt(0)
	v_mfma_f32_16x16x32_bf16 v[124:127], v[144:147], v[166:169], v[124:127]
	v_mfma_f32_16x16x32_bf16 v[120:123], v[158:161], v[166:169], v[120:123]
	v_mfma_f32_16x16x32_bf16 v[116:119], v[144:147], v[174:177], v[116:119]
	v_mfma_f32_16x16x32_bf16 v[104:107], v[158:161], v[174:177], v[104:107]
	v_mfma_f32_16x16x32_bf16 v[96:99], v[144:147], v[184:187], v[96:99]
	v_mfma_f32_16x16x32_bf16 v[88:91], v[158:161], v[184:187], v[88:91]
	v_mfma_f32_16x16x32_bf16 v[80:83], v[144:147], v[192:195], v[80:83]
	v_mfma_f32_16x16x32_bf16 v[72:75], v[158:161], v[192:195], v[72:75]
	v_mfma_f32_16x16x32_bf16 v[124:127], v[154:157], v[170:173], v[124:127]
	v_mfma_f32_16x16x32_bf16 v[120:123], v[162:165], v[170:173], v[120:123]
	v_mfma_f32_16x16x32_bf16 v[116:119], v[154:157], v[180:183], v[116:119]
	v_mfma_f32_16x16x32_bf16 v[104:107], v[162:165], v[180:183], v[104:107]
	v_mfma_f32_16x16x32_bf16 v[96:99], v[154:157], v[188:191], v[96:99]
	v_mfma_f32_16x16x32_bf16 v[88:91], v[162:165], v[188:191], v[88:91]
	v_mfma_f32_16x16x32_bf16 v[80:83], v[154:157], v[196:199], v[80:83]
	v_mfma_f32_16x16x32_bf16 v[72:75], v[162:165], v[196:199], v[72:75]
	s_setprio 0
	s_barrier
	s_add_i32 s24, 0, 0x1c000
	s_add_i32 s25, s47, s31
	v_add_u32_e32 v212, s24, v149
	v_lshl_add_u64 v[216:217], v[216:217], 0, s[8:9]
	s_mov_b32 m0, s25
	ds_read_b128 v[200:203], v212
	ds_read_b128 v[204:207], v212 offset:1024
	ds_read_b128 v[208:211], v212 offset:2048
	ds_read_b128 v[212:215], v212 offset:3072
	global_load_lds_dwordx4 v[216:217], off
	v_lshl_add_u64 v[216:217], v[218:219], 0, s[8:9]
	s_add_i32 m0, s25, 0x2000
	s_nop 0
	global_load_lds_dwordx4 v[216:217], off
	s_barrier
; #define PG8_STAGE(bufoff, gbase, voff) do { _Pragma("unroll") for (int _i = 0; _i < 2; ++_i) \
;         __builtin_amdgcn_global_load_lds((const unsigned*)((const char*)(gbase) + (voff)[_i]), (LAS unsigned*)(lds + (bufoff) + ldsw + _i * 8192), 16, 0, 0); } while (0)
; #define PG8_LDA(dst, b, h) do { _Pragma("unroll") for (int m = 0; m < 4; ++m) _Pragma("unroll") for (int k = 0; k < 2; ++k) dst[m][k] = *(const LAS bf16x8*)(lds + PG8_SA(b, h) + aoff + m * 2048 + k * 1024); } while (0)
; #define PG8_MMA(ai, bj, At, Bt) do { __builtin_amdgcn_s_setprio(1); _Pragma("unroll") for (int m = 0; m < 4; ++m) _Pragma("unroll") for (int n = 0; n < 2; ++n) _Pragma("unroll") for (int k = 0; k < 2; ++k) \
;         acc[ai][bj][m][n] = __builtin_amdgcn_mfma_f32_16x16x32_bf16(Bt[n][k], At[m][k], acc[ai][bj][m][n], 0, 0, 0); __builtin_amdgcn_s_setprio(0); } while (0)
; #define PG8_WAIT_V(n) asm volatile("s_waitcnt vmcnt(" #n ")" ::: "memory")
; #define PG8_WAIT_L(n) asm volatile("s_waitcnt lgkmcnt(" #n ")" ::: "memory")
; #define PG8_BAR __builtin_amdgcn_s_barrier()
; #define PG8_SCHED __builtin_amdgcn_sched_barrier(0)
; template <class Epi, class Sched>
; __device__ __forceinline__ void gemm_phase(const int wv, LAS unsigned char* lds, const Gemm g, const Sched& S, const Epi& E) {
;     ...
;             PG8_BAR; PG8_WAIT_L(0); PG8_MMA(0, 1, At, B1); PG8_BAR;
;             PG8_LDA(At, 1, 1); PG8_STAGE(PG8_SA(1, 0), a3, voffA);
;             PG8_BAR; PG8_WAIT_L(0); PG8_MMA(1, 0, At, B0); PG8_BAR; PG8_SCHED;
;             PG8_STAGE(PG8_SB(1, 1), b3 + hstepB, voffB);
;             PG8_WAIT_V(6); PG8_BAR; PG8_MMA(1, 1, At, B1); PG8_BAR;
;         }
	s_waitcnt lgkmcnt(0)
	s_setprio 1
	s_waitcnt lgkmcnt(0)
	v_mfma_f32_16x16x32_bf16 v[112:115], v[200:203], v[166:169], v[112:115]
	v_mfma_f32_16x16x32_bf16 v[108:111], v[208:211], v[166:169], v[108:111]
	v_mfma_f32_16x16x32_bf16 v[100:103], v[200:203], v[174:177], v[100:103]
	v_mfma_f32_16x16x32_bf16 v[92:95], v[208:211], v[174:177], v[92:95]
	v_mfma_f32_16x16x32_bf16 v[84:87], v[200:203], v[184:187], v[84:87]
	v_mfma_f32_16x16x32_bf16 v[76:79], v[208:211], v[184:187], v[76:79]
	v_mfma_f32_16x16x32_bf16 v[68:71], v[200:203], v[192:195], v[68:71]
	v_mfma_f32_16x16x32_bf16 v[64:67], v[208:211], v[192:195], v[64:67]
	v_mfma_f32_16x16x32_bf16 v[112:115], v[204:207], v[170:173], v[112:115]
	v_mfma_f32_16x16x32_bf16 v[108:111], v[212:215], v[170:173], v[108:111]
	v_mfma_f32_16x16x32_bf16 v[100:103], v[204:207], v[180:183], v[100:103]
	v_mfma_f32_16x16x32_bf16 v[92:95], v[212:215], v[180:183], v[92:95]
	v_mfma_f32_16x16x32_bf16 v[84:87], v[204:207], v[188:191], v[84:87]
	v_mfma_f32_16x16x32_bf16 v[76:79], v[212:215], v[188:191], v[76:79]
	v_mfma_f32_16x16x32_bf16 v[68:71], v[204:207], v[196:199], v[68:71]
	v_mfma_f32_16x16x32_bf16 v[64:67], v[212:215], v[196:199], v[64:67]
	s_setprio 0
	s_mov_b32 m0, s37
	v_lshl_add_u64 v[216:217], v[220:221], 0, s[8:9]
	s_barrier
	ds_read_b128 v[166:169], v152 offset:49152
	ds_read_b128 v[170:173], v152 offset:50176
	ds_read_b128 v[174:177], v152 offset:51200
	ds_read_b128 v[180:183], v152 offset:52224
	ds_read_b128 v[184:187], v152 offset:53248
	ds_read_b128 v[188:191], v152 offset:54272
	ds_read_b128 v[192:195], v152 offset:55296
	ds_read_b128 v[196:199], v152 offset:56320
	global_load_lds_dwordx4 v[216:217], off
	v_lshl_add_u64 v[216:217], v[222:223], 0, s[8:9]
	s_mov_b32 m0, s38
	s_nop 0
	global_load_lds_dwordx4 v[216:217], off
	s_barrier
	s_waitcnt lgkmcnt(0)
	s_setprio 1
	s_waitcnt lgkmcnt(0)
	v_mfma_f32_16x16x32_bf16 v[60:63], v[144:147], v[166:169], v[60:63]
	v_mfma_f32_16x16x32_bf16 v[56:59], v[158:161], v[166:169], v[56:59]
	v_mfma_f32_16x16x32_bf16 v[48:51], v[144:147], v[174:177], v[48:51]
	v_mfma_f32_16x16x32_bf16 v[40:43], v[158:161], v[174:177], v[40:43]
	v_mfma_f32_16x16x32_bf16 v[32:35], v[144:147], v[184:187], v[32:35]
	v_mfma_f32_16x16x32_bf16 v[24:27], v[158:161], v[184:187], v[24:27]
	v_mfma_f32_16x16x32_bf16 v[16:19], v[144:147], v[192:195], v[16:19]
	v_mfma_f32_16x16x32_bf16 v[8:11], v[158:161], v[192:195], v[8:11]
	v_mfma_f32_16x16x32_bf16 v[60:63], v[154:157], v[170:173], v[60:63]
	v_mfma_f32_16x16x32_bf16 v[56:59], v[162:165], v[170:173], v[56:59]
	v_mfma_f32_16x16x32_bf16 v[48:51], v[154:157], v[180:183], v[48:51]
	v_mfma_f32_16x16x32_bf16 v[40:43], v[162:165], v[180:183], v[40:43]
	v_mfma_f32_16x16x32_bf16 v[32:35], v[154:157], v[188:191], v[32:35]
	v_mfma_f32_16x16x32_bf16 v[24:27], v[162:165], v[188:191], v[24:27]
	v_mfma_f32_16x16x32_bf16 v[16:19], v[154:157], v[196:199], v[16:19]
	v_mfma_f32_16x16x32_bf16 v[8:11], v[162:165], v[196:199], v[8:11]
	s_setprio 0
	s_barrier
	s_add_u32 s22, s22, 0x20080
	s_addc_u32 s23, s23, 0
	s_add_i32 s24, s24, s31
	v_lshl_add_u64 v[144:145], s[22:23], 0, v[130:131]
	s_mov_b32 m0, s24
	s_nop 0
	global_load_lds_dwordx4 v[144:145], off
	v_lshl_add_u64 v[144:145], s[22:23], 0, v[134:135]
	s_add_i32 m0, s24, 0x2000
	s_nop 0
	global_load_lds_dwordx4 v[144:145], off
	s_waitcnt vmcnt(6)
	s_barrier
	s_setprio 1
	v_mfma_f32_16x16x32_bf16 v[52:55], v[200:203], v[166:169], v[52:55]
	v_mfma_f32_16x16x32_bf16 v[44:47], v[208:211], v[166:169], v[44:47]
	v_mfma_f32_16x16x32_bf16 v[36:39], v[200:203], v[174:177], v[36:39]
	v_mfma_f32_16x16x32_bf16 v[28:31], v[208:211], v[174:177], v[28:31]
	v_mfma_f32_16x16x32_bf16 v[20:23], v[200:203], v[184:187], v[20:23]
	v_mfma_f32_16x16x32_bf16 v[12:15], v[208:211], v[184:187], v[12:15]
	v_mfma_f32_16x16x32_bf16 v[4:7], v[200:203], v[192:195], v[4:7]
	v_mfma_f32_16x16x32_bf16 v[0:3], v[208:211], v[192:195], v[0:3]
	v_mfma_f32_16x16x32_bf16 v[52:55], v[204:207], v[170:173], v[52:55]
	v_mfma_f32_16x16x32_bf16 v[44:47], v[212:215], v[170:173], v[44:47]
	v_mfma_f32_16x16x32_bf16 v[36:39], v[204:207], v[180:183], v[36:39]
	v_mfma_f32_16x16x32_bf16 v[28:31], v[212:215], v[180:183], v[28:31]
	v_mfma_f32_16x16x32_bf16 v[20:23], v[204:207], v[188:191], v[20:23]
	v_mfma_f32_16x16x32_bf16 v[12:15], v[212:215], v[188:191], v[12:15]
	v_mfma_f32_16x16x32_bf16 v[4:7], v[204:207], v[196:199], v[4:7]
	v_mfma_f32_16x16x32_bf16 v[0:3], v[212:215], v[196:199], v[0:3]
	s_setprio 0
	s_add_i32 s46, s46, 2
	s_add_u32 s20, s20, 0x100
	s_addc_u32 s21, s21, 0
	s_add_u32 s44, s44, 0x100
	s_addc_u32 s45, s45, 0
	s_cmp_gt_u32 s46, 5
	s_barrier
	s_cbranch_scc0 .LBB0_577
	s_branch .Lpeel_exit_t577

; template <class Epi, class Sched>
; __device__ __forceinline__ void gemm_phase(const int wv, LAS unsigned char* lds, const Gemm g, const Sched& S, const Epi& E) {
;     ...
;         E(acc, cur, wr, wc, fr, fq); S.done(cur);
;         if (!has_next) break;
; #pragma unroll
;         for (int a = 0; a < 2; ++a)
; #pragma unroll
;             for (int b = 0; b < 2; ++b)
; #pragma unroll
;                 for (int m = 0; m < 4; ++m)
; #pragma unroll
;                     for (int n = 0; n < 2; ++n) acc[a][b][m][n] = (f32x4){0.f, 0.f, 0.f, 0.f};
;         cur = nxt; cA = nA; cB = nB; ++ui;
;     __device__ __forceinline__ void operator()(const f32x4 (&acc)[2][2][4][2], const Unit& u, int wr, int wc, int fr, int fq) const {
;         const int row0 = u.pm * 256 + wr * 64 + fr; const int col0 = u.pn * 256 + wc * 32 + 8 * fq;
; #pragma unroll
;         for (int ai = 0; ai < 2; ++ai) {
;             u32x4 gv[4][2], yv[4][2];
; #pragma unroll
;             for (int m = 0; m < 4; ++m)
; #pragma unroll
;                 for (int bj = 0; bj < 2; ++bj) {
;                     const int row = row0 + ai * 128 + m * 16, col = col0 + bj * 128;
;                     gv[m][bj] = *(const u32x4*)(gates + (size_t)row * 2048 + SECOND * 1024 + col);
;                     if (SECOND) yv[m][bj] = *(const u32x4*)(Y + (size_t)row * 1024 + col);
;                 }
; #pragma unroll
;             for (int m = 0; m < 4; ++m)
; #pragma unroll
;                 for (int bj = 0; bj < 2; ++bj) {
;                     const int row = row0 + ai * 128 + m * 16, col = col0 + bj * 128;
;                     const u32x4 g = gv[m][bj];
;                     const f32x4 a0 = acc[ai][bj][m][0], a1 = acc[ai][bj][m][1];
;                     float r[8] = {a0[0] * bflo(g.x), a0[1] * bfhi(g.x), a0[2] * bflo(g.y), a0[3] * bfhi(g.y), a1[0] * bflo(g.z), a1[1] * bfhi(g.z), a1[2] * bflo(g.w), a1[3] * bfhi(g.w)};
;                     if (SECOND) { const u32x4 y = yv[m][bj];
;                         r[0] += bflo(y.x); r[1] += bfhi(y.x); r[2] += bflo(y.y); r[3] += bfhi(y.y); r[4] += bflo(y.z); r[5] += bfhi(y.z); r[6] += bflo(y.w); r[7] += bfhi(y.w); }
;                     u32x4 w; w.x = cvt_pk_bf16(r[0], r[1]); w.y = cvt_pk_bf16(r[2], r[3]); w.z = cvt_pk_bf16(r[4], r[5]); w.w = cvt_pk_bf16(r[6], r[7]);
;                     *(u32x4*)(Y + (size_t)row * 1024 + col) = w;
.Lpeel_exit_t577:
	v_lshl_add_u32 v146, s18, 8, v148
	v_lshl_or_b32 v144, s41, 8, v150
	v_ashrrev_i32_e32 v147, 31, v146
	v_or_b32_e32 v170, 16, v146
	v_ashrrev_i32_e32 v145, 31, v144
	v_lshlrev_b64 v[154:155], 12, v[146:147]
	v_ashrrev_i32_e32 v171, 31, v170
	v_lshl_add_u64 v[154:155], s[4:5], 0, v[154:155]
	v_lshlrev_b64 v[144:145], 1, v[144:145]
	v_lshlrev_b64 v[162:163], 12, v[170:171]
	v_lshl_add_u64 v[158:159], v[154:155], 0, v[144:145]
	v_lshl_add_u64 v[162:163], s[4:5], 0, v[162:163]
	global_load_dwordx4 v[154:157], v[158:159], off
	s_nop 0
	global_load_dwordx4 v[158:161], v[158:159], off offset:256
	v_lshl_add_u64 v[166:167], v[162:163], 0, v[144:145]
	global_load_dwordx4 v[162:165], v[166:167], off
	v_or_b32_e32 v188, 32, v146
	global_load_dwordx4 v[166:169], v[166:167], off offset:256
	v_or_b32_e32 v190, 48, v146
	v_ashrrev_i32_e32 v189, 31, v188
	v_ashrrev_i32_e32 v191, 31, v190
	v_lshlrev_b64 v[174:175], 12, v[188:189]
	v_lshlrev_b64 v[176:177], 12, v[190:191]
	v_lshlrev_b64 v[172:173], 11, v[146:147]
	v_lshlrev_b64 v[192:193], 11, v[170:171]
	v_lshl_add_u64 v[170:171], s[4:5], 0, v[174:175]
	v_lshl_add_u64 v[174:175], s[4:5], 0, v[176:177]
	v_lshl_add_u64 v[172:173], s[2:3], 0, v[172:173]
	v_lshl_add_u64 v[176:177], v[170:171], 0, v[144:145]
	v_lshl_add_u64 v[184:185], v[174:175], 0, v[144:145]
	v_lshl_add_u64 v[194:195], v[172:173], 0, v[144:145]
	global_load_dwordx4 v[170:173], v[176:177], off
	s_nop 0
	global_load_dwordx4 v[174:177], v[176:177], off offset:256
	s_nop 0
	global_load_dwordx4 v[180:183], v[184:185], off
	s_nop 0
	global_load_dwordx4 v[184:187], v[184:185], off offset:256
	s_and_b64 vcc, exec, s[0:1]
	s_mov_b32 s41, s10
	s_mov_b32 s18, s12
	s_mov_b64 s[22:23], s[16:17]
	s_mov_b64 s[20:21], s[14:15]
	s_waitcnt vmcnt(0)
	v_lshlrev_b32_e32 v147, 16, v154
	v_lshlrev_b32_e32 v201, 16, v160
	v_and_b32_e32 v154, 0xffff0000, v154
	v_lshlrev_b32_e32 v196, 16, v155
	v_and_b32_e32 v155, 0xffff0000, v155
	v_lshlrev_b32_e32 v197, 16, v156
	v_and_b32_e32 v156, 0xffff0000, v156
	v_lshlrev_b32_e32 v198, 16, v157
	v_and_b32_e32 v157, 0xffff0000, v157
	v_and_b32_e32 v160, 0xffff0000, v160
	v_lshlrev_b32_e32 v202, 16, v161
	v_and_b32_e32 v161, 0xffff0000, v161
	v_mul_f32_e32 v124, v124, v147
	v_mul_f32_e32 v147, v108, v201
	v_lshlrev_b32_e32 v108, 16, v162
	v_lshlrev_b32_e32 v199, 16, v158
	v_and_b32_e32 v158, 0xffff0000, v158
	v_lshlrev_b32_e32 v200, 16, v159
	v_and_b32_e32 v159, 0xffff0000, v159
	v_mul_f32_e32 v125, v125, v154
	v_mul_f32_e32 v127, v127, v155
	v_mul_f32_e32 v120, v120, v197
	v_mul_f32_e32 v121, v121, v156
	v_mul_f32_e32 v123, v123, v157
	v_mul_f32_e32 v154, v109, v160
	v_mul_f32_e32 v155, v110, v202
	v_mul_f32_e32 v156, v111, v161
	v_and_b32_e32 v109, 0xffff0000, v162
	v_lshlrev_b32_e32 v110, 16, v163
	v_and_b32_e32 v111, 0xffff0000, v163
	v_lshlrev_b32_e32 v157, 16, v164
	v_mul_f32_e32 v116, v116, v108
	v_cvt_pk_bf16_f32 v108, v124, v125
	v_mul_f32_e32 v126, v126, v196
	v_mul_f32_e32 v122, v122, v198
	v_mul_f32_e32 v112, v112, v199
	v_mul_f32_e32 v113, v113, v158
	v_mul_f32_e32 v115, v115, v159
	v_lshlrev_b32_e32 v159, 16, v165
	v_mul_f32_e32 v117, v117, v109
	v_mul_f32_e32 v118, v118, v110
	v_mul_f32_e32 v119, v119, v111
	v_cvt_pk_bf16_f32 v109, v126, v127
	v_cvt_pk_bf16_f32 v110, v120, v121
	v_cvt_pk_bf16_f32 v111, v122, v123
	v_mul_f32_e32 v120, v104, v157
	global_store_dwordx4 v[194:195], v[108:111], off
	v_and_b32_e32 v104, 0xffff0000, v165
	v_mul_f32_e32 v114, v114, v200
	v_cvt_pk_bf16_f32 v108, v112, v113
	v_and_b32_e32 v158, 0xffff0000, v164
	v_cvt_pk_bf16_f32 v109, v114, v115
	v_cvt_pk_bf16_f32 v110, v147, v154
	v_cvt_pk_bf16_f32 v111, v155, v156
	global_store_dwordx4 v[194:195], v[108:111], off offset:256
	v_mul_f32_e32 v107, v107, v104
	v_mul_f32_e32 v121, v105, v158
	v_mul_f32_e32 v108, v106, v159
	v_cvt_pk_bf16_f32 v104, v116, v117
	v_cvt_pk_bf16_f32 v105, v118, v119
	v_cvt_pk_bf16_f32 v106, v120, v121
	v_cvt_pk_bf16_f32 v107, v108, v107
	v_lshl_add_u64 v[108:109], s[2:3], 0, v[192:193]
	v_lshl_add_u64 v[108:109], v[108:109], 0, v[144:145]
	global_store_dwordx4 v[108:109], v[104:107], off
	s_nop 1
	v_lshlrev_b32_e32 v104, 16, v166
	v_mul_f32_e32 v100, v100, v104
	v_and_b32_e32 v104, 0xffff0000, v166
	v_mul_f32_e32 v101, v101, v104
	v_lshlrev_b32_e32 v104, 16, v167
	v_mul_f32_e32 v102, v102, v104
	v_and_b32_e32 v104, 0xffff0000, v167
	v_mul_f32_e32 v103, v103, v104
	v_lshlrev_b32_e32 v104, 16, v168
	v_mul_f32_e32 v104, v92, v104
	v_and_b32_e32 v92, 0xffff0000, v168
	v_mul_f32_e32 v105, v93, v92
	v_lshlrev_b32_e32 v92, 16, v169
	v_mul_f32_e32 v106, v94, v92
	v_and_b32_e32 v92, 0xffff0000, v169
	v_mul_f32_e32 v95, v95, v92
	v_cvt_pk_bf16_f32 v92, v100, v101
	v_cvt_pk_bf16_f32 v93, v102, v103
	v_cvt_pk_bf16_f32 v94, v104, v105
	v_cvt_pk_bf16_f32 v95, v106, v95
	global_store_dwordx4 v[108:109], v[92:95], off offset:256
	v_add_u32_e32 v102, 0xb0, v146
	v_ashrrev_i32_e32 v103, 31, v102
	v_lshlrev_b32_e32 v94, 16, v170
	v_mul_f32_e32 v94, v96, v94
	v_lshlrev_b32_e32 v96, 16, v171
	v_and_b32_e32 v95, 0xffff0000, v170
	v_mul_f32_e32 v96, v98, v96
	v_lshlrev_b32_e32 v98, 16, v172
	v_mul_f32_e32 v95, v97, v95
	v_and_b32_e32 v97, 0xffff0000, v171
	v_mul_f32_e32 v98, v88, v98
	v_and_b32_e32 v88, 0xffff0000, v172
	v_lshlrev_b64 v[92:93], 11, v[188:189]
	v_mul_f32_e32 v97, v99, v97
	v_mul_f32_e32 v99, v89, v88
	v_lshlrev_b32_e32 v88, 16, v173
	v_mul_f32_e32 v100, v90, v88
	v_and_b32_e32 v88, 0xffff0000, v173
	v_lshl_add_u64 v[92:93], s[2:3], 0, v[92:93]
	v_mul_f32_e32 v91, v91, v88
	v_cvt_pk_bf16_f32 v88, v94, v95
	v_lshl_add_u64 v[92:93], v[92:93], 0, v[144:145]
	v_cvt_pk_bf16_f32 v89, v96, v97
; __device__ __forceinline__ unsigned cvt_pk_bf16(float lo, float hi) { unsigned r; asm volatile("v_cvt_pk_bf16_f32 %0, %1, %2" : "=v"(r) : "v"(lo), "v"(hi)); return r; }
; __device__ __forceinline__ float bflo(unsigned u) { return __uint_as_float(u << 16); }
; __device__ __forceinline__ float bfhi(unsigned u) { return __uint_as_float(u & 0xffff0000u); }
;     __device__ __forceinline__ void operator()(const f32x4 (&acc)[2][2][4][2], const Unit& u, int wr, int wc, int fr, int fq) const {
;     ...
;             for (int m = 0; m < 4; ++m)
; #pragma unroll
;                 for (int bj = 0; bj < 2; ++bj) {
;                     const int row = row0 + ai * 128 + m * 16, col = col0 + bj * 128;
;                     gv[m][bj] = *(const u32x4*)(gates + (size_t)row * 2048 + SECOND * 1024 + col);
;                     if (SECOND) yv[m][bj] = *(const u32x4*)(Y + (size_t)row * 1024 + col);
;                 }
; #pragma unroll
;             for (int m = 0; m < 4; ++m)
; #pragma unroll
;                 for (int bj = 0; bj < 2; ++bj) {
;                     const int row = row0 + ai * 128 + m * 16, col = col0 + bj * 128;
;                     const u32x4 g = gv[m][bj];
;                     const f32x4 a0 = acc[ai][bj][m][0], a1 = acc[ai][bj][m][1];
;                     float r[8] = {a0[0] * bflo(g.x), a0[1] * bfhi(g.x), a0[2] * bflo(g.y), a0[3] * bfhi(g.y), a1[0] * bflo(g.z), a1[1] * bfhi(g.z), a1[2] * bflo(g.w), a1[3] * bfhi(g.w)};
;                     if (SECOND) { const u32x4 y = yv[m][bj];
;                         r[0] += bflo(y.x); r[1] += bfhi(y.x); r[2] += bflo(y.y); r[3] += bfhi(y.y); r[4] += bflo(y.z); r[5] += bfhi(y.z); r[6] += bflo(y.w); r[7] += bfhi(y.w); }
;                     u32x4 w; w.x = cvt_pk_bf16(r[0], r[1]); w.y = cvt_pk_bf16(r[2], r[3]); w.z = cvt_pk_bf16(r[4], r[5]); w.w = cvt_pk_bf16(r[6], r[7]);
;                     *(u32x4*)(Y + (size_t)row * 1024 + col) = w;
	v_cvt_pk_bf16_f32 v90, v98, v99
	v_cvt_pk_bf16_f32 v91, v100, v91
	global_store_dwordx4 v[92:93], v[88:91], off
	v_add_u32_e32 v96, 0x80, v146
	v_ashrrev_i32_e32 v97, 31, v96
	v_lshlrev_b32_e32 v88, 16, v174
	v_mul_f32_e32 v84, v84, v88
	v_and_b32_e32 v88, 0xffff0000, v174
	v_mul_f32_e32 v85, v85, v88
	v_lshlrev_b32_e32 v88, 16, v175
	v_mul_f32_e32 v86, v86, v88
	v_and_b32_e32 v88, 0xffff0000, v175
	v_mul_f32_e32 v87, v87, v88
	v_lshlrev_b32_e32 v88, 16, v176
	v_mul_f32_e32 v88, v76, v88
	v_and_b32_e32 v76, 0xffff0000, v176
	v_mul_f32_e32 v89, v77, v76
	v_lshlrev_b32_e32 v76, 16, v177
	v_mul_f32_e32 v90, v78, v76
	v_and_b32_e32 v76, 0xffff0000, v177
	v_mul_f32_e32 v79, v79, v76
	v_cvt_pk_bf16_f32 v76, v84, v85
	v_cvt_pk_bf16_f32 v77, v86, v87
	v_cvt_pk_bf16_f32 v78, v88, v89
	v_cvt_pk_bf16_f32 v79, v90, v79
	global_store_dwordx4 v[92:93], v[76:79], off offset:256
	v_add_u32_e32 v98, 0x90, v146
	v_ashrrev_i32_e32 v99, 31, v98
	v_lshlrev_b32_e32 v78, 16, v180
	v_mul_f32_e32 v78, v80, v78
	v_lshlrev_b32_e32 v80, 16, v181
	v_and_b32_e32 v79, 0xffff0000, v180
	v_mul_f32_e32 v80, v82, v80
	v_lshlrev_b32_e32 v82, 16, v182
	v_mul_f32_e32 v79, v81, v79
	v_and_b32_e32 v81, 0xffff0000, v181
	v_mul_f32_e32 v82, v72, v82
	v_and_b32_e32 v72, 0xffff0000, v182
	v_lshlrev_b64 v[76:77], 11, v[190:191]
	v_mul_f32_e32 v81, v83, v81
	v_mul_f32_e32 v83, v73, v72
	v_lshlrev_b32_e32 v72, 16, v183
	v_mul_f32_e32 v84, v74, v72
	v_and_b32_e32 v72, 0xffff0000, v183
	v_lshl_add_u64 v[76:77], s[2:3], 0, v[76:77]
	v_mul_f32_e32 v75, v75, v72
	v_cvt_pk_bf16_f32 v72, v78, v79
	v_lshl_add_u64 v[76:77], v[76:77], 0, v[144:145]
	v_cvt_pk_bf16_f32 v73, v80, v81
	v_cvt_pk_bf16_f32 v74, v82, v83
	v_cvt_pk_bf16_f32 v75, v84, v75
	global_store_dwordx4 v[76:77], v[72:75], off
	v_add_u32_e32 v100, 0xa0, v146
	v_ashrrev_i32_e32 v101, 31, v100
	v_lshlrev_b32_e32 v72, 16, v184
	v_mul_f32_e32 v68, v68, v72
	v_and_b32_e32 v72, 0xffff0000, v184
	v_mul_f32_e32 v69, v69, v72
	v_lshlrev_b32_e32 v72, 16, v185
	v_mul_f32_e32 v70, v70, v72
	v_and_b32_e32 v72, 0xffff0000, v185
	v_mul_f32_e32 v71, v71, v72
	v_lshlrev_b32_e32 v72, 16, v186
	v_mul_f32_e32 v72, v64, v72
	v_and_b32_e32 v64, 0xffff0000, v186
	v_mul_f32_e32 v73, v65, v64
	v_lshlrev_b32_e32 v64, 16, v187
	v_mul_f32_e32 v74, v66, v64
	v_and_b32_e32 v64, 0xffff0000, v187
	v_mul_f32_e32 v67, v67, v64
	v_cvt_pk_bf16_f32 v64, v68, v69
	v_cvt_pk_bf16_f32 v65, v70, v71
	v_cvt_pk_bf16_f32 v66, v72, v73
	v_cvt_pk_bf16_f32 v67, v74, v67
	global_store_dwordx4 v[76:77], v[64:67], off offset:256
	v_lshlrev_b64 v[72:73], 12, v[98:99]
	v_lshl_add_u64 v[72:73], s[4:5], 0, v[72:73]
	v_lshlrev_b64 v[64:65], 12, v[96:97]
	v_lshl_add_u64 v[64:65], s[4:5], 0, v[64:65]
	v_lshl_add_u64 v[68:69], v[64:65], 0, v[144:145]
	global_load_dwordx4 v[64:67], v[68:69], off
	s_nop 0
	global_load_dwordx4 v[68:71], v[68:69], off offset:256
	v_lshl_add_u64 v[76:77], v[72:73], 0, v[144:145]
	global_load_dwordx4 v[72:75], v[76:77], off
	s_nop 0
	global_load_dwordx4 v[76:79], v[76:77], off offset:256
	v_lshlrev_b64 v[80:81], 12, v[100:101]
	v_lshl_add_u64 v[80:81], s[4:5], 0, v[80:81]
	v_lshl_add_u64 v[84:85], v[80:81], 0, v[144:145]
	global_load_dwordx4 v[80:83], v[84:85], off
	s_nop 0
	global_load_dwordx4 v[84:87], v[84:85], off offset:256
	v_lshlrev_b64 v[88:89], 12, v[102:103]
	v_lshl_add_u64 v[88:89], s[4:5], 0, v[88:89]
	v_lshl_add_u64 v[92:93], v[88:89], 0, v[144:145]
	global_load_dwordx4 v[88:91], v[92:93], off
	s_nop 0
	global_load_dwordx4 v[92:95], v[92:93], off offset:256
	v_lshlrev_b64 v[96:97], 11, v[96:97]
	s_waitcnt vmcnt(0)
; __device__ __forceinline__ unsigned cvt_pk_bf16(float lo, float hi) { unsigned r; asm volatile("v_cvt_pk_bf16_f32 %0, %1, %2" : "=v"(r) : "v"(lo), "v"(hi)); return r; }
; __device__ __forceinline__ float bflo(unsigned u) { return __uint_as_float(u << 16); }
; __device__ __forceinline__ float bfhi(unsigned u) { return __uint_as_float(u & 0xffff0000u); }
; #define PG8_WAIT_V(n) asm volatile("s_waitcnt vmcnt(" #n ")" ::: "memory")
; #define PG8_BAR __builtin_amdgcn_s_barrier()
; template <class Epi, class Sched>
; __device__ __forceinline__ void gemm_phase(const int wv, LAS unsigned char* lds, const Gemm g, const Sched& S, const Epi& E) {
;     ...
;         E(acc, cur, wr, wc, fr, fq); S.done(cur);
;         if (!has_next) break;
; #pragma unroll
;         for (int a = 0; a < 2; ++a)
; #pragma unroll
;             for (int b = 0; b < 2; ++b)
; #pragma unroll
;                 for (int m = 0; m < 4; ++m)
; #pragma unroll
;                     for (int n = 0; n < 2; ++n) acc[a][b][m][n] = (f32x4){0.f, 0.f, 0.f, 0.f};
;         cur = nxt; cA = nA; cB = nB; ++ui;
;     }
;     PG8_WAIT_V(0);
;     if (wr == 0) PG8_BAR;
;     PG8_BAR;
;     __device__ __forceinline__ void operator()(const f32x4 (&acc)[2][2][4][2], const Unit& u, int wr, int wc, int fr, int fq) const {
;     ...
;             for (int m = 0; m < 4; ++m)
; #pragma unroll
;                 for (int bj = 0; bj < 2; ++bj) {
;                     const int row = row0 + ai * 128 + m * 16, col = col0 + bj * 128;
;                     const u32x4 g = gv[m][bj];
;                     const f32x4 a0 = acc[ai][bj][m][0], a1 = acc[ai][bj][m][1];
;                     float r[8] = {a0[0] * bflo(g.x), a0[1] * bfhi(g.x), a0[2] * bflo(g.y), a0[3] * bfhi(g.y), a1[0] * bflo(g.z), a1[1] * bfhi(g.z), a1[2] * bflo(g.w), a1[3] * bfhi(g.w)};
;                     if (SECOND) { const u32x4 y = yv[m][bj];
;                         r[0] += bflo(y.x); r[1] += bfhi(y.x); r[2] += bflo(y.y); r[3] += bfhi(y.y); r[4] += bflo(y.z); r[5] += bfhi(y.z); r[6] += bflo(y.w); r[7] += bfhi(y.w); }
;                     u32x4 w; w.x = cvt_pk_bf16(r[0], r[1]); w.y = cvt_pk_bf16(r[2], r[3]); w.z = cvt_pk_bf16(r[4], r[5]); w.w = cvt_pk_bf16(r[6], r[7]);
;                     *(u32x4*)(Y + (size_t)row * 1024 + col) = w;
	v_lshlrev_b32_e32 v104, 16, v64
	v_and_b32_e32 v64, 0xffff0000, v64
	v_mul_f32_e32 v61, v61, v64
	v_lshlrev_b32_e32 v64, 16, v65
	v_mul_f32_e32 v62, v62, v64
	v_and_b32_e32 v64, 0xffff0000, v65
	v_mul_f32_e32 v63, v63, v64
	v_lshlrev_b32_e32 v64, 16, v66
	v_mul_f32_e32 v64, v56, v64
	v_and_b32_e32 v56, 0xffff0000, v66
	v_mul_f32_e32 v65, v57, v56
	v_lshlrev_b32_e32 v56, 16, v67
	v_mul_f32_e32 v60, v60, v104
	v_mul_f32_e32 v66, v58, v56
	v_and_b32_e32 v56, 0xffff0000, v67
	v_mul_f32_e32 v59, v59, v56
	v_cvt_pk_bf16_f32 v56, v60, v61
	v_lshl_add_u64 v[60:61], s[2:3], 0, v[96:97]
	v_lshl_add_u64 v[60:61], v[60:61], 0, v[144:145]
	v_cvt_pk_bf16_f32 v57, v62, v63
	v_cvt_pk_bf16_f32 v58, v64, v65
	v_cvt_pk_bf16_f32 v59, v66, v59
	global_store_dwordx4 v[60:61], v[56:59], off
	s_nop 1
	v_lshlrev_b32_e32 v56, 16, v68
	v_mul_f32_e32 v52, v52, v56
	v_and_b32_e32 v56, 0xffff0000, v68
	v_mul_f32_e32 v53, v53, v56
	v_lshlrev_b32_e32 v56, 16, v69
	v_mul_f32_e32 v54, v54, v56
	v_and_b32_e32 v56, 0xffff0000, v69
	v_mul_f32_e32 v55, v55, v56
	v_lshlrev_b32_e32 v56, 16, v70
	v_mul_f32_e32 v56, v44, v56
	v_and_b32_e32 v44, 0xffff0000, v70
	v_mul_f32_e32 v57, v45, v44
	v_lshlrev_b32_e32 v44, 16, v71
	v_mul_f32_e32 v58, v46, v44
	v_and_b32_e32 v44, 0xffff0000, v71
	v_mul_f32_e32 v47, v47, v44
	v_cvt_pk_bf16_f32 v44, v52, v53
	v_cvt_pk_bf16_f32 v45, v54, v55
	v_cvt_pk_bf16_f32 v46, v56, v57
	v_cvt_pk_bf16_f32 v47, v58, v47
	global_store_dwordx4 v[60:61], v[44:47], off offset:256
	s_nop 1
	v_lshlrev_b32_e32 v46, 16, v72
	v_mul_f32_e32 v46, v48, v46
	v_lshlrev_b32_e32 v48, 16, v73
	v_and_b32_e32 v47, 0xffff0000, v72
	v_mul_f32_e32 v48, v50, v48
	v_lshlrev_b32_e32 v50, 16, v74
	v_mul_f32_e32 v47, v49, v47
	v_and_b32_e32 v49, 0xffff0000, v73
	v_mul_f32_e32 v50, v40, v50
	v_and_b32_e32 v40, 0xffff0000, v74
	v_lshlrev_b64 v[44:45], 11, v[98:99]
	v_mul_f32_e32 v49, v51, v49
	v_mul_f32_e32 v51, v41, v40
	v_lshlrev_b32_e32 v40, 16, v75
	v_mul_f32_e32 v52, v42, v40
	v_and_b32_e32 v40, 0xffff0000, v75
	v_lshl_add_u64 v[44:45], s[2:3], 0, v[44:45]
	v_mul_f32_e32 v43, v43, v40
	v_cvt_pk_bf16_f32 v40, v46, v47
	v_lshl_add_u64 v[44:45], v[44:45], 0, v[144:145]
	v_cvt_pk_bf16_f32 v41, v48, v49
	v_cvt_pk_bf16_f32 v42, v50, v51
	v_cvt_pk_bf16_f32 v43, v52, v43
	global_store_dwordx4 v[44:45], v[40:43], off
	s_nop 1
	v_lshlrev_b32_e32 v40, 16, v76
	v_mul_f32_e32 v36, v36, v40
	v_and_b32_e32 v40, 0xffff0000, v76
	v_mul_f32_e32 v37, v37, v40
	v_lshlrev_b32_e32 v40, 16, v77
	v_mul_f32_e32 v38, v38, v40
	v_and_b32_e32 v40, 0xffff0000, v77
	v_mul_f32_e32 v39, v39, v40
	v_lshlrev_b32_e32 v40, 16, v78
	v_mul_f32_e32 v40, v28, v40
	v_and_b32_e32 v28, 0xffff0000, v78
	v_mul_f32_e32 v41, v29, v28
	v_lshlrev_b32_e32 v28, 16, v79
	v_mul_f32_e32 v42, v30, v28
	v_and_b32_e32 v28, 0xffff0000, v79
	v_mul_f32_e32 v31, v31, v28
	v_cvt_pk_bf16_f32 v28, v36, v37
	v_cvt_pk_bf16_f32 v29, v38, v39
	v_cvt_pk_bf16_f32 v30, v40, v41
	v_cvt_pk_bf16_f32 v31, v42, v31
	global_store_dwordx4 v[44:45], v[28:31], off offset:256
	s_nop 1
	v_lshlrev_b32_e32 v30, 16, v80
	v_mul_f32_e32 v30, v32, v30
	v_lshlrev_b32_e32 v32, 16, v81
	v_and_b32_e32 v31, 0xffff0000, v80
	v_mul_f32_e32 v32, v34, v32
	v_lshlrev_b32_e32 v34, 16, v82
	v_mul_f32_e32 v31, v33, v31
	v_and_b32_e32 v33, 0xffff0000, v81
	v_mul_f32_e32 v34, v24, v34
	v_and_b32_e32 v24, 0xffff0000, v82
	v_lshlrev_b64 v[28:29], 11, v[100:101]
	v_mul_f32_e32 v33, v35, v33
	v_mul_f32_e32 v35, v25, v24
	v_lshlrev_b32_e32 v24, 16, v83
	v_mul_f32_e32 v36, v26, v24
	v_and_b32_e32 v24, 0xffff0000, v83
	v_lshl_add_u64 v[28:29], s[2:3], 0, v[28:29]
	v_mul_f32_e32 v27, v27, v24
	v_cvt_pk_bf16_f32 v24, v30, v31
	v_lshl_add_u64 v[28:29], v[28:29], 0, v[144:145]
	v_cvt_pk_bf16_f32 v25, v32, v33
	v_cvt_pk_bf16_f32 v26, v34, v35
	v_cvt_pk_bf16_f32 v27, v36, v27
	global_store_dwordx4 v[28:29], v[24:27], off
	s_nop 1
	v_lshlrev_b32_e32 v24, 16, v84
	v_mul_f32_e32 v20, v20, v24
	v_and_b32_e32 v24, 0xffff0000, v84
	v_mul_f32_e32 v21, v21, v24
	v_lshlrev_b32_e32 v24, 16, v85
	v_mul_f32_e32 v22, v22, v24
	v_and_b32_e32 v24, 0xffff0000, v85
	v_mul_f32_e32 v23, v23, v24
	v_lshlrev_b32_e32 v24, 16, v86
	v_mul_f32_e32 v24, v12, v24
	v_and_b32_e32 v12, 0xffff0000, v86
	v_mul_f32_e32 v25, v13, v12
	v_lshlrev_b32_e32 v12, 16, v87
	v_mul_f32_e32 v26, v14, v12
	v_and_b32_e32 v12, 0xffff0000, v87
	v_mul_f32_e32 v15, v15, v12
	v_cvt_pk_bf16_f32 v12, v20, v21
	v_cvt_pk_bf16_f32 v13, v22, v23
	v_cvt_pk_bf16_f32 v14, v24, v25
	v_cvt_pk_bf16_f32 v15, v26, v15
	global_store_dwordx4 v[28:29], v[12:15], off offset:256
	s_nop 1
	v_lshlrev_b32_e32 v14, 16, v88
	v_mul_f32_e32 v14, v16, v14
	v_lshlrev_b32_e32 v16, 16, v89
	v_and_b32_e32 v15, 0xffff0000, v88
	v_mul_f32_e32 v16, v18, v16
	v_lshlrev_b32_e32 v18, 16, v90
	v_mul_f32_e32 v15, v17, v15
	v_and_b32_e32 v17, 0xffff0000, v89
	v_mul_f32_e32 v18, v8, v18
	v_and_b32_e32 v8, 0xffff0000, v90
	v_lshlrev_b64 v[12:13], 11, v[102:103]
	v_mul_f32_e32 v17, v19, v17
	v_mul_f32_e32 v19, v9, v8
	v_lshlrev_b32_e32 v8, 16, v91
	v_mul_f32_e32 v20, v10, v8
	v_and_b32_e32 v8, 0xffff0000, v91
	v_lshl_add_u64 v[12:13], s[2:3], 0, v[12:13]
	v_mul_f32_e32 v11, v11, v8
	v_cvt_pk_bf16_f32 v8, v14, v15
	v_lshl_add_u64 v[12:13], v[12:13], 0, v[144:145]
	v_cvt_pk_bf16_f32 v9, v16, v17
	v_cvt_pk_bf16_f32 v10, v18, v19
	v_cvt_pk_bf16_f32 v11, v20, v11
	global_store_dwordx4 v[12:13], v[8:11], off
	s_nop 1
	v_lshlrev_b32_e32 v8, 16, v92
	v_mul_f32_e32 v4, v4, v8
	v_and_b32_e32 v8, 0xffff0000, v92
	v_mul_f32_e32 v5, v5, v8
	v_lshlrev_b32_e32 v8, 16, v93
	v_mul_f32_e32 v6, v6, v8
	v_and_b32_e32 v8, 0xffff0000, v93
	v_mul_f32_e32 v7, v7, v8
	v_lshlrev_b32_e32 v8, 16, v94
	v_mul_f32_e32 v8, v0, v8
	v_and_b32_e32 v0, 0xffff0000, v94
	v_mul_f32_e32 v9, v1, v0
	v_lshlrev_b32_e32 v0, 16, v95
	v_mul_f32_e32 v10, v2, v0
	v_and_b32_e32 v0, 0xffff0000, v95
	v_mul_f32_e32 v3, v3, v0
	v_cvt_pk_bf16_f32 v0, v4, v5
	v_cvt_pk_bf16_f32 v1, v6, v7
	v_cvt_pk_bf16_f32 v2, v8, v9
	v_cvt_pk_bf16_f32 v3, v10, v3
	global_store_dwordx4 v[12:13], v[0:3], off offset:256
	s_cbranch_vccz .LBB0_570
	s_waitcnt vmcnt(0)
	s_cmpk_gt_u32 s26, 0xff
	s_cbranch_scc1 .LBB0_581
	s_barrier

; #define PG8_STAGE(bufoff, gbase, voff) do { _Pragma("unroll") for (int _i = 0; _i < 2; ++_i) \
;         __builtin_amdgcn_global_load_lds((const unsigned*)((const char*)(gbase) + (voff)[_i]), (LAS unsigned*)(lds + (bufoff) + ldsw + _i * 8192), 16, 0, 0); } while (0)
; #define PG8_LDA(dst, b, h) do { _Pragma("unroll") for (int m = 0; m < 4; ++m) _Pragma("unroll") for (int k = 0; k < 2; ++k) dst[m][k] = *(const LAS bf16x8*)(lds + PG8_SA(b, h) + aoff + m * 2048 + k * 1024); } while (0)
; #define PG8_LDB(dst, b, h) do { _Pragma("unroll") for (int n = 0; n < 2; ++n) _Pragma("unroll") for (int k = 0; k < 2; ++k) dst[n][k] = *(const LAS bf16x8*)(lds + PG8_SB(b, h) + boff + n * 2048 + k * 1024); } while (0)
; #define PG8_MMA(ai, bj, At, Bt) do { __builtin_amdgcn_s_setprio(1); _Pragma("unroll") for (int m = 0; m < 4; ++m) _Pragma("unroll") for (int n = 0; n < 2; ++n) _Pragma("unroll") for (int k = 0; k < 2; ++k) \
;         acc[ai][bj][m][n] = __builtin_amdgcn_mfma_f32_16x16x32_bf16(Bt[n][k], At[m][k], acc[ai][bj][m][n], 0, 0, 0); __builtin_amdgcn_s_setprio(0); } while (0)
; template <class Epi, class Sched>
; __device__ __forceinline__ void gemm_phase(const int wv, LAS unsigned char* lds, const Gemm g, const Sched& S, const Epi& E) {
;     ...
;         const bool has_next = S.next(ui + 1, nxt);
;         const char* nA = has_next ? (const char*)g.A + (size_t)nxt.pm * tstepA : cA; const char* nB = has_next ? (const char*)g.Bt + (size_t)nxt.pn * tstepB : cB;
;         for (int t = 0; t < nt; t += 2) {
;             const bool last = (t == nt - 2);
;             const char* a1 = cA + (size_t)(t + 1) * kstepA;
;             const char* a2 = last ? nA : cA + (size_t)(t + 2) * kstepA; const char* b2 = last ? nB : cB + (size_t)(t + 2) * kstep;
;             const char* a3 = a2 + kstepA; const char* b3 = b2 + kstep;
;             if (last && has_next) S.a_ready(nxt);
;             PG8_LDB(B0, 0, 0); PG8_SCHED; PG8_LDA(At, 0, 0); PG8_STAGE(PG8_SA(1, 1), a1 + hstepA, voffA);
;             PG8_WAIT_L(8); PG8_BAR; PG8_WAIT_L(0); PG8_MMA(0, 0, At, B0); PG8_BAR; PG8_SCHED;
;             PG8_LDB(B1, 0, 1); PG8_STAGE(PG8_SB(0, 0), b2, voffB);
;             PG8_BAR; PG8_WAIT_L(0); PG8_MMA(0, 1, At, B1); PG8_BAR;
;             PG8_LDA(At, 0, 1); PG8_STAGE(PG8_SA(0, 0), a2, voffA);
;             PG8_BAR; PG8_WAIT_L(0); PG8_MMA(1, 0, At, B0); PG8_BAR; PG8_SCHED;
.LBB0_596:
	s_ashr_i32 s11, s10, 31
	v_cmp_lt_i64_e32 vcc, s[12:13], v[160:161]
	s_lshl_b64 s[12:13], s[10:11], 20
	s_add_u32 s12, s25, s12
	s_addc_u32 s13, s26, s13
	s_and_b64 s[14:15], vcc, exec
	s_cselect_b32 s11, s13, s19
	s_cselect_b32 s40, s12, s18
	s_ashr_i32 s9, s8, 31
	s_lshl_b64 s[14:15], s[8:9], 20
	s_add_u32 s14, s27, s14
	s_addc_u32 s15, s28, s15
	s_and_b64 s[22:23], vcc, exec
	s_cselect_b32 s9, s15, s21
	s_cselect_b32 s41, s14, s20
	s_add_u32 s18, s18, 0x80080
	s_addc_u32 s19, s19, 0
	s_add_u32 s42, s20, 0x100
	s_addc_u32 s43, s21, 0
	s_mov_b32 s44, -2
	ds_read_b128 v[128:131], v175
	ds_read_b128 v[132:135], v175 offset:1024
	ds_read_b128 v[136:139], v175 offset:2048
	ds_read_b128 v[140:143], v175 offset:3072
	s_add_u32 s20, s18, 0xfff80080
	s_addc_u32 s21, s19, -1
	s_cmp_eq_u32 s44, 28
	s_cselect_b32 s23, s11, s21
	s_cselect_b32 s22, s40, s20
	s_cselect_b32 s21, s9, s43
	s_cselect_b32 s20, s41, s42
	v_lshl_add_u64 v[200:201], s[18:19], 0, v[156:157]
	s_add_i32 m0, s17, 0xc000
	ds_read_b128 v[144:147], v176
	ds_read_b128 v[164:167], v176 offset:1024
	ds_read_b128 v[168:171], v176 offset:2048
	ds_read_b128 v[180:183], v176 offset:3072
	ds_read_b128 v[184:187], v176 offset:4096
	ds_read_b128 v[188:191], v176 offset:5120
	ds_read_b128 v[192:195], v176 offset:6144
	ds_read_b128 v[196:199], v176 offset:7168
	global_load_lds_dwordx4 v[200:201], off
	v_lshl_add_u64 v[200:201], s[18:19], 0, v[158:159]
	s_add_i32 m0, s17, 0xe000
	s_nop 0
	global_load_lds_dwordx4 v[200:201], off
	s_waitcnt lgkmcnt(8)
	s_barrier
	s_waitcnt lgkmcnt(0)
	s_setprio 1
	s_waitcnt lgkmcnt(0)
	v_mfma_f32_16x16x32_bf16 v[124:127], v[128:131], v[144:147], 0
	v_mfma_f32_16x16x32_bf16 v[120:123], v[136:139], v[144:147], 0
	v_mfma_f32_16x16x32_bf16 v[108:111], v[128:131], v[168:171], 0
	v_mfma_f32_16x16x32_bf16 v[104:107], v[136:139], v[168:171], 0
	v_mfma_f32_16x16x32_bf16 v[92:95], v[128:131], v[184:187], 0
	v_mfma_f32_16x16x32_bf16 v[88:91], v[136:139], v[184:187], 0
	v_mfma_f32_16x16x32_bf16 v[76:79], v[128:131], v[192:195], 0
	v_mfma_f32_16x16x32_bf16 v[72:75], v[136:139], v[192:195], 0
	v_mfma_f32_16x16x32_bf16 v[124:127], v[132:135], v[164:167], v[124:127]
	v_mfma_f32_16x16x32_bf16 v[120:123], v[140:143], v[164:167], v[120:123]
	v_mfma_f32_16x16x32_bf16 v[108:111], v[132:135], v[180:183], v[108:111]
	v_mfma_f32_16x16x32_bf16 v[104:107], v[140:143], v[180:183], v[104:107]
	v_mfma_f32_16x16x32_bf16 v[92:95], v[132:135], v[188:191], v[92:95]
	v_mfma_f32_16x16x32_bf16 v[88:91], v[140:143], v[188:191], v[88:91]
	v_mfma_f32_16x16x32_bf16 v[76:79], v[132:135], v[196:199], v[76:79]
	v_mfma_f32_16x16x32_bf16 v[72:75], v[140:143], v[196:199], v[72:75]
	s_setprio 0
	s_barrier
	s_add_i32 s45, s37, s29
	v_lshl_add_u64 v[216:217], s[20:21], 0, v[150:151]
	s_mov_b32 m0, s45
	ds_read_b128 v[200:203], v177
	ds_read_b128 v[204:207], v177 offset:1024
	ds_read_b128 v[208:211], v177 offset:2048
	ds_read_b128 v[212:215], v177 offset:3072
	global_load_lds_dwordx4 v[216:217], off
	v_lshl_add_u64 v[218:219], s[20:21], 0, v[154:155]
	s_add_i32 m0, s45, 0x2000
	s_nop 0
	global_load_lds_dwordx4 v[218:219], off
	s_barrier
	s_waitcnt lgkmcnt(0)
	s_setprio 1
	s_waitcnt lgkmcnt(0)
	v_mfma_f32_16x16x32_bf16 v[116:119], v[200:203], v[144:147], 0
	v_mfma_f32_16x16x32_bf16 v[112:115], v[208:211], v[144:147], 0
	v_mfma_f32_16x16x32_bf16 v[100:103], v[200:203], v[168:171], 0
	v_mfma_f32_16x16x32_bf16 v[96:99], v[208:211], v[168:171], 0
	v_mfma_f32_16x16x32_bf16 v[84:87], v[200:203], v[184:187], 0
	v_mfma_f32_16x16x32_bf16 v[80:83], v[208:211], v[184:187], 0
	v_mfma_f32_16x16x32_bf16 v[68:71], v[200:203], v[192:195], 0
	v_mfma_f32_16x16x32_bf16 v[64:67], v[208:211], v[192:195], 0
	v_mfma_f32_16x16x32_bf16 v[116:119], v[204:207], v[164:167], v[116:119]
	v_mfma_f32_16x16x32_bf16 v[112:115], v[212:215], v[164:167], v[112:115]
	v_mfma_f32_16x16x32_bf16 v[100:103], v[204:207], v[180:183], v[100:103]
	v_mfma_f32_16x16x32_bf16 v[96:99], v[212:215], v[180:183], v[96:99]
	v_mfma_f32_16x16x32_bf16 v[84:87], v[204:207], v[188:191], v[84:87]
	v_mfma_f32_16x16x32_bf16 v[80:83], v[212:215], v[188:191], v[80:83]
	v_mfma_f32_16x16x32_bf16 v[68:71], v[204:207], v[196:199], v[68:71]
	v_mfma_f32_16x16x32_bf16 v[64:67], v[212:215], v[196:199], v[64:67]
	s_setprio 0
	s_mov_b32 m0, s17
	v_lshl_add_u64 v[220:221], s[22:23], 0, v[148:149]
	s_barrier
	ds_read_b128 v[144:147], v176 offset:16384
	ds_read_b128 v[164:167], v176 offset:17408
	ds_read_b128 v[168:171], v176 offset:18432
	ds_read_b128 v[180:183], v176 offset:19456
	ds_read_b128 v[184:187], v176 offset:20480
	ds_read_b128 v[188:191], v176 offset:21504
	ds_read_b128 v[192:195], v176 offset:22528
	ds_read_b128 v[196:199], v176 offset:23552
	global_load_lds_dwordx4 v[220:221], off
	v_lshl_add_u64 v[222:223], s[22:23], 0, v[152:153]
	s_mov_b32 m0, s30
	s_nop 0
	global_load_lds_dwordx4 v[222:223], off
	s_barrier
	s_waitcnt lgkmcnt(0)
	s_setprio 1
	s_waitcnt lgkmcnt(0)
	v_mfma_f32_16x16x32_bf16 v[60:63], v[128:131], v[144:147], 0
	v_mfma_f32_16x16x32_bf16 v[56:59], v[136:139], v[144:147], 0
	v_mfma_f32_16x16x32_bf16 v[44:47], v[128:131], v[168:171], 0
	v_mfma_f32_16x16x32_bf16 v[40:43], v[136:139], v[168:171], 0
	v_mfma_f32_16x16x32_bf16 v[28:31], v[128:131], v[184:187], 0
	v_mfma_f32_16x16x32_bf16 v[24:27], v[136:139], v[184:187], 0
	v_mfma_f32_16x16x32_bf16 v[12:15], v[128:131], v[192:195], 0
	v_mfma_f32_16x16x32_bf16 v[8:11], v[136:139], v[192:195], 0
	v_mfma_f32_16x16x32_bf16 v[60:63], v[132:135], v[164:167], v[60:63]
	v_mfma_f32_16x16x32_bf16 v[56:59], v[140:143], v[164:167], v[56:59]
	v_mfma_f32_16x16x32_bf16 v[44:47], v[132:135], v[180:183], v[44:47]
	v_mfma_f32_16x16x32_bf16 v[40:43], v[140:143], v[180:183], v[40:43]
	v_mfma_f32_16x16x32_bf16 v[28:31], v[132:135], v[188:191], v[28:31]
	v_mfma_f32_16x16x32_bf16 v[24:27], v[140:143], v[188:191], v[24:27]
	v_mfma_f32_16x16x32_bf16 v[12:15], v[132:135], v[196:199], v[12:15]
	v_mfma_f32_16x16x32_bf16 v[8:11], v[140:143], v[196:199], v[8:11]
	s_setprio 0
	s_barrier
; #define PG8_STAGE(bufoff, gbase, voff) do { _Pragma("unroll") for (int _i = 0; _i < 2; ++_i) \
;         __builtin_amdgcn_global_load_lds((const unsigned*)((const char*)(gbase) + (voff)[_i]), (LAS unsigned*)(lds + (bufoff) + ldsw + _i * 8192), 16, 0, 0); } while (0)
; #define PG8_LDA(dst, b, h) do { _Pragma("unroll") for (int m = 0; m < 4; ++m) _Pragma("unroll") for (int k = 0; k < 2; ++k) dst[m][k] = *(const LAS bf16x8*)(lds + PG8_SA(b, h) + aoff + m * 2048 + k * 1024); } while (0)
; #define PG8_LDB(dst, b, h) do { _Pragma("unroll") for (int n = 0; n < 2; ++n) _Pragma("unroll") for (int k = 0; k < 2; ++k) dst[n][k] = *(const LAS bf16x8*)(lds + PG8_SB(b, h) + boff + n * 2048 + k * 1024); } while (0)
; #define PG8_MMA(ai, bj, At, Bt) do { __builtin_amdgcn_s_setprio(1); _Pragma("unroll") for (int m = 0; m < 4; ++m) _Pragma("unroll") for (int n = 0; n < 2; ++n) _Pragma("unroll") for (int k = 0; k < 2; ++k) \
;         acc[ai][bj][m][n] = __builtin_amdgcn_mfma_f32_16x16x32_bf16(Bt[n][k], At[m][k], acc[ai][bj][m][n], 0, 0, 0); __builtin_amdgcn_s_setprio(0); } while (0)
; #define PG8_WAIT_V(n) asm volatile("s_waitcnt vmcnt(" #n ")" ::: "memory")
; #define PG8_WAIT_L(n) asm volatile("s_waitcnt lgkmcnt(" #n ")" ::: "memory")
; #define PG8_BAR __builtin_amdgcn_s_barrier()
; #define PG8_SCHED __builtin_amdgcn_sched_barrier(0)
; template <class Epi, class Sched>
; __device__ __forceinline__ void gemm_phase(const int wv, LAS unsigned char* lds, const Gemm g, const Sched& S, const Epi& E) {
;     ...
;             PG8_STAGE(PG8_SB(0, 1), b2 + hstepB, voffB);
;             PG8_WAIT_V(6); PG8_BAR; PG8_MMA(1, 1, At, B1); PG8_BAR;
;             PG8_LDB(B0, 1, 0); PG8_SCHED; PG8_LDA(At, 1, 0); PG8_STAGE(PG8_SA(0, 1), a2 + hstepA, voffA);
;             PG8_WAIT_L(8); PG8_BAR; PG8_WAIT_L(0); PG8_MMA(0, 0, At, B0); PG8_BAR; PG8_SCHED;
;             PG8_LDB(B1, 1, 1); PG8_STAGE(PG8_SB(1, 0), b3, voffB);
;             PG8_BAR; PG8_WAIT_L(0); PG8_MMA(0, 1, At, B1); PG8_BAR;
	s_add_u32 s46, s20, 0x80000
	s_addc_u32 s47, s21, 0
	s_add_i32 s45, s38, s29
	v_lshl_add_u64 v[128:129], s[46:47], 0, v[150:151]
	s_mov_b32 m0, s45
	s_nop 0
	global_load_lds_dwordx4 v[128:129], off
	v_lshl_add_u64 v[128:129], s[46:47], 0, v[154:155]
	s_add_i32 m0, s45, 0x2000
	s_nop 0
	global_load_lds_dwordx4 v[128:129], off
	s_waitcnt vmcnt(6)
	s_barrier
	s_setprio 1
	v_mfma_f32_16x16x32_bf16 v[52:55], v[200:203], v[144:147], 0
	v_mfma_f32_16x16x32_bf16 v[48:51], v[208:211], v[144:147], 0
	v_mfma_f32_16x16x32_bf16 v[36:39], v[200:203], v[168:171], 0
	v_mfma_f32_16x16x32_bf16 v[32:35], v[208:211], v[168:171], 0
	v_mfma_f32_16x16x32_bf16 v[20:23], v[200:203], v[184:187], 0
	v_mfma_f32_16x16x32_bf16 v[16:19], v[208:211], v[184:187], 0
	v_mfma_f32_16x16x32_bf16 v[4:7], v[200:203], v[192:195], 0
	v_mfma_f32_16x16x32_bf16 v[0:3], v[208:211], v[192:195], 0
	v_mfma_f32_16x16x32_bf16 v[52:55], v[204:207], v[164:167], v[52:55]
	v_mfma_f32_16x16x32_bf16 v[48:51], v[212:215], v[164:167], v[48:51]
	v_mfma_f32_16x16x32_bf16 v[36:39], v[204:207], v[180:183], v[36:39]
	v_mfma_f32_16x16x32_bf16 v[32:35], v[212:215], v[180:183], v[32:35]
	v_mfma_f32_16x16x32_bf16 v[20:23], v[204:207], v[188:191], v[20:23]
	v_mfma_f32_16x16x32_bf16 v[16:19], v[212:215], v[188:191], v[16:19]
	v_mfma_f32_16x16x32_bf16 v[4:7], v[204:207], v[196:199], v[4:7]
	v_mfma_f32_16x16x32_bf16 v[0:3], v[212:215], v[196:199], v[0:3]
	s_setprio 0
	s_add_i32 s45, 0, 0x18000
	v_add_u32_e32 v140, s45, v173
	s_barrier
	ds_read_b128 v[128:131], v140
	ds_read_b128 v[132:135], v140 offset:1024
	ds_read_b128 v[136:139], v140 offset:2048
	ds_read_b128 v[140:143], v140 offset:3072
	s_add_u32 s22, s22, 0x80000
	s_addc_u32 s23, s23, 0
	s_mov_b32 m0, s31
	v_lshl_add_u64 v[200:201], s[22:23], 0, v[148:149]
	ds_read_b128 v[144:147], v176 offset:32768
	ds_read_b128 v[164:167], v176 offset:33792
	ds_read_b128 v[168:171], v176 offset:34816
	ds_read_b128 v[180:183], v176 offset:35840
	ds_read_b128 v[184:187], v176 offset:36864
	ds_read_b128 v[188:191], v176 offset:37888
	ds_read_b128 v[192:195], v176 offset:38912
	ds_read_b128 v[196:199], v176 offset:39936
	global_load_lds_dwordx4 v[200:201], off
	v_lshl_add_u64 v[200:201], s[22:23], 0, v[152:153]
	s_mov_b32 m0, s33
	s_nop 0
	global_load_lds_dwordx4 v[200:201], off
	s_waitcnt lgkmcnt(8)
	s_barrier
	s_waitcnt lgkmcnt(0)
	s_setprio 1
	s_waitcnt lgkmcnt(0)
	v_mfma_f32_16x16x32_bf16 v[124:127], v[128:131], v[144:147], v[124:127]
	v_mfma_f32_16x16x32_bf16 v[120:123], v[136:139], v[144:147], v[120:123]
	v_mfma_f32_16x16x32_bf16 v[108:111], v[128:131], v[168:171], v[108:111]
	v_mfma_f32_16x16x32_bf16 v[104:107], v[136:139], v[168:171], v[104:107]
	v_mfma_f32_16x16x32_bf16 v[92:95], v[128:131], v[184:187], v[92:95]
	v_mfma_f32_16x16x32_bf16 v[88:91], v[136:139], v[184:187], v[88:91]
	v_mfma_f32_16x16x32_bf16 v[76:79], v[128:131], v[192:195], v[76:79]
	v_mfma_f32_16x16x32_bf16 v[72:75], v[136:139], v[192:195], v[72:75]
	v_mfma_f32_16x16x32_bf16 v[124:127], v[132:135], v[164:167], v[124:127]
	v_mfma_f32_16x16x32_bf16 v[120:123], v[140:143], v[164:167], v[120:123]
	v_mfma_f32_16x16x32_bf16 v[108:111], v[132:135], v[180:183], v[108:111]
	v_mfma_f32_16x16x32_bf16 v[104:107], v[140:143], v[180:183], v[104:107]
	v_mfma_f32_16x16x32_bf16 v[92:95], v[132:135], v[188:191], v[92:95]
	v_mfma_f32_16x16x32_bf16 v[88:91], v[140:143], v[188:191], v[88:91]
	v_mfma_f32_16x16x32_bf16 v[76:79], v[132:135], v[196:199], v[76:79]
	v_mfma_f32_16x16x32_bf16 v[72:75], v[140:143], v[196:199], v[72:75]
	s_setprio 0
	s_barrier
	s_add_i32 s22, 0, 0x1c000
	s_add_i32 s23, s45, s29
	v_add_u32_e32 v212, s22, v173
	v_lshl_add_u64 v[216:217], v[216:217], 0, s[6:7]
	s_mov_b32 m0, s23
	ds_read_b128 v[200:203], v212
	ds_read_b128 v[204:207], v212 offset:1024
	ds_read_b128 v[208:211], v212 offset:2048
	ds_read_b128 v[212:215], v212 offset:3072
	global_load_lds_dwordx4 v[216:217], off
	v_lshl_add_u64 v[216:217], v[218:219], 0, s[6:7]
	s_add_i32 m0, s23, 0x2000
	s_nop 0
	global_load_lds_dwordx4 v[216:217], off
	s_barrier
; #define PG8_STAGE(bufoff, gbase, voff) do { _Pragma("unroll") for (int _i = 0; _i < 2; ++_i) \
;         __builtin_amdgcn_global_load_lds((const unsigned*)((const char*)(gbase) + (voff)[_i]), (LAS unsigned*)(lds + (bufoff) + ldsw + _i * 8192), 16, 0, 0); } while (0)
; #define PG8_LDA(dst, b, h) do { _Pragma("unroll") for (int m = 0; m < 4; ++m) _Pragma("unroll") for (int k = 0; k < 2; ++k) dst[m][k] = *(const LAS bf16x8*)(lds + PG8_SA(b, h) + aoff + m * 2048 + k * 1024); } while (0)
; #define PG8_MMA(ai, bj, At, Bt) do { __builtin_amdgcn_s_setprio(1); _Pragma("unroll") for (int m = 0; m < 4; ++m) _Pragma("unroll") for (int n = 0; n < 2; ++n) _Pragma("unroll") for (int k = 0; k < 2; ++k) \
;         acc[ai][bj][m][n] = __builtin_amdgcn_mfma_f32_16x16x32_bf16(Bt[n][k], At[m][k], acc[ai][bj][m][n], 0, 0, 0); __builtin_amdgcn_s_setprio(0); } while (0)
; #define PG8_WAIT_V(n) asm volatile("s_waitcnt vmcnt(" #n ")" ::: "memory")
; #define PG8_WAIT_L(n) asm volatile("s_waitcnt lgkmcnt(" #n ")" ::: "memory")
; #define PG8_BAR __builtin_amdgcn_s_barrier()
; #define PG8_SCHED __builtin_amdgcn_sched_barrier(0)
; template <class Epi, class Sched>
; __device__ __forceinline__ void gemm_phase(const int wv, LAS unsigned char* lds, const Gemm g, const Sched& S, const Epi& E) {
;     ...
;             PG8_BAR; PG8_WAIT_L(0); PG8_MMA(0, 1, At, B1); PG8_BAR;
;             PG8_LDA(At, 1, 1); PG8_STAGE(PG8_SA(1, 0), a3, voffA);
;             PG8_BAR; PG8_WAIT_L(0); PG8_MMA(1, 0, At, B0); PG8_BAR; PG8_SCHED;
;             PG8_STAGE(PG8_SB(1, 1), b3 + hstepB, voffB);
;             PG8_WAIT_V(6); PG8_BAR; PG8_MMA(1, 1, At, B1); PG8_BAR;
;         }
	s_waitcnt lgkmcnt(0)
	s_setprio 1
	s_waitcnt lgkmcnt(0)
	v_mfma_f32_16x16x32_bf16 v[116:119], v[200:203], v[144:147], v[116:119]
	v_mfma_f32_16x16x32_bf16 v[112:115], v[208:211], v[144:147], v[112:115]
	v_mfma_f32_16x16x32_bf16 v[100:103], v[200:203], v[168:171], v[100:103]
	v_mfma_f32_16x16x32_bf16 v[96:99], v[208:211], v[168:171], v[96:99]
	v_mfma_f32_16x16x32_bf16 v[84:87], v[200:203], v[184:187], v[84:87]
	v_mfma_f32_16x16x32_bf16 v[80:83], v[208:211], v[184:187], v[80:83]
	v_mfma_f32_16x16x32_bf16 v[68:71], v[200:203], v[192:195], v[68:71]
	v_mfma_f32_16x16x32_bf16 v[64:67], v[208:211], v[192:195], v[64:67]
	v_mfma_f32_16x16x32_bf16 v[116:119], v[204:207], v[164:167], v[116:119]
	v_mfma_f32_16x16x32_bf16 v[112:115], v[212:215], v[164:167], v[112:115]
	v_mfma_f32_16x16x32_bf16 v[100:103], v[204:207], v[180:183], v[100:103]
	v_mfma_f32_16x16x32_bf16 v[96:99], v[212:215], v[180:183], v[96:99]
	v_mfma_f32_16x16x32_bf16 v[84:87], v[204:207], v[188:191], v[84:87]
	v_mfma_f32_16x16x32_bf16 v[80:83], v[212:215], v[188:191], v[80:83]
	v_mfma_f32_16x16x32_bf16 v[68:71], v[204:207], v[196:199], v[68:71]
	v_mfma_f32_16x16x32_bf16 v[64:67], v[212:215], v[196:199], v[64:67]
	s_setprio 0
	s_mov_b32 m0, s35
	v_lshl_add_u64 v[216:217], v[220:221], 0, s[6:7]
	s_barrier
	ds_read_b128 v[144:147], v176 offset:49152
	ds_read_b128 v[164:167], v176 offset:50176
	ds_read_b128 v[168:171], v176 offset:51200
	ds_read_b128 v[180:183], v176 offset:52224
	ds_read_b128 v[184:187], v176 offset:53248
	ds_read_b128 v[188:191], v176 offset:54272
	ds_read_b128 v[192:195], v176 offset:55296
	ds_read_b128 v[196:199], v176 offset:56320
	global_load_lds_dwordx4 v[216:217], off
	v_lshl_add_u64 v[216:217], v[222:223], 0, s[6:7]
	s_mov_b32 m0, s36
	s_nop 0
	global_load_lds_dwordx4 v[216:217], off
	s_barrier
	s_waitcnt lgkmcnt(0)
	s_setprio 1
	s_waitcnt lgkmcnt(0)
	v_mfma_f32_16x16x32_bf16 v[60:63], v[128:131], v[144:147], v[60:63]
	v_mfma_f32_16x16x32_bf16 v[56:59], v[136:139], v[144:147], v[56:59]
	v_mfma_f32_16x16x32_bf16 v[44:47], v[128:131], v[168:171], v[44:47]
	v_mfma_f32_16x16x32_bf16 v[40:43], v[136:139], v[168:171], v[40:43]
	v_mfma_f32_16x16x32_bf16 v[28:31], v[128:131], v[184:187], v[28:31]
	v_mfma_f32_16x16x32_bf16 v[24:27], v[136:139], v[184:187], v[24:27]
	v_mfma_f32_16x16x32_bf16 v[12:15], v[128:131], v[192:195], v[12:15]
	v_mfma_f32_16x16x32_bf16 v[8:11], v[136:139], v[192:195], v[8:11]
	v_mfma_f32_16x16x32_bf16 v[60:63], v[132:135], v[164:167], v[60:63]
	v_mfma_f32_16x16x32_bf16 v[56:59], v[140:143], v[164:167], v[56:59]
	v_mfma_f32_16x16x32_bf16 v[44:47], v[132:135], v[180:183], v[44:47]
	v_mfma_f32_16x16x32_bf16 v[40:43], v[140:143], v[180:183], v[40:43]
	v_mfma_f32_16x16x32_bf16 v[28:31], v[132:135], v[188:191], v[28:31]
	v_mfma_f32_16x16x32_bf16 v[24:27], v[140:143], v[188:191], v[24:27]
	v_mfma_f32_16x16x32_bf16 v[12:15], v[132:135], v[196:199], v[12:15]
	v_mfma_f32_16x16x32_bf16 v[8:11], v[140:143], v[196:199], v[8:11]
	s_setprio 0
	s_barrier
	s_add_u32 s20, s20, 0x80080
	s_addc_u32 s21, s21, 0
	s_add_i32 s22, s22, s29
	v_lshl_add_u64 v[128:129], s[20:21], 0, v[150:151]
	s_mov_b32 m0, s22
	s_nop 0
	global_load_lds_dwordx4 v[128:129], off
	v_lshl_add_u64 v[128:129], s[20:21], 0, v[154:155]
	s_add_i32 m0, s22, 0x2000
	s_nop 0
	global_load_lds_dwordx4 v[128:129], off
	s_waitcnt vmcnt(6)
	s_barrier
	s_setprio 1
	v_mfma_f32_16x16x32_bf16 v[52:55], v[200:203], v[144:147], v[52:55]
	v_mfma_f32_16x16x32_bf16 v[48:51], v[208:211], v[144:147], v[48:51]
	v_mfma_f32_16x16x32_bf16 v[36:39], v[200:203], v[168:171], v[36:39]
	v_mfma_f32_16x16x32_bf16 v[32:35], v[208:211], v[168:171], v[32:35]
	v_mfma_f32_16x16x32_bf16 v[20:23], v[200:203], v[184:187], v[20:23]
	v_mfma_f32_16x16x32_bf16 v[16:19], v[208:211], v[184:187], v[16:19]
	v_mfma_f32_16x16x32_bf16 v[4:7], v[200:203], v[192:195], v[4:7]
	v_mfma_f32_16x16x32_bf16 v[0:3], v[208:211], v[192:195], v[0:3]
	v_mfma_f32_16x16x32_bf16 v[52:55], v[204:207], v[164:167], v[52:55]
	v_mfma_f32_16x16x32_bf16 v[48:51], v[212:215], v[164:167], v[48:51]
	v_mfma_f32_16x16x32_bf16 v[36:39], v[204:207], v[180:183], v[36:39]
	v_mfma_f32_16x16x32_bf16 v[32:35], v[212:215], v[180:183], v[32:35]
	v_mfma_f32_16x16x32_bf16 v[20:23], v[204:207], v[188:191], v[20:23]
	v_mfma_f32_16x16x32_bf16 v[16:19], v[212:215], v[188:191], v[16:19]
	v_mfma_f32_16x16x32_bf16 v[4:7], v[204:207], v[196:199], v[4:7]
	v_mfma_f32_16x16x32_bf16 v[0:3], v[212:215], v[196:199], v[0:3]
	s_setprio 0
	s_add_i32 s44, s44, 2
	s_add_u32 s18, s18, 0x100
	s_addc_u32 s19, s19, 0
	s_add_u32 s42, s42, 0x100
	s_addc_u32 s43, s43, 0
	s_cmp_gt_u32 s44, 29
	s_barrier
	s_cbranch_scc0 .LBB0_597
	s_branch .Lpeel_exit_t597

; __device__ __forceinline__ unsigned cvt_pk_bf16(float lo, float hi) { unsigned r; asm volatile("v_cvt_pk_bf16_f32 %0, %1, %2" : "=v"(r) : "v"(lo), "v"(hi)); return r; }
; __device__ __forceinline__ float bflo(unsigned u) { return __uint_as_float(u << 16); }
; __device__ __forceinline__ float bfhi(unsigned u) { return __uint_as_float(u & 0xffff0000u); }
;     __device__ __forceinline__ void operator()(const f32x4 (&acc)[2][2][4][2], const Unit& u, int wr, int wc, int fr, int fq) const {
;         const int row0 = u.pm * 256 + wr * 64 + fr; const int col0 = u.pn * 256 + wc * 32 + 8 * fq;
; #pragma unroll
;         for (int ai = 0; ai < 2; ++ai) {
;             u32x4 gv[4][2], yv[4][2];
; #pragma unroll
;             for (int m = 0; m < 4; ++m)
; #pragma unroll
;                 for (int bj = 0; bj < 2; ++bj) {
;                     const int row = row0 + ai * 128 + m * 16, col = col0 + bj * 128;
;                     gv[m][bj] = *(const u32x4*)(gates + (size_t)row * 2048 + SECOND * 1024 + col);
;                     if (SECOND) yv[m][bj] = *(const u32x4*)(Y + (size_t)row * 1024 + col);
;                 }
; #pragma unroll
;             for (int m = 0; m < 4; ++m)
; #pragma unroll
;                 for (int bj = 0; bj < 2; ++bj) {
;                     const int row = row0 + ai * 128 + m * 16, col = col0 + bj * 128;
;                     const u32x4 g = gv[m][bj];
;                     const f32x4 a0 = acc[ai][bj][m][0], a1 = acc[ai][bj][m][1];
;                     float r[8] = {a0[0] * bflo(g.x), a0[1] * bfhi(g.x), a0[2] * bflo(g.y), a0[3] * bfhi(g.y), a1[0] * bflo(g.z), a1[1] * bfhi(g.z), a1[2] * bflo(g.w), a1[3] * bfhi(g.w)};
;                     if (SECOND) { const u32x4 y = yv[m][bj];
;                         r[0] += bflo(y.x); r[1] += bfhi(y.x); r[2] += bflo(y.y); r[3] += bfhi(y.y); r[4] += bflo(y.z); r[5] += bfhi(y.z); r[6] += bflo(y.w); r[7] += bfhi(y.w); }
;                     u32x4 w; w.x = cvt_pk_bf16(r[0], r[1]); w.y = cvt_pk_bf16(r[2], r[3]); w.z = cvt_pk_bf16(r[4], r[5]); w.w = cvt_pk_bf16(r[6], r[7]);
;                     *(u32x4*)(Y + (size_t)row * 1024 + col) = w;
.Lpeel_exit_t597:
	v_lshl_add_u32 v164, s16, 8, v172
	v_lshl_or_b32 v128, s39, 8, v174
	v_ashrrev_i32_e32 v165, 31, v164
	v_ashrrev_i32_e32 v129, 31, v128
	v_lshlrev_b64 v[130:131], 12, v[164:165]
	v_lshl_add_u64 v[130:131], s[4:5], 0, v[130:131]
	v_lshlrev_b64 v[166:167], 1, v[128:129]
	v_lshl_add_u64 v[128:129], v[130:131], 0, v[166:167]
	v_lshlrev_b64 v[130:131], 11, v[164:165]
	v_lshl_add_u64 v[130:131], s[2:3], 0, v[130:131]
	v_lshl_add_u64 v[224:225], v[130:131], 0, v[166:167]
	global_load_dwordx4 v[180:183], v[128:129], off offset:2048
	global_load_dwordx4 v[184:187], v[224:225], off
	global_load_dwordx4 v[188:191], v[128:129], off offset:2304
	global_load_dwordx4 v[192:195], v[224:225], off offset:256
	v_or_b32_e32 v128, 16, v164
	v_ashrrev_i32_e32 v129, 31, v128
	v_lshlrev_b64 v[134:135], 12, v[128:129]
	v_lshlrev_b64 v[128:129], 11, v[128:129]
	v_lshl_add_u64 v[134:135], s[4:5], 0, v[134:135]
	v_lshl_add_u64 v[128:129], s[2:3], 0, v[128:129]
	v_lshl_add_u64 v[134:135], v[134:135], 0, v[166:167]
	v_lshl_add_u64 v[226:227], v[128:129], 0, v[166:167]
	global_load_dwordx4 v[196:199], v[134:135], off offset:2048
	global_load_dwordx4 v[200:203], v[226:227], off
	v_or_b32_e32 v130, 32, v164
	v_or_b32_e32 v132, 48, v164
	v_ashrrev_i32_e32 v131, 31, v130
	v_ashrrev_i32_e32 v133, 31, v132
	v_lshlrev_b64 v[136:137], 12, v[130:131]
	v_lshlrev_b64 v[130:131], 11, v[130:131]
	v_lshlrev_b64 v[138:139], 12, v[132:133]
	v_lshlrev_b64 v[132:133], 11, v[132:133]
	v_lshl_add_u64 v[136:137], s[4:5], 0, v[136:137]
	v_lshl_add_u64 v[130:131], s[2:3], 0, v[130:131]
	v_lshl_add_u64 v[138:139], s[4:5], 0, v[138:139]
	v_lshl_add_u64 v[132:133], s[2:3], 0, v[132:133]
	v_lshl_add_u64 v[128:129], v[136:137], 0, v[166:167]
	v_lshl_add_u64 v[170:171], v[130:131], 0, v[166:167]
	v_lshl_add_u64 v[130:131], v[138:139], 0, v[166:167]
	v_lshl_add_u64 v[168:169], v[132:133], 0, v[166:167]
	global_load_dwordx4 v[204:207], v[134:135], off offset:2304
	global_load_dwordx4 v[208:211], v[226:227], off offset:256
	global_load_dwordx4 v[212:215], v[128:129], off offset:2048
	global_load_dwordx4 v[216:219], v[128:129], off offset:2304
	global_load_dwordx4 v[220:223], v[170:171], off
	global_load_dwordx4 v[144:147], v[170:171], off offset:256
	global_load_dwordx4 v[140:143], v[130:131], off offset:2048
	global_load_dwordx4 v[132:135], v[130:131], off offset:2304
	global_load_dwordx4 v[136:139], v[168:169], off
	s_nop 0
	global_load_dwordx4 v[128:131], v[168:169], off offset:256
	s_and_b64 vcc, exec, s[0:1]
	s_mov_b32 s39, s8
	s_mov_b32 s16, s10
	s_mov_b64 s[20:21], s[14:15]
	s_mov_b64 s[18:19], s[12:13]
	s_waitcnt vmcnt(0)
	v_lshlrev_b32_e32 v231, 16, v184
	v_lshlrev_b32_e32 v235, 16, v188
	v_lshlrev_b32_e32 v239, 16, v192
	v_and_b32_e32 v188, 0xffff0000, v188
	v_fmac_f32_e32 v239, v116, v235
	v_and_b32_e32 v116, 0xffff0000, v192
	v_lshlrev_b32_e32 v165, 16, v180
	v_and_b32_e32 v180, 0xffff0000, v180
	v_lshlrev_b32_e32 v229, 16, v182
	v_and_b32_e32 v184, 0xffff0000, v184
	v_lshlrev_b32_e32 v233, 16, v186
	v_lshlrev_b32_e32 v236, 16, v189
	v_fmac_f32_e32 v116, v117, v188
	v_lshlrev_b32_e32 v117, 16, v193
	v_lshlrev_b32_e32 v228, 16, v181
	v_and_b32_e32 v181, 0xffff0000, v181
	v_and_b32_e32 v182, 0xffff0000, v182
	v_lshlrev_b32_e32 v230, 16, v183
	v_and_b32_e32 v183, 0xffff0000, v183
	v_lshlrev_b32_e32 v232, 16, v185
	v_and_b32_e32 v185, 0xffff0000, v185
	v_and_b32_e32 v186, 0xffff0000, v186
	v_lshlrev_b32_e32 v234, 16, v187
	v_and_b32_e32 v187, 0xffff0000, v187
	v_and_b32_e32 v189, 0xffff0000, v189
	v_fmac_f32_e32 v231, v124, v165
	v_fmac_f32_e32 v184, v125, v180
	v_fmac_f32_e32 v233, v120, v229
	v_cvt_pk_bf16_f32 v120, v231, v184
	v_fmac_f32_e32 v117, v118, v236
	v_and_b32_e32 v118, 0xffff0000, v193
	v_lshlrev_b32_e32 v237, 16, v190
	v_and_b32_e32 v190, 0xffff0000, v190
	v_fmac_f32_e32 v232, v126, v228
	v_fmac_f32_e32 v185, v127, v181
	v_fmac_f32_e32 v186, v121, v182
	v_fmac_f32_e32 v234, v122, v230
	v_fmac_f32_e32 v187, v123, v183
	v_cvt_pk_bf16_f32 v121, v232, v185
	v_cvt_pk_bf16_f32 v122, v233, v186
	v_cvt_pk_bf16_f32 v123, v234, v187
	global_store_dwordx4 v[224:225], v[120:123], off
	v_fmac_f32_e32 v118, v119, v189
	v_lshlrev_b32_e32 v119, 16, v194
	v_and_b32_e32 v120, 0xffff0000, v194
	v_lshlrev_b32_e32 v238, 16, v191
	v_and_b32_e32 v191, 0xffff0000, v191
	v_fmac_f32_e32 v119, v112, v237
	v_fmac_f32_e32 v120, v113, v190
	v_lshlrev_b32_e32 v121, 16, v195
	v_and_b32_e32 v122, 0xffff0000, v195
	v_cvt_pk_bf16_f32 v112, v239, v116
	v_fmac_f32_e32 v121, v114, v238
	v_fmac_f32_e32 v122, v115, v191
	v_cvt_pk_bf16_f32 v113, v117, v118
	v_cvt_pk_bf16_f32 v114, v119, v120
	v_cvt_pk_bf16_f32 v115, v121, v122
	global_store_dwordx4 v[224:225], v[112:115], off offset:256
	v_lshlrev_b32_e32 v120, 16, v200
	v_lshlrev_b32_e32 v116, 16, v198
	v_lshlrev_b32_e32 v112, 16, v196
	v_and_b32_e32 v113, 0xffff0000, v196
	v_fmac_f32_e32 v120, v108, v112
	v_and_b32_e32 v108, 0xffff0000, v200
	v_lshlrev_b32_e32 v114, 16, v197
	v_fmac_f32_e32 v108, v109, v113
	v_lshlrev_b32_e32 v109, 16, v201
	v_and_b32_e32 v115, 0xffff0000, v197
	v_fmac_f32_e32 v109, v110, v114
	v_and_b32_e32 v110, 0xffff0000, v201
	v_and_b32_e32 v117, 0xffff0000, v198
	v_fmac_f32_e32 v110, v111, v115
	v_lshlrev_b32_e32 v111, 16, v202
	v_and_b32_e32 v112, 0xffff0000, v202
	v_lshlrev_b32_e32 v118, 16, v199
	v_and_b32_e32 v119, 0xffff0000, v199
	v_fmac_f32_e32 v111, v104, v116
	v_fmac_f32_e32 v112, v105, v117
	v_lshlrev_b32_e32 v113, 16, v203
	v_and_b32_e32 v114, 0xffff0000, v203
	v_cvt_pk_bf16_f32 v104, v120, v108
	v_fmac_f32_e32 v113, v106, v118
	v_fmac_f32_e32 v114, v107, v119
	v_cvt_pk_bf16_f32 v105, v109, v110
; __device__ __forceinline__ unsigned cvt_pk_bf16(float lo, float hi) { unsigned r; asm volatile("v_cvt_pk_bf16_f32 %0, %1, %2" : "=v"(r) : "v"(lo), "v"(hi)); return r; }
; __device__ __forceinline__ float bflo(unsigned u) { return __uint_as_float(u << 16); }
; __device__ __forceinline__ float bfhi(unsigned u) { return __uint_as_float(u & 0xffff0000u); }
;     __device__ __forceinline__ void operator()(const f32x4 (&acc)[2][2][4][2], const Unit& u, int wr, int wc, int fr, int fq) const {
;     ...
;             for (int m = 0; m < 4; ++m)
; #pragma unroll
;                 for (int bj = 0; bj < 2; ++bj) {
;                     const int row = row0 + ai * 128 + m * 16, col = col0 + bj * 128;
;                     const u32x4 g = gv[m][bj];
;                     const f32x4 a0 = acc[ai][bj][m][0], a1 = acc[ai][bj][m][1];
;                     float r[8] = {a0[0] * bflo(g.x), a0[1] * bfhi(g.x), a0[2] * bflo(g.y), a0[3] * bfhi(g.y), a1[0] * bflo(g.z), a1[1] * bfhi(g.z), a1[2] * bflo(g.w), a1[3] * bfhi(g.w)};
;                     if (SECOND) { const u32x4 y = yv[m][bj];
;                         r[0] += bflo(y.x); r[1] += bfhi(y.x); r[2] += bflo(y.y); r[3] += bfhi(y.y); r[4] += bflo(y.z); r[5] += bfhi(y.z); r[6] += bflo(y.w); r[7] += bfhi(y.w); }
;                     u32x4 w; w.x = cvt_pk_bf16(r[0], r[1]); w.y = cvt_pk_bf16(r[2], r[3]); w.z = cvt_pk_bf16(r[4], r[5]); w.w = cvt_pk_bf16(r[6], r[7]);
;                     *(u32x4*)(Y + (size_t)row * 1024 + col) = w;
	v_cvt_pk_bf16_f32 v106, v111, v112
	v_cvt_pk_bf16_f32 v107, v113, v114
	global_store_dwordx4 v[226:227], v[104:107], off
	v_lshlrev_b32_e32 v112, 16, v208
	v_lshlrev_b32_e32 v108, 16, v206
	v_lshlrev_b32_e32 v104, 16, v204
	v_and_b32_e32 v105, 0xffff0000, v204
	v_fmac_f32_e32 v112, v100, v104
	v_and_b32_e32 v100, 0xffff0000, v208
	v_lshlrev_b32_e32 v106, 16, v205
	v_fmac_f32_e32 v100, v101, v105
	v_lshlrev_b32_e32 v101, 16, v209
	v_and_b32_e32 v107, 0xffff0000, v205
	v_fmac_f32_e32 v101, v102, v106
	v_and_b32_e32 v102, 0xffff0000, v209
	v_and_b32_e32 v109, 0xffff0000, v206
	v_fmac_f32_e32 v102, v103, v107
	v_lshlrev_b32_e32 v103, 16, v210
	v_and_b32_e32 v104, 0xffff0000, v210
	v_lshlrev_b32_e32 v110, 16, v207
	v_and_b32_e32 v111, 0xffff0000, v207
	v_fmac_f32_e32 v103, v96, v108
	v_fmac_f32_e32 v104, v97, v109
	v_lshlrev_b32_e32 v105, 16, v211
	v_and_b32_e32 v106, 0xffff0000, v211
	v_cvt_pk_bf16_f32 v96, v112, v100
	v_fmac_f32_e32 v105, v98, v110
	v_fmac_f32_e32 v106, v99, v111
	v_cvt_pk_bf16_f32 v97, v101, v102
	v_cvt_pk_bf16_f32 v98, v103, v104
	v_cvt_pk_bf16_f32 v99, v105, v106
	global_store_dwordx4 v[226:227], v[96:99], off offset:256
	v_lshlrev_b32_e32 v104, 16, v220
	v_lshlrev_b32_e32 v100, 16, v214
	v_lshlrev_b32_e32 v96, 16, v212
	v_and_b32_e32 v97, 0xffff0000, v212
	v_fmac_f32_e32 v104, v92, v96
	v_and_b32_e32 v92, 0xffff0000, v220
	v_lshlrev_b32_e32 v98, 16, v213
	v_fmac_f32_e32 v92, v93, v97
	v_lshlrev_b32_e32 v93, 16, v221
	v_and_b32_e32 v99, 0xffff0000, v213
	v_fmac_f32_e32 v93, v94, v98
	v_and_b32_e32 v94, 0xffff0000, v221
	v_and_b32_e32 v101, 0xffff0000, v214
	v_fmac_f32_e32 v94, v95, v99
	v_lshlrev_b32_e32 v95, 16, v222
	v_and_b32_e32 v96, 0xffff0000, v222
	v_lshlrev_b32_e32 v102, 16, v215
	v_and_b32_e32 v103, 0xffff0000, v215
	v_fmac_f32_e32 v95, v88, v100
	v_fmac_f32_e32 v96, v89, v101
	v_lshlrev_b32_e32 v97, 16, v223
	v_and_b32_e32 v98, 0xffff0000, v223
	v_cvt_pk_bf16_f32 v88, v104, v92
	v_fmac_f32_e32 v97, v90, v102
	v_fmac_f32_e32 v98, v91, v103
	v_cvt_pk_bf16_f32 v89, v93, v94
	v_cvt_pk_bf16_f32 v90, v95, v96
	v_cvt_pk_bf16_f32 v91, v97, v98
	global_store_dwordx4 v[170:171], v[88:91], off
	v_lshlrev_b32_e32 v96, 16, v144
	v_lshlrev_b32_e32 v92, 16, v218
	v_lshlrev_b32_e32 v88, 16, v216
	v_and_b32_e32 v89, 0xffff0000, v216
	v_fmac_f32_e32 v96, v84, v88
	v_and_b32_e32 v84, 0xffff0000, v144
	v_lshlrev_b32_e32 v90, 16, v217
	v_fmac_f32_e32 v84, v85, v89
	v_lshlrev_b32_e32 v85, 16, v145
	v_and_b32_e32 v91, 0xffff0000, v217
	v_fmac_f32_e32 v85, v86, v90
	v_and_b32_e32 v86, 0xffff0000, v145
	v_and_b32_e32 v93, 0xffff0000, v218
	v_fmac_f32_e32 v86, v87, v91
	v_lshlrev_b32_e32 v87, 16, v146
	v_and_b32_e32 v88, 0xffff0000, v146
	v_lshlrev_b32_e32 v94, 16, v219
	v_and_b32_e32 v95, 0xffff0000, v219
	v_fmac_f32_e32 v87, v80, v92
	v_fmac_f32_e32 v88, v81, v93
	v_lshlrev_b32_e32 v89, 16, v147
	v_and_b32_e32 v90, 0xffff0000, v147
	v_cvt_pk_bf16_f32 v80, v96, v84
	v_fmac_f32_e32 v89, v82, v94
	v_fmac_f32_e32 v90, v83, v95
	v_cvt_pk_bf16_f32 v81, v85, v86
	v_cvt_pk_bf16_f32 v82, v87, v88
	v_cvt_pk_bf16_f32 v83, v89, v90
	global_store_dwordx4 v[170:171], v[80:83], off offset:256
	v_lshlrev_b32_e32 v88, 16, v136
	v_lshlrev_b32_e32 v84, 16, v142
	v_lshlrev_b32_e32 v80, 16, v140
	v_and_b32_e32 v81, 0xffff0000, v140
	v_fmac_f32_e32 v88, v76, v80
	v_and_b32_e32 v76, 0xffff0000, v136
	v_lshlrev_b32_e32 v82, 16, v141
	v_fmac_f32_e32 v76, v77, v81
	v_lshlrev_b32_e32 v77, 16, v137
	v_and_b32_e32 v83, 0xffff0000, v141
	v_fmac_f32_e32 v77, v78, v82
	v_and_b32_e32 v78, 0xffff0000, v137
	v_and_b32_e32 v85, 0xffff0000, v142
	v_fmac_f32_e32 v78, v79, v83
	v_lshlrev_b32_e32 v79, 16, v138
	v_and_b32_e32 v80, 0xffff0000, v138
	v_lshlrev_b32_e32 v86, 16, v143
	v_and_b32_e32 v87, 0xffff0000, v143
	v_fmac_f32_e32 v79, v72, v84
	v_fmac_f32_e32 v80, v73, v85
	v_lshlrev_b32_e32 v81, 16, v139
	v_and_b32_e32 v82, 0xffff0000, v139
	v_cvt_pk_bf16_f32 v72, v88, v76
	v_fmac_f32_e32 v81, v74, v86
	v_fmac_f32_e32 v82, v75, v87
	v_cvt_pk_bf16_f32 v73, v77, v78
	v_cvt_pk_bf16_f32 v74, v79, v80
	v_cvt_pk_bf16_f32 v75, v81, v82
	global_store_dwordx4 v[168:169], v[72:75], off
	v_lshlrev_b32_e32 v80, 16, v128
	v_lshlrev_b32_e32 v76, 16, v134
	v_lshlrev_b32_e32 v72, 16, v132
	v_and_b32_e32 v73, 0xffff0000, v132
	v_fmac_f32_e32 v80, v68, v72
	v_and_b32_e32 v68, 0xffff0000, v128
	v_lshlrev_b32_e32 v74, 16, v133
	v_fmac_f32_e32 v68, v69, v73
	v_lshlrev_b32_e32 v69, 16, v129
	v_and_b32_e32 v75, 0xffff0000, v133
	v_fmac_f32_e32 v69, v70, v74
	v_and_b32_e32 v70, 0xffff0000, v129
	v_fmac_f32_e32 v70, v71, v75
	v_lshlrev_b32_e32 v71, 16, v130
	v_and_b32_e32 v77, 0xffff0000, v134
	v_lshlrev_b32_e32 v78, 16, v135
	v_and_b32_e32 v79, 0xffff0000, v135
	v_fmac_f32_e32 v71, v64, v76
	v_and_b32_e32 v72, 0xffff0000, v130
	v_lshlrev_b32_e32 v73, 16, v131
	v_and_b32_e32 v74, 0xffff0000, v131
	v_cvt_pk_bf16_f32 v64, v80, v68
	v_fmac_f32_e32 v72, v65, v77
	v_fmac_f32_e32 v73, v66, v78
	v_fmac_f32_e32 v74, v67, v79
	v_cvt_pk_bf16_f32 v65, v69, v70
	v_cvt_pk_bf16_f32 v66, v71, v72
	v_cvt_pk_bf16_f32 v67, v73, v74
	global_store_dwordx4 v[168:169], v[64:67], off offset:256
	s_nop 1
	v_add_u32_e32 v64, 0x80, v164
	v_ashrrev_i32_e32 v65, 31, v64
	v_lshlrev_b64 v[66:67], 12, v[64:65]
	v_lshl_add_u64 v[66:67], s[4:5], 0, v[66:67]
	v_lshl_add_u64 v[66:67], v[66:67], 0, v[166:167]
	v_lshlrev_b64 v[64:65], 11, v[64:65]
	global_load_dwordx4 v[88:91], v[66:67], off offset:2048
	v_lshl_add_u64 v[64:65], s[2:3], 0, v[64:65]
	v_lshl_add_u64 v[132:133], v[64:65], 0, v[166:167]
	global_load_dwordx4 v[92:95], v[132:133], off
	global_load_dwordx4 v[96:99], v[66:67], off offset:2304
; __device__ __forceinline__ unsigned cvt_pk_bf16(float lo, float hi) { unsigned r; asm volatile("v_cvt_pk_bf16_f32 %0, %1, %2" : "=v"(r) : "v"(lo), "v"(hi)); return r; }
; __device__ __forceinline__ float bflo(unsigned u) { return __uint_as_float(u << 16); }
; __device__ __forceinline__ float bfhi(unsigned u) { return __uint_as_float(u & 0xffff0000u); }
;     __device__ __forceinline__ void operator()(const f32x4 (&acc)[2][2][4][2], const Unit& u, int wr, int wc, int fr, int fq) const {
;     ...
;             for (int m = 0; m < 4; ++m)
; #pragma unroll
;                 for (int bj = 0; bj < 2; ++bj) {
;                     const int row = row0 + ai * 128 + m * 16, col = col0 + bj * 128;
;                     gv[m][bj] = *(const u32x4*)(gates + (size_t)row * 2048 + SECOND * 1024 + col);
;                     if (SECOND) yv[m][bj] = *(const u32x4*)(Y + (size_t)row * 1024 + col);
;                 }
; #pragma unroll
;             for (int m = 0; m < 4; ++m)
; #pragma unroll
;                 for (int bj = 0; bj < 2; ++bj) {
;                     const int row = row0 + ai * 128 + m * 16, col = col0 + bj * 128;
;                     const u32x4 g = gv[m][bj];
;                     const f32x4 a0 = acc[ai][bj][m][0], a1 = acc[ai][bj][m][1];
;                     float r[8] = {a0[0] * bflo(g.x), a0[1] * bfhi(g.x), a0[2] * bflo(g.y), a0[3] * bfhi(g.y), a1[0] * bflo(g.z), a1[1] * bfhi(g.z), a1[2] * bflo(g.w), a1[3] * bfhi(g.w)};
;                     if (SECOND) { const u32x4 y = yv[m][bj];
;                         r[0] += bflo(y.x); r[1] += bfhi(y.x); r[2] += bflo(y.y); r[3] += bfhi(y.y); r[4] += bflo(y.z); r[5] += bfhi(y.z); r[6] += bflo(y.w); r[7] += bfhi(y.w); }
;                     u32x4 w; w.x = cvt_pk_bf16(r[0], r[1]); w.y = cvt_pk_bf16(r[2], r[3]); w.z = cvt_pk_bf16(r[4], r[5]); w.w = cvt_pk_bf16(r[6], r[7]);
;                     *(u32x4*)(Y + (size_t)row * 1024 + col) = w;
	global_load_dwordx4 v[100:103], v[132:133], off offset:256
	v_add_u32_e32 v64, 0x90, v164
	v_ashrrev_i32_e32 v65, 31, v64
	v_lshlrev_b64 v[66:67], 12, v[64:65]
	v_lshl_add_u64 v[66:67], s[4:5], 0, v[66:67]
	v_lshlrev_b64 v[64:65], 11, v[64:65]
	v_lshl_add_u64 v[64:65], s[2:3], 0, v[64:65]
	v_lshl_add_u64 v[66:67], v[66:67], 0, v[166:167]
	v_lshl_add_u64 v[134:135], v[64:65], 0, v[166:167]
	global_load_dwordx4 v[104:107], v[66:67], off offset:2048
	global_load_dwordx4 v[108:111], v[66:67], off offset:2304
	global_load_dwordx4 v[112:115], v[134:135], off
	global_load_dwordx4 v[116:119], v[134:135], off offset:256
	v_add_u32_e32 v64, 0xa0, v164
	v_ashrrev_i32_e32 v65, 31, v64
	v_lshlrev_b64 v[66:67], 12, v[64:65]
	v_lshl_add_u64 v[66:67], s[4:5], 0, v[66:67]
	v_lshlrev_b64 v[64:65], 11, v[64:65]
	v_lshl_add_u64 v[64:65], s[2:3], 0, v[64:65]
	v_lshl_add_u64 v[66:67], v[66:67], 0, v[166:167]
	v_lshl_add_u64 v[86:87], v[64:65], 0, v[166:167]
	global_load_dwordx4 v[120:123], v[66:67], off offset:2048
	global_load_dwordx4 v[124:127], v[66:67], off offset:2304
	global_load_dwordx4 v[128:131], v[86:87], off
	global_load_dwordx4 v[80:83], v[86:87], off offset:256
	v_add_u32_e32 v64, 0xb0, v164
	v_ashrrev_i32_e32 v65, 31, v64
	v_lshlrev_b64 v[66:67], 12, v[64:65]
	v_lshl_add_u64 v[66:67], s[4:5], 0, v[66:67]
	v_lshlrev_b64 v[64:65], 11, v[64:65]
	v_lshl_add_u64 v[64:65], s[2:3], 0, v[64:65]
	v_lshl_add_u64 v[66:67], v[66:67], 0, v[166:167]
	v_lshl_add_u64 v[84:85], v[64:65], 0, v[166:167]
	global_load_dwordx4 v[76:79], v[66:67], off offset:2048
	global_load_dwordx4 v[68:71], v[66:67], off offset:2304
	global_load_dwordx4 v[72:75], v[84:85], off
	s_nop 0
	global_load_dwordx4 v[64:67], v[84:85], off offset:256
	s_waitcnt vmcnt(0)
	v_lshlrev_b32_e32 v136, 16, v88
	v_lshlrev_b32_e32 v140, 16, v92
	v_and_b32_e32 v88, 0xffff0000, v88
	v_fmac_f32_e32 v140, v60, v136
	v_and_b32_e32 v60, 0xffff0000, v92
	v_lshlrev_b32_e32 v137, 16, v89
	v_fmac_f32_e32 v60, v61, v88
	v_lshlrev_b32_e32 v61, 16, v93
	v_and_b32_e32 v89, 0xffff0000, v89
	v_fmac_f32_e32 v61, v62, v137
	v_and_b32_e32 v62, 0xffff0000, v93
	v_lshlrev_b32_e32 v138, 16, v90
	v_and_b32_e32 v90, 0xffff0000, v90
	v_fmac_f32_e32 v62, v63, v89
	v_lshlrev_b32_e32 v63, 16, v94
	v_and_b32_e32 v88, 0xffff0000, v94
	v_lshlrev_b32_e32 v139, 16, v91
	v_and_b32_e32 v91, 0xffff0000, v91
	v_fmac_f32_e32 v63, v56, v138
	v_fmac_f32_e32 v88, v57, v90
	v_lshlrev_b32_e32 v89, 16, v95
	v_and_b32_e32 v90, 0xffff0000, v95
	v_cvt_pk_bf16_f32 v56, v140, v60
	v_fmac_f32_e32 v89, v58, v139
	v_fmac_f32_e32 v90, v59, v91
	v_cvt_pk_bf16_f32 v57, v61, v62
	v_cvt_pk_bf16_f32 v58, v63, v88
	v_cvt_pk_bf16_f32 v59, v89, v90
	global_store_dwordx4 v[132:133], v[56:59], off
	v_lshlrev_b32_e32 v88, 16, v100
	v_lshlrev_b32_e32 v60, 16, v98
	v_lshlrev_b32_e32 v56, 16, v96
	v_and_b32_e32 v57, 0xffff0000, v96
	v_fmac_f32_e32 v88, v52, v56
	v_and_b32_e32 v52, 0xffff0000, v100
	v_lshlrev_b32_e32 v58, 16, v97
	v_fmac_f32_e32 v52, v53, v57
	v_lshlrev_b32_e32 v53, 16, v101
	v_and_b32_e32 v59, 0xffff0000, v97
	v_fmac_f32_e32 v53, v54, v58
	v_and_b32_e32 v54, 0xffff0000, v101
	v_and_b32_e32 v61, 0xffff0000, v98
	v_fmac_f32_e32 v54, v55, v59
	v_lshlrev_b32_e32 v55, 16, v102
	v_and_b32_e32 v56, 0xffff0000, v102
	v_lshlrev_b32_e32 v62, 16, v99
	v_and_b32_e32 v63, 0xffff0000, v99
	v_fmac_f32_e32 v55, v48, v60
	v_fmac_f32_e32 v56, v49, v61
	v_lshlrev_b32_e32 v57, 16, v103
	v_and_b32_e32 v58, 0xffff0000, v103
	v_cvt_pk_bf16_f32 v48, v88, v52
	v_fmac_f32_e32 v57, v50, v62
	v_fmac_f32_e32 v58, v51, v63
	v_cvt_pk_bf16_f32 v49, v53, v54
	v_cvt_pk_bf16_f32 v50, v55, v56
	v_cvt_pk_bf16_f32 v51, v57, v58
	global_store_dwordx4 v[132:133], v[48:51], off offset:256
	v_lshlrev_b32_e32 v56, 16, v112
	v_lshlrev_b32_e32 v52, 16, v106
	v_lshlrev_b32_e32 v48, 16, v104
	v_and_b32_e32 v49, 0xffff0000, v104
	v_fmac_f32_e32 v56, v44, v48
	v_and_b32_e32 v44, 0xffff0000, v112
	v_lshlrev_b32_e32 v50, 16, v105
	v_fmac_f32_e32 v44, v45, v49
	v_lshlrev_b32_e32 v45, 16, v113
	v_and_b32_e32 v51, 0xffff0000, v105
	v_fmac_f32_e32 v45, v46, v50
	v_and_b32_e32 v46, 0xffff0000, v113
	v_and_b32_e32 v53, 0xffff0000, v106
	v_fmac_f32_e32 v46, v47, v51
	v_lshlrev_b32_e32 v47, 16, v114
	v_and_b32_e32 v48, 0xffff0000, v114
	v_lshlrev_b32_e32 v54, 16, v107
	v_and_b32_e32 v55, 0xffff0000, v107
	v_fmac_f32_e32 v47, v40, v52
	v_fmac_f32_e32 v48, v41, v53
	v_lshlrev_b32_e32 v49, 16, v115
	v_and_b32_e32 v50, 0xffff0000, v115
	v_cvt_pk_bf16_f32 v40, v56, v44
	v_fmac_f32_e32 v49, v42, v54
	v_fmac_f32_e32 v50, v43, v55
	v_cvt_pk_bf16_f32 v41, v45, v46
	v_cvt_pk_bf16_f32 v42, v47, v48
	v_cvt_pk_bf16_f32 v43, v49, v50
	global_store_dwordx4 v[134:135], v[40:43], off
	v_lshlrev_b32_e32 v48, 16, v116
	v_lshlrev_b32_e32 v44, 16, v110
	v_lshlrev_b32_e32 v40, 16, v108
	v_and_b32_e32 v41, 0xffff0000, v108
; __device__ __forceinline__ unsigned cvt_pk_bf16(float lo, float hi) { unsigned r; asm volatile("v_cvt_pk_bf16_f32 %0, %1, %2" : "=v"(r) : "v"(lo), "v"(hi)); return r; }
; __device__ __forceinline__ float bflo(unsigned u) { return __uint_as_float(u << 16); }
; __device__ __forceinline__ float bfhi(unsigned u) { return __uint_as_float(u & 0xffff0000u); }
; #define PG8_WAIT_V(n) asm volatile("s_waitcnt vmcnt(" #n ")" ::: "memory")
; #define PG8_BAR __builtin_amdgcn_s_barrier()
; template <class Epi, class Sched>
; __device__ __forceinline__ void gemm_phase(const int wv, LAS unsigned char* lds, const Gemm g, const Sched& S, const Epi& E) {
;     ...
;         E(acc, cur, wr, wc, fr, fq); S.done(cur);
;         if (!has_next) break;
; #pragma unroll
;         for (int a = 0; a < 2; ++a)
; #pragma unroll
;             for (int b = 0; b < 2; ++b)
; #pragma unroll
;                 for (int m = 0; m < 4; ++m)
; #pragma unroll
;                     for (int n = 0; n < 2; ++n) acc[a][b][m][n] = (f32x4){0.f, 0.f, 0.f, 0.f};
;         cur = nxt; cA = nA; cB = nB; ++ui;
;     }
;     PG8_WAIT_V(0);
;     if (wr == 0) PG8_BAR;
;     PG8_BAR;
;     __device__ __forceinline__ void operator()(const f32x4 (&acc)[2][2][4][2], const Unit& u, int wr, int wc, int fr, int fq) const {
;     ...
;             for (int m = 0; m < 4; ++m)
; #pragma unroll
;                 for (int bj = 0; bj < 2; ++bj) {
;                     const int row = row0 + ai * 128 + m * 16, col = col0 + bj * 128;
;                     const u32x4 g = gv[m][bj];
;                     const f32x4 a0 = acc[ai][bj][m][0], a1 = acc[ai][bj][m][1];
;                     float r[8] = {a0[0] * bflo(g.x), a0[1] * bfhi(g.x), a0[2] * bflo(g.y), a0[3] * bfhi(g.y), a1[0] * bflo(g.z), a1[1] * bfhi(g.z), a1[2] * bflo(g.w), a1[3] * bfhi(g.w)};
;                     if (SECOND) { const u32x4 y = yv[m][bj];
;                         r[0] += bflo(y.x); r[1] += bfhi(y.x); r[2] += bflo(y.y); r[3] += bfhi(y.y); r[4] += bflo(y.z); r[5] += bfhi(y.z); r[6] += bflo(y.w); r[7] += bfhi(y.w); }
;                     u32x4 w; w.x = cvt_pk_bf16(r[0], r[1]); w.y = cvt_pk_bf16(r[2], r[3]); w.z = cvt_pk_bf16(r[4], r[5]); w.w = cvt_pk_bf16(r[6], r[7]);
;                     *(u32x4*)(Y + (size_t)row * 1024 + col) = w;
	v_fmac_f32_e32 v48, v36, v40
	v_and_b32_e32 v36, 0xffff0000, v116
	v_lshlrev_b32_e32 v42, 16, v109
	v_fmac_f32_e32 v36, v37, v41
	v_lshlrev_b32_e32 v37, 16, v117
	v_and_b32_e32 v43, 0xffff0000, v109
	v_fmac_f32_e32 v37, v38, v42
	v_and_b32_e32 v38, 0xffff0000, v117
	v_and_b32_e32 v45, 0xffff0000, v110
	v_fmac_f32_e32 v38, v39, v43
	v_lshlrev_b32_e32 v39, 16, v118
	v_and_b32_e32 v40, 0xffff0000, v118
	v_lshlrev_b32_e32 v46, 16, v111
	v_and_b32_e32 v47, 0xffff0000, v111
	v_fmac_f32_e32 v39, v32, v44
	v_fmac_f32_e32 v40, v33, v45
	v_lshlrev_b32_e32 v41, 16, v119
	v_and_b32_e32 v42, 0xffff0000, v119
	v_cvt_pk_bf16_f32 v32, v48, v36
	v_fmac_f32_e32 v41, v34, v46
	v_fmac_f32_e32 v42, v35, v47
	v_cvt_pk_bf16_f32 v33, v37, v38
	v_cvt_pk_bf16_f32 v34, v39, v40
	v_cvt_pk_bf16_f32 v35, v41, v42
	global_store_dwordx4 v[134:135], v[32:35], off offset:256
	v_lshlrev_b32_e32 v40, 16, v128
	v_lshlrev_b32_e32 v36, 16, v122
	v_lshlrev_b32_e32 v32, 16, v120
	v_and_b32_e32 v33, 0xffff0000, v120
	v_fmac_f32_e32 v40, v28, v32
	v_and_b32_e32 v28, 0xffff0000, v128
	v_lshlrev_b32_e32 v34, 16, v121
	v_fmac_f32_e32 v28, v29, v33
	v_lshlrev_b32_e32 v29, 16, v129
	v_and_b32_e32 v35, 0xffff0000, v121
	v_fmac_f32_e32 v29, v30, v34
	v_and_b32_e32 v30, 0xffff0000, v129
	v_and_b32_e32 v37, 0xffff0000, v122
	v_fmac_f32_e32 v30, v31, v35
	v_lshlrev_b32_e32 v31, 16, v130
	v_and_b32_e32 v32, 0xffff0000, v130
	v_lshlrev_b32_e32 v38, 16, v123
	v_and_b32_e32 v39, 0xffff0000, v123
	v_fmac_f32_e32 v31, v24, v36
	v_fmac_f32_e32 v32, v25, v37
	v_lshlrev_b32_e32 v33, 16, v131
	v_and_b32_e32 v34, 0xffff0000, v131
	v_cvt_pk_bf16_f32 v24, v40, v28
	v_fmac_f32_e32 v33, v26, v38
	v_fmac_f32_e32 v34, v27, v39
	v_cvt_pk_bf16_f32 v25, v29, v30
	v_cvt_pk_bf16_f32 v26, v31, v32
	v_cvt_pk_bf16_f32 v27, v33, v34
	global_store_dwordx4 v[86:87], v[24:27], off
	v_lshlrev_b32_e32 v32, 16, v80
	v_lshlrev_b32_e32 v28, 16, v126
	v_lshlrev_b32_e32 v24, 16, v124
	v_and_b32_e32 v25, 0xffff0000, v124
	v_fmac_f32_e32 v32, v20, v24
	v_and_b32_e32 v20, 0xffff0000, v80
	v_lshlrev_b32_e32 v26, 16, v125
	v_fmac_f32_e32 v20, v21, v25
	v_lshlrev_b32_e32 v21, 16, v81
	v_and_b32_e32 v27, 0xffff0000, v125
	v_fmac_f32_e32 v21, v22, v26
	v_and_b32_e32 v22, 0xffff0000, v81
	v_and_b32_e32 v29, 0xffff0000, v126
	v_fmac_f32_e32 v22, v23, v27
	v_lshlrev_b32_e32 v23, 16, v82
	v_and_b32_e32 v24, 0xffff0000, v82
	v_lshlrev_b32_e32 v30, 16, v127
	v_and_b32_e32 v31, 0xffff0000, v127
	v_fmac_f32_e32 v23, v16, v28
	v_fmac_f32_e32 v24, v17, v29
	v_lshlrev_b32_e32 v25, 16, v83
	v_and_b32_e32 v26, 0xffff0000, v83
	v_cvt_pk_bf16_f32 v16, v32, v20
	v_fmac_f32_e32 v25, v18, v30
	v_fmac_f32_e32 v26, v19, v31
	v_cvt_pk_bf16_f32 v17, v21, v22
	v_cvt_pk_bf16_f32 v18, v23, v24
	v_cvt_pk_bf16_f32 v19, v25, v26
	global_store_dwordx4 v[86:87], v[16:19], off offset:256
	v_lshlrev_b32_e32 v24, 16, v72
	v_lshlrev_b32_e32 v20, 16, v78
	v_lshlrev_b32_e32 v16, 16, v76
	v_and_b32_e32 v17, 0xffff0000, v76
	v_fmac_f32_e32 v24, v12, v16
	v_and_b32_e32 v12, 0xffff0000, v72
	v_lshlrev_b32_e32 v18, 16, v77
	v_fmac_f32_e32 v12, v13, v17
	v_lshlrev_b32_e32 v13, 16, v73
	v_and_b32_e32 v19, 0xffff0000, v77
	v_fmac_f32_e32 v13, v14, v18
	v_and_b32_e32 v14, 0xffff0000, v73
	v_and_b32_e32 v21, 0xffff0000, v78
	v_fmac_f32_e32 v14, v15, v19
	v_lshlrev_b32_e32 v15, 16, v74
	v_and_b32_e32 v16, 0xffff0000, v74
	v_lshlrev_b32_e32 v22, 16, v79
	v_and_b32_e32 v23, 0xffff0000, v79
	v_fmac_f32_e32 v15, v8, v20
	v_fmac_f32_e32 v16, v9, v21
	v_lshlrev_b32_e32 v17, 16, v75
	v_and_b32_e32 v18, 0xffff0000, v75
	v_cvt_pk_bf16_f32 v8, v24, v12
	v_fmac_f32_e32 v17, v10, v22
	v_fmac_f32_e32 v18, v11, v23
	v_cvt_pk_bf16_f32 v9, v13, v14
	v_cvt_pk_bf16_f32 v10, v15, v16
	v_cvt_pk_bf16_f32 v11, v17, v18
	global_store_dwordx4 v[84:85], v[8:11], off
	v_lshlrev_b32_e32 v16, 16, v64
	v_lshlrev_b32_e32 v12, 16, v70
	v_lshlrev_b32_e32 v8, 16, v68
	v_and_b32_e32 v9, 0xffff0000, v68
	v_fmac_f32_e32 v16, v4, v8
	v_and_b32_e32 v4, 0xffff0000, v64
	v_lshlrev_b32_e32 v10, 16, v69
	v_fmac_f32_e32 v4, v5, v9
	v_lshlrev_b32_e32 v5, 16, v65
	v_and_b32_e32 v11, 0xffff0000, v69
	v_fmac_f32_e32 v5, v6, v10
	v_and_b32_e32 v6, 0xffff0000, v65
	v_and_b32_e32 v13, 0xffff0000, v70
	v_lshlrev_b32_e32 v14, 16, v71
	v_and_b32_e32 v15, 0xffff0000, v71
	v_fmac_f32_e32 v6, v7, v11
	v_lshlrev_b32_e32 v7, 16, v66
	v_and_b32_e32 v8, 0xffff0000, v66
	v_lshlrev_b32_e32 v9, 16, v67
	v_and_b32_e32 v10, 0xffff0000, v67
	v_fmac_f32_e32 v7, v0, v12
	v_fmac_f32_e32 v8, v1, v13
	v_fmac_f32_e32 v9, v2, v14
	v_fmac_f32_e32 v10, v3, v15
	v_cvt_pk_bf16_f32 v0, v16, v4
	v_cvt_pk_bf16_f32 v1, v5, v6
	v_cvt_pk_bf16_f32 v2, v7, v8
	v_cvt_pk_bf16_f32 v3, v9, v10
	global_store_dwordx4 v[84:85], v[0:3], off offset:256
	s_cbranch_vccz .LBB0_590
	s_waitcnt vmcnt(0)
	s_cmpk_gt_u32 s24, 0xff
	s_cbranch_scc1 .LBB0_601
	s_barrier

; #define PG8_STAGE(bufoff, gbase, voff) do { _Pragma("unroll") for (int _i = 0; _i < 2; ++_i) \
;         __builtin_amdgcn_global_load_lds((const unsigned*)((const char*)(gbase) + (voff)[_i]), (LAS unsigned*)(lds + (bufoff) + ldsw + _i * 8192), 16, 0, 0); } while (0)
; #define PG8_LDA(dst, b, h) do { _Pragma("unroll") for (int m = 0; m < 4; ++m) _Pragma("unroll") for (int k = 0; k < 2; ++k) dst[m][k] = *(const LAS bf16x8*)(lds + PG8_SA(b, h) + aoff + m * 2048 + k * 1024); } while (0)
; #define PG8_LDB(dst, b, h) do { _Pragma("unroll") for (int n = 0; n < 2; ++n) _Pragma("unroll") for (int k = 0; k < 2; ++k) dst[n][k] = *(const LAS bf16x8*)(lds + PG8_SB(b, h) + boff + n * 2048 + k * 1024); } while (0)
; #define PG8_MMA(ai, bj, At, Bt) do { __builtin_amdgcn_s_setprio(1); _Pragma("unroll") for (int m = 0; m < 4; ++m) _Pragma("unroll") for (int n = 0; n < 2; ++n) _Pragma("unroll") for (int k = 0; k < 2; ++k) \
;         acc[ai][bj][m][n] = __builtin_amdgcn_mfma_f32_16x16x32_bf16(Bt[n][k], At[m][k], acc[ai][bj][m][n], 0, 0, 0); __builtin_amdgcn_s_setprio(0); } while (0)
; template <class Epi, class Sched>
; __device__ __forceinline__ void gemm_phase(const int wv, LAS unsigned char* lds, const Gemm g, const Sched& S, const Epi& E) {
;     ...
;         const bool has_next = S.next(ui + 1, nxt);
;         const char* nA = has_next ? (const char*)g.A + (size_t)nxt.pm * tstepA : cA; const char* nB = has_next ? (const char*)g.Bt + (size_t)nxt.pn * tstepB : cB;
;         for (int t = 0; t < nt; t += 2) {
;             const bool last = (t == nt - 2);
;             const char* a1 = cA + (size_t)(t + 1) * kstepA;
;             const char* a2 = last ? nA : cA + (size_t)(t + 2) * kstepA; const char* b2 = last ? nB : cB + (size_t)(t + 2) * kstep;
;             const char* a3 = a2 + kstepA; const char* b3 = b2 + kstep;
;             if (last && has_next) S.a_ready(nxt);
;             PG8_LDB(B0, 0, 0); PG8_SCHED; PG8_LDA(At, 0, 0); PG8_STAGE(PG8_SA(1, 1), a1 + hstepA, voffA);
;             PG8_WAIT_L(8); PG8_BAR; PG8_WAIT_L(0); PG8_MMA(0, 0, At, B0); PG8_BAR; PG8_SCHED;
;             PG8_LDB(B1, 0, 1); PG8_STAGE(PG8_SB(0, 0), b2, voffB);
;             PG8_BAR; PG8_WAIT_L(0); PG8_MMA(0, 1, At, B1); PG8_BAR;
;             PG8_LDA(At, 0, 1); PG8_STAGE(PG8_SA(0, 0), a2, voffA);
;             PG8_BAR; PG8_WAIT_L(0); PG8_MMA(1, 0, At, B0); PG8_BAR; PG8_SCHED;
.LBB0_660:
	s_ashr_i32 s15, s14, 31
	v_cmp_lt_i64_e32 vcc, s[16:17], v[156:157]
	s_lshl_b64 s[16:17], s[14:15], 19
	s_add_u32 s16, s29, s16
	s_addc_u32 s17, s30, s17
	s_and_b64 s[18:19], vcc, exec
	s_cselect_b32 s15, s17, s23
	s_cselect_b32 s44, s16, s22
	s_ashr_i32 s13, s12, 31
	s_lshl_b64 s[18:19], s[12:13], 19
	s_add_u32 s18, s31, s18
	s_addc_u32 s19, s33, s19
	s_and_b64 s[26:27], vcc, exec
	s_cselect_b32 s13, s19, s25
	s_cselect_b32 s45, s18, s24
	s_add_u32 s22, s22, 0x40080
	s_addc_u32 s23, s23, 0
	s_add_u32 s46, s24, 0x100
	s_addc_u32 s47, s25, 0
	s_mov_b32 s48, -2
	ds_read_b128 v[128:131], v177
	ds_read_b128 v[132:135], v177 offset:1024
	ds_read_b128 v[136:139], v177 offset:2048
	ds_read_b128 v[140:143], v177 offset:3072
	s_add_u32 s24, s22, 0xfffc0080
	s_addc_u32 s25, s23, -1
	s_cmp_eq_u32 s48, 12
	s_cselect_b32 s27, s15, s25
	s_cselect_b32 s26, s44, s24
	s_cselect_b32 s25, s13, s47
	s_cselect_b32 s24, s45, s46
	v_lshl_add_u64 v[202:203], s[22:23], 0, v[152:153]
	s_add_i32 m0, s35, 0xc000
	ds_read_b128 v[160:163], v180
	ds_read_b128 v[164:167], v180 offset:1024
	ds_read_b128 v[168:171], v180 offset:2048
	ds_read_b128 v[182:185], v180 offset:3072
	ds_read_b128 v[186:189], v180 offset:4096
	ds_read_b128 v[190:193], v180 offset:5120
	ds_read_b128 v[194:197], v180 offset:6144
	ds_read_b128 v[198:201], v180 offset:7168
	global_load_lds_dwordx4 v[202:203], off
	v_lshl_add_u64 v[202:203], s[22:23], 0, v[154:155]
	s_add_i32 m0, s35, 0xe000
	s_nop 0
	global_load_lds_dwordx4 v[202:203], off
	s_waitcnt lgkmcnt(8)
	s_barrier
	s_waitcnt lgkmcnt(0)
	s_setprio 1
	s_waitcnt lgkmcnt(0)
	v_mfma_f32_16x16x32_bf16 v[124:127], v[128:131], v[160:163], 0
	v_mfma_f32_16x16x32_bf16 v[120:123], v[136:139], v[160:163], 0
	v_mfma_f32_16x16x32_bf16 v[116:119], v[128:131], v[168:171], 0
	v_mfma_f32_16x16x32_bf16 v[104:107], v[136:139], v[168:171], 0
	v_mfma_f32_16x16x32_bf16 v[92:95], v[128:131], v[186:189], 0
	v_mfma_f32_16x16x32_bf16 v[88:91], v[136:139], v[186:189], 0
	v_mfma_f32_16x16x32_bf16 v[76:79], v[128:131], v[194:197], 0
	v_mfma_f32_16x16x32_bf16 v[72:75], v[136:139], v[194:197], 0
	v_mfma_f32_16x16x32_bf16 v[124:127], v[132:135], v[164:167], v[124:127]
	v_mfma_f32_16x16x32_bf16 v[120:123], v[140:143], v[164:167], v[120:123]
	v_mfma_f32_16x16x32_bf16 v[116:119], v[132:135], v[182:185], v[116:119]
	v_mfma_f32_16x16x32_bf16 v[104:107], v[140:143], v[182:185], v[104:107]
	v_mfma_f32_16x16x32_bf16 v[92:95], v[132:135], v[190:193], v[92:95]
	v_mfma_f32_16x16x32_bf16 v[88:91], v[140:143], v[190:193], v[88:91]
	v_mfma_f32_16x16x32_bf16 v[76:79], v[132:135], v[198:201], v[76:79]
	v_mfma_f32_16x16x32_bf16 v[72:75], v[140:143], v[198:201], v[72:75]
	s_setprio 0
	s_barrier
	s_add_i32 s49, s41, s34
	v_lshl_add_u64 v[218:219], s[24:25], 0, v[146:147]
	s_mov_b32 m0, s49
	ds_read_b128 v[202:205], v181
	ds_read_b128 v[206:209], v181 offset:1024
	ds_read_b128 v[210:213], v181 offset:2048
	ds_read_b128 v[214:217], v181 offset:3072
	global_load_lds_dwordx4 v[218:219], off
	v_lshl_add_u64 v[220:221], s[24:25], 0, v[150:151]
	s_add_i32 m0, s49, 0x2000
	s_nop 0
	global_load_lds_dwordx4 v[220:221], off
	s_barrier
	s_waitcnt lgkmcnt(0)
	s_setprio 1
	s_waitcnt lgkmcnt(0)
	v_mfma_f32_16x16x32_bf16 v[112:115], v[202:205], v[160:163], 0
	v_mfma_f32_16x16x32_bf16 v[108:111], v[210:213], v[160:163], 0
	v_mfma_f32_16x16x32_bf16 v[100:103], v[202:205], v[168:171], 0
	v_mfma_f32_16x16x32_bf16 v[96:99], v[210:213], v[168:171], 0
	v_mfma_f32_16x16x32_bf16 v[84:87], v[202:205], v[186:189], 0
	v_mfma_f32_16x16x32_bf16 v[80:83], v[210:213], v[186:189], 0
	v_mfma_f32_16x16x32_bf16 v[68:71], v[202:205], v[194:197], 0
	v_mfma_f32_16x16x32_bf16 v[64:67], v[210:213], v[194:197], 0
	v_mfma_f32_16x16x32_bf16 v[112:115], v[206:209], v[164:167], v[112:115]
	v_mfma_f32_16x16x32_bf16 v[108:111], v[214:217], v[164:167], v[108:111]
	v_mfma_f32_16x16x32_bf16 v[100:103], v[206:209], v[182:185], v[100:103]
	v_mfma_f32_16x16x32_bf16 v[96:99], v[214:217], v[182:185], v[96:99]
	v_mfma_f32_16x16x32_bf16 v[84:87], v[206:209], v[190:193], v[84:87]
	v_mfma_f32_16x16x32_bf16 v[80:83], v[214:217], v[190:193], v[80:83]
	v_mfma_f32_16x16x32_bf16 v[68:71], v[206:209], v[198:201], v[68:71]
	v_mfma_f32_16x16x32_bf16 v[64:67], v[214:217], v[198:201], v[64:67]
	s_setprio 0
	s_mov_b32 m0, s35
	v_lshl_add_u64 v[222:223], s[26:27], 0, v[144:145]
	s_barrier
	ds_read_b128 v[160:163], v180 offset:16384
	ds_read_b128 v[164:167], v180 offset:17408
	ds_read_b128 v[168:171], v180 offset:18432
	ds_read_b128 v[182:185], v180 offset:19456
	ds_read_b128 v[186:189], v180 offset:20480
	ds_read_b128 v[190:193], v180 offset:21504
	ds_read_b128 v[194:197], v180 offset:22528
	ds_read_b128 v[198:201], v180 offset:23552
	global_load_lds_dwordx4 v[222:223], off
	v_lshl_add_u64 v[224:225], s[26:27], 0, v[148:149]
	s_mov_b32 m0, s36
	s_nop 0
	global_load_lds_dwordx4 v[224:225], off
	s_barrier
	s_waitcnt lgkmcnt(0)
	s_setprio 1
	s_waitcnt lgkmcnt(0)
	v_mfma_f32_16x16x32_bf16 v[60:63], v[128:131], v[160:163], 0
	v_mfma_f32_16x16x32_bf16 v[56:59], v[136:139], v[160:163], 0
	v_mfma_f32_16x16x32_bf16 v[44:47], v[128:131], v[168:171], 0
	v_mfma_f32_16x16x32_bf16 v[40:43], v[136:139], v[168:171], 0
	v_mfma_f32_16x16x32_bf16 v[28:31], v[128:131], v[186:189], 0
	v_mfma_f32_16x16x32_bf16 v[24:27], v[136:139], v[186:189], 0
	v_mfma_f32_16x16x32_bf16 v[12:15], v[128:131], v[194:197], 0
	v_mfma_f32_16x16x32_bf16 v[8:11], v[136:139], v[194:197], 0
	v_mfma_f32_16x16x32_bf16 v[60:63], v[132:135], v[164:167], v[60:63]
	v_mfma_f32_16x16x32_bf16 v[56:59], v[140:143], v[164:167], v[56:59]
	v_mfma_f32_16x16x32_bf16 v[44:47], v[132:135], v[182:185], v[44:47]
	v_mfma_f32_16x16x32_bf16 v[40:43], v[140:143], v[182:185], v[40:43]
	v_mfma_f32_16x16x32_bf16 v[28:31], v[132:135], v[190:193], v[28:31]
	v_mfma_f32_16x16x32_bf16 v[24:27], v[140:143], v[190:193], v[24:27]
	v_mfma_f32_16x16x32_bf16 v[12:15], v[132:135], v[198:201], v[12:15]
	v_mfma_f32_16x16x32_bf16 v[8:11], v[140:143], v[198:201], v[8:11]
	s_setprio 0
	s_barrier
; #define PG8_STAGE(bufoff, gbase, voff) do { _Pragma("unroll") for (int _i = 0; _i < 2; ++_i) \
;         __builtin_amdgcn_global_load_lds((const unsigned*)((const char*)(gbase) + (voff)[_i]), (LAS unsigned*)(lds + (bufoff) + ldsw + _i * 8192), 16, 0, 0); } while (0)
; #define PG8_LDA(dst, b, h) do { _Pragma("unroll") for (int m = 0; m < 4; ++m) _Pragma("unroll") for (int k = 0; k < 2; ++k) dst[m][k] = *(const LAS bf16x8*)(lds + PG8_SA(b, h) + aoff + m * 2048 + k * 1024); } while (0)
; #define PG8_LDB(dst, b, h) do { _Pragma("unroll") for (int n = 0; n < 2; ++n) _Pragma("unroll") for (int k = 0; k < 2; ++k) dst[n][k] = *(const LAS bf16x8*)(lds + PG8_SB(b, h) + boff + n * 2048 + k * 1024); } while (0)
; #define PG8_MMA(ai, bj, At, Bt) do { __builtin_amdgcn_s_setprio(1); _Pragma("unroll") for (int m = 0; m < 4; ++m) _Pragma("unroll") for (int n = 0; n < 2; ++n) _Pragma("unroll") for (int k = 0; k < 2; ++k) \
;         acc[ai][bj][m][n] = __builtin_amdgcn_mfma_f32_16x16x32_bf16(Bt[n][k], At[m][k], acc[ai][bj][m][n], 0, 0, 0); __builtin_amdgcn_s_setprio(0); } while (0)
; #define PG8_WAIT_V(n) asm volatile("s_waitcnt vmcnt(" #n ")" ::: "memory")
; #define PG8_WAIT_L(n) asm volatile("s_waitcnt lgkmcnt(" #n ")" ::: "memory")
; #define PG8_BAR __builtin_amdgcn_s_barrier()
; #define PG8_SCHED __builtin_amdgcn_sched_barrier(0)
; template <class Epi, class Sched>
; __device__ __forceinline__ void gemm_phase(const int wv, LAS unsigned char* lds, const Gemm g, const Sched& S, const Epi& E) {
;     ...
;             PG8_STAGE(PG8_SB(0, 1), b2 + hstepB, voffB);
;             PG8_WAIT_V(6); PG8_BAR; PG8_MMA(1, 1, At, B1); PG8_BAR;
;             PG8_LDB(B0, 1, 0); PG8_SCHED; PG8_LDA(At, 1, 0); PG8_STAGE(PG8_SA(0, 1), a2 + hstepA, voffA);
;             PG8_WAIT_L(8); PG8_BAR; PG8_WAIT_L(0); PG8_MMA(0, 0, At, B0); PG8_BAR; PG8_SCHED;
;             PG8_LDB(B1, 1, 1); PG8_STAGE(PG8_SB(1, 0), b3, voffB);
;             PG8_BAR; PG8_WAIT_L(0); PG8_MMA(0, 1, At, B1); PG8_BAR;
	s_add_u32 s50, s24, 0x40000
	s_addc_u32 s51, s25, 0
	s_add_i32 s49, s42, s34
	v_lshl_add_u64 v[128:129], s[50:51], 0, v[146:147]
	s_mov_b32 m0, s49
	s_nop 0
	global_load_lds_dwordx4 v[128:129], off
	v_lshl_add_u64 v[128:129], s[50:51], 0, v[150:151]
	s_add_i32 m0, s49, 0x2000
	s_nop 0
	global_load_lds_dwordx4 v[128:129], off
	s_waitcnt vmcnt(6)
	s_barrier
	s_setprio 1
	v_mfma_f32_16x16x32_bf16 v[52:55], v[202:205], v[160:163], 0
	v_mfma_f32_16x16x32_bf16 v[48:51], v[210:213], v[160:163], 0
	v_mfma_f32_16x16x32_bf16 v[36:39], v[202:205], v[168:171], 0
	v_mfma_f32_16x16x32_bf16 v[32:35], v[210:213], v[168:171], 0
	v_mfma_f32_16x16x32_bf16 v[20:23], v[202:205], v[186:189], 0
	v_mfma_f32_16x16x32_bf16 v[16:19], v[210:213], v[186:189], 0
	v_mfma_f32_16x16x32_bf16 v[4:7], v[202:205], v[194:197], 0
	v_mfma_f32_16x16x32_bf16 v[0:3], v[210:213], v[194:197], 0
	v_mfma_f32_16x16x32_bf16 v[52:55], v[206:209], v[164:167], v[52:55]
	v_mfma_f32_16x16x32_bf16 v[48:51], v[214:217], v[164:167], v[48:51]
	v_mfma_f32_16x16x32_bf16 v[36:39], v[206:209], v[182:185], v[36:39]
	v_mfma_f32_16x16x32_bf16 v[32:35], v[214:217], v[182:185], v[32:35]
	v_mfma_f32_16x16x32_bf16 v[20:23], v[206:209], v[190:193], v[20:23]
	v_mfma_f32_16x16x32_bf16 v[16:19], v[214:217], v[190:193], v[16:19]
	v_mfma_f32_16x16x32_bf16 v[4:7], v[206:209], v[198:201], v[4:7]
	v_mfma_f32_16x16x32_bf16 v[0:3], v[214:217], v[198:201], v[0:3]
	s_setprio 0
	s_add_i32 s49, 0, 0x18000
	v_add_u32_e32 v140, s49, v173
	s_barrier
	ds_read_b128 v[128:131], v140
	ds_read_b128 v[132:135], v140 offset:1024
	ds_read_b128 v[136:139], v140 offset:2048
	ds_read_b128 v[140:143], v140 offset:3072
	s_add_u32 s26, s26, 0x40000
	s_addc_u32 s27, s27, 0
	s_mov_b32 m0, s37
	v_lshl_add_u64 v[202:203], s[26:27], 0, v[144:145]
	ds_read_b128 v[160:163], v180 offset:32768
	ds_read_b128 v[164:167], v180 offset:33792
	ds_read_b128 v[168:171], v180 offset:34816
	ds_read_b128 v[182:185], v180 offset:35840
	ds_read_b128 v[186:189], v180 offset:36864
	ds_read_b128 v[190:193], v180 offset:37888
	ds_read_b128 v[194:197], v180 offset:38912
	ds_read_b128 v[198:201], v180 offset:39936
	global_load_lds_dwordx4 v[202:203], off
	v_lshl_add_u64 v[202:203], s[26:27], 0, v[148:149]
	s_mov_b32 m0, s38
	s_nop 0
	global_load_lds_dwordx4 v[202:203], off
	s_waitcnt lgkmcnt(8)
	s_barrier
	s_waitcnt lgkmcnt(0)
	s_setprio 1
	s_waitcnt lgkmcnt(0)
	v_mfma_f32_16x16x32_bf16 v[124:127], v[128:131], v[160:163], v[124:127]
	v_mfma_f32_16x16x32_bf16 v[120:123], v[136:139], v[160:163], v[120:123]
	v_mfma_f32_16x16x32_bf16 v[116:119], v[128:131], v[168:171], v[116:119]
	v_mfma_f32_16x16x32_bf16 v[104:107], v[136:139], v[168:171], v[104:107]
	v_mfma_f32_16x16x32_bf16 v[92:95], v[128:131], v[186:189], v[92:95]
	v_mfma_f32_16x16x32_bf16 v[88:91], v[136:139], v[186:189], v[88:91]
	v_mfma_f32_16x16x32_bf16 v[76:79], v[128:131], v[194:197], v[76:79]
	v_mfma_f32_16x16x32_bf16 v[72:75], v[136:139], v[194:197], v[72:75]
	v_mfma_f32_16x16x32_bf16 v[124:127], v[132:135], v[164:167], v[124:127]
	v_mfma_f32_16x16x32_bf16 v[120:123], v[140:143], v[164:167], v[120:123]
	v_mfma_f32_16x16x32_bf16 v[116:119], v[132:135], v[182:185], v[116:119]
	v_mfma_f32_16x16x32_bf16 v[104:107], v[140:143], v[182:185], v[104:107]
	v_mfma_f32_16x16x32_bf16 v[92:95], v[132:135], v[190:193], v[92:95]
	v_mfma_f32_16x16x32_bf16 v[88:91], v[140:143], v[190:193], v[88:91]
	v_mfma_f32_16x16x32_bf16 v[76:79], v[132:135], v[198:201], v[76:79]
	v_mfma_f32_16x16x32_bf16 v[72:75], v[140:143], v[198:201], v[72:75]
	s_setprio 0
	s_barrier
	s_add_i32 s26, 0, 0x1c000
	s_add_i32 s27, s49, s34
	v_add_u32_e32 v214, s26, v173
	v_lshl_add_u64 v[218:219], v[218:219], 0, s[10:11]
	s_mov_b32 m0, s27
	ds_read_b128 v[202:205], v214
	ds_read_b128 v[206:209], v214 offset:1024
	ds_read_b128 v[210:213], v214 offset:2048
	ds_read_b128 v[214:217], v214 offset:3072
	global_load_lds_dwordx4 v[218:219], off
	v_lshl_add_u64 v[218:219], v[220:221], 0, s[10:11]
	s_add_i32 m0, s27, 0x2000
	s_nop 0
	global_load_lds_dwordx4 v[218:219], off
	s_barrier
; #define PG8_STAGE(bufoff, gbase, voff) do { _Pragma("unroll") for (int _i = 0; _i < 2; ++_i) \
;         __builtin_amdgcn_global_load_lds((const unsigned*)((const char*)(gbase) + (voff)[_i]), (LAS unsigned*)(lds + (bufoff) + ldsw + _i * 8192), 16, 0, 0); } while (0)
; #define PG8_LDA(dst, b, h) do { _Pragma("unroll") for (int m = 0; m < 4; ++m) _Pragma("unroll") for (int k = 0; k < 2; ++k) dst[m][k] = *(const LAS bf16x8*)(lds + PG8_SA(b, h) + aoff + m * 2048 + k * 1024); } while (0)
; #define PG8_MMA(ai, bj, At, Bt) do { __builtin_amdgcn_s_setprio(1); _Pragma("unroll") for (int m = 0; m < 4; ++m) _Pragma("unroll") for (int n = 0; n < 2; ++n) _Pragma("unroll") for (int k = 0; k < 2; ++k) \
;         acc[ai][bj][m][n] = __builtin_amdgcn_mfma_f32_16x16x32_bf16(Bt[n][k], At[m][k], acc[ai][bj][m][n], 0, 0, 0); __builtin_amdgcn_s_setprio(0); } while (0)
; #define PG8_WAIT_V(n) asm volatile("s_waitcnt vmcnt(" #n ")" ::: "memory")
; #define PG8_WAIT_L(n) asm volatile("s_waitcnt lgkmcnt(" #n ")" ::: "memory")
; #define PG8_BAR __builtin_amdgcn_s_barrier()
; #define PG8_SCHED __builtin_amdgcn_sched_barrier(0)
; template <class Epi, class Sched>
; __device__ __forceinline__ void gemm_phase(const int wv, LAS unsigned char* lds, const Gemm g, const Sched& S, const Epi& E) {
;     ...
;             PG8_BAR; PG8_WAIT_L(0); PG8_MMA(0, 1, At, B1); PG8_BAR;
;             PG8_LDA(At, 1, 1); PG8_STAGE(PG8_SA(1, 0), a3, voffA);
;             PG8_BAR; PG8_WAIT_L(0); PG8_MMA(1, 0, At, B0); PG8_BAR; PG8_SCHED;
;             PG8_STAGE(PG8_SB(1, 1), b3 + hstepB, voffB);
;             PG8_WAIT_V(6); PG8_BAR; PG8_MMA(1, 1, At, B1); PG8_BAR;
;         }
	s_waitcnt lgkmcnt(0)
	s_setprio 1
	s_waitcnt lgkmcnt(0)
	v_mfma_f32_16x16x32_bf16 v[112:115], v[202:205], v[160:163], v[112:115]
	v_mfma_f32_16x16x32_bf16 v[108:111], v[210:213], v[160:163], v[108:111]
	v_mfma_f32_16x16x32_bf16 v[100:103], v[202:205], v[168:171], v[100:103]
	v_mfma_f32_16x16x32_bf16 v[96:99], v[210:213], v[168:171], v[96:99]
	v_mfma_f32_16x16x32_bf16 v[84:87], v[202:205], v[186:189], v[84:87]
	v_mfma_f32_16x16x32_bf16 v[80:83], v[210:213], v[186:189], v[80:83]
	v_mfma_f32_16x16x32_bf16 v[68:71], v[202:205], v[194:197], v[68:71]
	v_mfma_f32_16x16x32_bf16 v[64:67], v[210:213], v[194:197], v[64:67]
	v_mfma_f32_16x16x32_bf16 v[112:115], v[206:209], v[164:167], v[112:115]
	v_mfma_f32_16x16x32_bf16 v[108:111], v[214:217], v[164:167], v[108:111]
	v_mfma_f32_16x16x32_bf16 v[100:103], v[206:209], v[182:185], v[100:103]
	v_mfma_f32_16x16x32_bf16 v[96:99], v[214:217], v[182:185], v[96:99]
	v_mfma_f32_16x16x32_bf16 v[84:87], v[206:209], v[190:193], v[84:87]
	v_mfma_f32_16x16x32_bf16 v[80:83], v[214:217], v[190:193], v[80:83]
	v_mfma_f32_16x16x32_bf16 v[68:71], v[206:209], v[198:201], v[68:71]
	v_mfma_f32_16x16x32_bf16 v[64:67], v[214:217], v[198:201], v[64:67]
	s_setprio 0
	s_mov_b32 m0, s39
	v_lshl_add_u64 v[218:219], v[222:223], 0, s[10:11]
	s_barrier
	ds_read_b128 v[160:163], v180 offset:49152
	ds_read_b128 v[164:167], v180 offset:50176
	ds_read_b128 v[168:171], v180 offset:51200
	ds_read_b128 v[182:185], v180 offset:52224
	ds_read_b128 v[186:189], v180 offset:53248
	ds_read_b128 v[190:193], v180 offset:54272
	ds_read_b128 v[194:197], v180 offset:55296
	ds_read_b128 v[198:201], v180 offset:56320
	global_load_lds_dwordx4 v[218:219], off
	v_lshl_add_u64 v[218:219], v[224:225], 0, s[10:11]
	s_mov_b32 m0, s40
	s_nop 0
	global_load_lds_dwordx4 v[218:219], off
	s_barrier
	s_waitcnt lgkmcnt(0)
	s_setprio 1
	s_waitcnt lgkmcnt(0)
	v_mfma_f32_16x16x32_bf16 v[60:63], v[128:131], v[160:163], v[60:63]
	v_mfma_f32_16x16x32_bf16 v[56:59], v[136:139], v[160:163], v[56:59]
	v_mfma_f32_16x16x32_bf16 v[44:47], v[128:131], v[168:171], v[44:47]
	v_mfma_f32_16x16x32_bf16 v[40:43], v[136:139], v[168:171], v[40:43]
	v_mfma_f32_16x16x32_bf16 v[28:31], v[128:131], v[186:189], v[28:31]
	v_mfma_f32_16x16x32_bf16 v[24:27], v[136:139], v[186:189], v[24:27]
	v_mfma_f32_16x16x32_bf16 v[12:15], v[128:131], v[194:197], v[12:15]
	v_mfma_f32_16x16x32_bf16 v[8:11], v[136:139], v[194:197], v[8:11]
	v_mfma_f32_16x16x32_bf16 v[60:63], v[132:135], v[164:167], v[60:63]
	v_mfma_f32_16x16x32_bf16 v[56:59], v[140:143], v[164:167], v[56:59]
	v_mfma_f32_16x16x32_bf16 v[44:47], v[132:135], v[182:185], v[44:47]
	v_mfma_f32_16x16x32_bf16 v[40:43], v[140:143], v[182:185], v[40:43]
	v_mfma_f32_16x16x32_bf16 v[28:31], v[132:135], v[190:193], v[28:31]
	v_mfma_f32_16x16x32_bf16 v[24:27], v[140:143], v[190:193], v[24:27]
	v_mfma_f32_16x16x32_bf16 v[12:15], v[132:135], v[198:201], v[12:15]
	v_mfma_f32_16x16x32_bf16 v[8:11], v[140:143], v[198:201], v[8:11]
	s_setprio 0
	s_barrier
	s_add_u32 s24, s24, 0x40080
	s_addc_u32 s25, s25, 0
	s_add_i32 s26, s26, s34
	v_lshl_add_u64 v[128:129], s[24:25], 0, v[146:147]
	s_mov_b32 m0, s26
	s_nop 0
	global_load_lds_dwordx4 v[128:129], off
	v_lshl_add_u64 v[128:129], s[24:25], 0, v[150:151]
	s_add_i32 m0, s26, 0x2000
	s_nop 0
	global_load_lds_dwordx4 v[128:129], off
	s_waitcnt vmcnt(6)
	s_barrier
	s_setprio 1
	v_mfma_f32_16x16x32_bf16 v[52:55], v[202:205], v[160:163], v[52:55]
	v_mfma_f32_16x16x32_bf16 v[48:51], v[210:213], v[160:163], v[48:51]
	v_mfma_f32_16x16x32_bf16 v[36:39], v[202:205], v[168:171], v[36:39]
	v_mfma_f32_16x16x32_bf16 v[32:35], v[210:213], v[168:171], v[32:35]
	v_mfma_f32_16x16x32_bf16 v[20:23], v[202:205], v[186:189], v[20:23]
	v_mfma_f32_16x16x32_bf16 v[16:19], v[210:213], v[186:189], v[16:19]
	v_mfma_f32_16x16x32_bf16 v[4:7], v[202:205], v[194:197], v[4:7]
	v_mfma_f32_16x16x32_bf16 v[0:3], v[210:213], v[194:197], v[0:3]
	v_mfma_f32_16x16x32_bf16 v[52:55], v[206:209], v[164:167], v[52:55]
	v_mfma_f32_16x16x32_bf16 v[48:51], v[214:217], v[164:167], v[48:51]
	v_mfma_f32_16x16x32_bf16 v[36:39], v[206:209], v[182:185], v[36:39]
	v_mfma_f32_16x16x32_bf16 v[32:35], v[214:217], v[182:185], v[32:35]
	v_mfma_f32_16x16x32_bf16 v[20:23], v[206:209], v[190:193], v[20:23]
	v_mfma_f32_16x16x32_bf16 v[16:19], v[214:217], v[190:193], v[16:19]
	v_mfma_f32_16x16x32_bf16 v[4:7], v[206:209], v[198:201], v[4:7]
	v_mfma_f32_16x16x32_bf16 v[0:3], v[214:217], v[198:201], v[0:3]
	s_setprio 0
	s_add_i32 s48, s48, 2
	s_add_u32 s22, s22, 0x100
	s_addc_u32 s23, s23, 0
	s_add_u32 s46, s46, 0x100
	s_addc_u32 s47, s47, 0
	s_cmp_gt_u32 s48, 13
	s_barrier
	s_cbranch_scc0 .LBB0_661
	s_branch .Lpeel_exit_t661

; __device__ __forceinline__ float shx(float v, int lane, int mask) { return __int_as_float(__builtin_amdgcn_ds_bpermute((lane ^ mask) << 2, __float_as_int(v))); }
; __device__ __forceinline__ unsigned cvt_pk_bf16(float lo, float hi) { unsigned r; asm volatile("v_cvt_pk_bf16_f32 %0, %1, %2" : "=v"(r) : "v"(lo), "v"(hi)); return r; }
;     __device__ __forceinline__ void operator()(const f32x4 (&acc)[2][2][4][2], const Unit& u, int wr, int wc, int fr, int fq) const {
;         const int row0 = u.pm * 256 + wr * 64 + fr; const int col0 = u.pn * 256 + wc * 32 + 8 * fq;
; #pragma unroll
;         for (int ai = 0; ai < 2; ++ai) {
;             f32x4 xv[4][2][2];
; #pragma unroll
;             for (int m = 0; m < 4; ++m)
; #pragma unroll
;                 for (int bj = 0; bj < 2; ++bj) {
;                     const size_t o = (size_t)(row0 + ai * 128 + m * 16) * 1024 + col0 + bj * 128;
;                     xv[m][bj][0] = *(const f32x4*)(x + o); xv[m][bj][1] = *(const f32x4*)(x + o + 4);
;                 }
; #pragma unroll
;             for (int m = 0; m < 4; ++m) {
;                 const int row = row0 + ai * 128 + m * 16; float ss = 0.f;
; #pragma unroll
;                 for (int bj = 0; bj < 2; ++bj) {
;                     const size_t o = (size_t)row * 1024 + col0 + bj * 128;
;                     const f32x4 v0 = xv[m][bj][0] + acc[ai][bj][m][0], v1 = xv[m][bj][1] + acc[ai][bj][m][1];
;                     ss += (v0[0] * v0[0] + v0[1] * v0[1]) + (v0[2] * v0[2] + v0[3] * v0[3]) + (v1[0] * v1[0] + v1[1] * v1[1]) + (v1[2] * v1[2] + v1[3] * v1[3]);
;                     u32x4 w; w.x = cvt_pk_bf16(v0[0], v0[1]); w.y = cvt_pk_bf16(v0[2], v0[3]); w.z = cvt_pk_bf16(v1[0], v1[1]); w.w = cvt_pk_bf16(v1[2], v1[3]);
;                     *(u32x4*)(x1b + o) = w;
;                 }
;                 ss += shx(ss, fq * 16 + fr, 16); ss += shx(ss, fq * 16 + fr, 32);
;                 ss2[(size_t)row * 16 + u.pn * 4 + wc] = ss;
;             }
.Lpeel_exit_t661:
	v_lshl_add_u32 v162, s20, 8, v172
	v_lshl_or_b32 v128, s21, 8, v174
	v_ashrrev_i32_e32 v129, 31, v128
	v_ashrrev_i32_e32 v163, 31, v162
	v_lshl_add_u64 v[164:165], v[128:129], 2, s[2:3]
	v_lshlrev_b64 v[130:131], 12, v[162:163]
	v_lshl_add_u64 v[130:131], v[164:165], 0, v[130:131]
	global_load_dwordx4 v[182:185], v[130:131], off
	global_load_dwordx4 v[186:189], v[130:131], off offset:16
	global_load_dwordx4 v[190:193], v[130:131], off offset:512
	global_load_dwordx4 v[194:197], v[130:131], off offset:528
	v_or_b32_e32 v170, 16, v162
	v_ashrrev_i32_e32 v171, 31, v170
	v_lshlrev_b64 v[130:131], 12, v[170:171]
	v_lshl_add_u64 v[130:131], v[164:165], 0, v[130:131]
	global_load_dwordx4 v[198:201], v[130:131], off
	global_load_dwordx4 v[202:205], v[130:131], off offset:16
	global_load_dwordx4 v[206:209], v[130:131], off offset:528
	global_load_dwordx4 v[210:213], v[130:131], off offset:512
	v_or_b32_e32 v168, 32, v162
	v_or_b32_e32 v166, 48, v162
	s_lshl_b32 s20, s21, 2
	v_ashrrev_i32_e32 v169, 31, v168
	v_ashrrev_i32_e32 v167, 31, v166
	s_ashr_i32 s21, s20, 31
	v_lshlrev_b64 v[132:133], 11, v[162:163]
	v_lshlrev_b64 v[160:161], 1, v[128:129]
	v_lshlrev_b64 v[128:129], 6, v[162:163]
	v_lshlrev_b64 v[134:135], 12, v[168:169]
	v_lshlrev_b64 v[136:137], 12, v[166:167]
	s_lshl_b64 s[20:21], s[20:21], 2
	v_lshl_add_u64 v[132:133], s[6:7], 0, v[132:133]
	v_lshl_add_u64 v[128:129], s[8:9], 0, v[128:129]
	v_lshl_add_u64 v[130:131], v[164:165], 0, v[134:135]
	v_lshl_add_u64 v[134:135], v[164:165], 0, v[136:137]
	v_lshl_add_u64 v[232:233], v[132:133], 0, v[160:161]
	v_lshl_add_u64 v[234:235], v[128:129], 0, s[20:21]
	global_load_dwordx4 v[214:217], v[130:131], off offset:16
	global_load_dwordx4 v[218:221], v[130:131], off
	global_load_dwordx4 v[222:225], v[130:131], off offset:528
	global_load_dwordx4 v[226:229], v[130:131], off offset:512
	global_load_dwordx4 v[136:139], v[134:135], off offset:16
	global_load_dwordx4 v[140:143], v[134:135], off
	s_nop 0
	global_load_dwordx4 v[128:131], v[134:135], off offset:528
	s_nop 0
	global_load_dwordx4 v[132:135], v[134:135], off offset:512
	v_lshl_add_u64 v[234:235], v[234:235], 0, s[4:5]
	v_lshlrev_b64 v[230:231], 11, v[170:171]
	s_and_b64 vcc, exec, s[0:1]
	s_mov_b64 s[24:25], s[18:19]
	s_mov_b64 s[22:23], s[16:17]
	s_waitcnt vmcnt(0)
	v_pk_add_f32 v[126:127], v[126:127], v[184:185]
	v_pk_add_f32 v[124:125], v[124:125], v[182:183]
	v_pk_add_f32 v[122:123], v[122:123], v[188:189]
	v_pk_add_f32 v[120:121], v[120:121], v[186:187]
	v_pk_add_f32 v[114:115], v[114:115], v[192:193]
	v_pk_add_f32 v[112:113], v[112:113], v[190:191]
	v_pk_add_f32 v[182:183], v[110:111], v[196:197]
	v_pk_add_f32 v[184:185], v[108:109], v[194:195]
	v_mul_f32_e32 v163, v125, v125
	v_mul_f32_e32 v190, v127, v127
	v_mul_f32_e32 v191, v121, v121
	v_mul_f32_e32 v192, v123, v123
	v_cvt_pk_bf16_f32 v108, v124, v125
	v_cvt_pk_bf16_f32 v109, v126, v127
	v_cvt_pk_bf16_f32 v110, v120, v121
	v_cvt_pk_bf16_f32 v111, v122, v123
	v_mul_f32_e32 v121, v113, v113
	v_mul_f32_e32 v123, v115, v115
	v_mul_f32_e32 v125, v185, v185
	v_fmac_f32_e32 v163, v124, v124
	v_fmac_f32_e32 v190, v126, v126
	v_fmac_f32_e32 v121, v112, v112
	v_fmac_f32_e32 v123, v114, v114
	v_mul_f32_e32 v127, v183, v183
	v_fmac_f32_e32 v191, v120, v120
	global_store_dwordx4 v[232:233], v[108:111], off
	v_fmac_f32_e32 v125, v184, v184
	v_fmac_f32_e32 v192, v122, v122
	v_add_f32_e32 v108, v163, v190
	v_add_f32_e32 v109, v121, v123
	v_fmac_f32_e32 v127, v182, v182
	v_add_f32_e32 v108, v108, v191
	v_add_f32_e32 v109, v109, v125
	v_add_f32_e32 v108, v192, v108
	v_add_f32_e32 v109, v127, v109
	v_add_f32_e32 v108, v108, v109
	ds_bpermute_b32 v109, v175, v108
	v_pk_add_f32 v[188:189], v[104:105], v[202:203]
	v_cvt_pk_bf16_f32 v104, v112, v113
	v_pk_add_f32 v[186:187], v[106:107], v[204:205]
	v_cvt_pk_bf16_f32 v105, v114, v115
	v_cvt_pk_bf16_f32 v106, v184, v185
	v_cvt_pk_bf16_f32 v107, v182, v183
	global_store_dwordx4 v[232:233], v[104:107], off offset:256
	v_pk_add_f32 v[102:103], v[102:103], v[212:213]
	v_pk_add_f32 v[100:101], v[100:101], v[210:211]
	s_waitcnt lgkmcnt(0)
	v_add_f32_e32 v104, v108, v109
	ds_bpermute_b32 v105, v176, v104
	v_pk_add_f32 v[108:109], v[98:99], v[208:209]
	v_pk_add_f32 v[98:99], v[96:97], v[206:207]
	v_mul_f32_e32 v96, v101, v101
	v_mul_f32_e32 v97, v103, v103
	v_pk_add_f32 v[118:119], v[118:119], v[200:201]
	v_pk_add_f32 v[116:117], v[116:117], v[198:199]
	v_fmac_f32_e32 v96, v100, v100
	v_fmac_f32_e32 v97, v102, v102
	v_mul_f32_e32 v110, v117, v117
	v_mul_f32_e32 v111, v119, v119
	v_add_f32_e32 v96, v96, v97
	v_mul_f32_e32 v97, v99, v99
	v_mul_f32_e32 v112, v189, v189
	v_fmac_f32_e32 v110, v116, v116
	v_fmac_f32_e32 v111, v118, v118
	v_fmac_f32_e32 v97, v98, v98
	v_fmac_f32_e32 v112, v188, v188
	v_add_f32_e32 v106, v110, v111
	s_waitcnt lgkmcnt(0)
	v_add_f32_e32 v104, v104, v105
	v_mul_f32_e32 v105, v187, v187
	v_add_f32_e32 v96, v96, v97
	v_mul_f32_e32 v97, v109, v109
	global_store_dword v[234:235], v104, off
	v_add_f32_e32 v104, v106, v112
	v_fmac_f32_e32 v105, v186, v186
	v_fmac_f32_e32 v97, v108, v108
	v_add_f32_e32 v110, v105, v104
	v_add_f32_e32 v96, v97, v96
	v_add_f32_e32 v112, v110, v96
	ds_bpermute_b32 v113, v175, v112
	v_lshl_add_u64 v[96:97], s[6:7], 0, v[230:231]
	v_lshl_add_u64 v[110:111], v[96:97], 0, v[160:161]
	v_cvt_pk_bf16_f32 v104, v116, v117
	v_cvt_pk_bf16_f32 v105, v118, v119
	v_cvt_pk_bf16_f32 v106, v188, v189
	v_cvt_pk_bf16_f32 v107, v186, v187
	global_store_dwordx4 v[110:111], v[104:107], off
	v_cvt_pk_bf16_f32 v96, v100, v101
	s_waitcnt lgkmcnt(0)
; __device__ __forceinline__ float shx(float v, int lane, int mask) { return __int_as_float(__builtin_amdgcn_ds_bpermute((lane ^ mask) << 2, __float_as_int(v))); }
; __device__ __forceinline__ unsigned cvt_pk_bf16(float lo, float hi) { unsigned r; asm volatile("v_cvt_pk_bf16_f32 %0, %1, %2" : "=v"(r) : "v"(lo), "v"(hi)); return r; }
;     __device__ __forceinline__ void operator()(const f32x4 (&acc)[2][2][4][2], const Unit& u, int wr, int wc, int fr, int fq) const {
;     ...
;                     const size_t o = (size_t)(row0 + ai * 128 + m * 16) * 1024 + col0 + bj * 128;
;                     xv[m][bj][0] = *(const f32x4*)(x + o); xv[m][bj][1] = *(const f32x4*)(x + o + 4);
;                 }
; #pragma unroll
;             for (int m = 0; m < 4; ++m) {
;                 const int row = row0 + ai * 128 + m * 16; float ss = 0.f;
; #pragma unroll
;                 for (int bj = 0; bj < 2; ++bj) {
;                     const size_t o = (size_t)row * 1024 + col0 + bj * 128;
;                     const f32x4 v0 = xv[m][bj][0] + acc[ai][bj][m][0], v1 = xv[m][bj][1] + acc[ai][bj][m][1];
;                     ss += (v0[0] * v0[0] + v0[1] * v0[1]) + (v0[2] * v0[2] + v0[3] * v0[3]) + (v1[0] * v1[0] + v1[1] * v1[1]) + (v1[2] * v1[2] + v1[3] * v1[3]);
;                     u32x4 w; w.x = cvt_pk_bf16(v0[0], v0[1]); w.y = cvt_pk_bf16(v0[2], v0[3]); w.z = cvt_pk_bf16(v1[0], v1[1]); w.w = cvt_pk_bf16(v1[2], v1[3]);
;                     *(u32x4*)(x1b + o) = w;
;                 }
;                 ss += shx(ss, fq * 16 + fr, 16); ss += shx(ss, fq * 16 + fr, 32);
;                 ss2[(size_t)row * 16 + u.pn * 4 + wc] = ss;
;             }
	v_add_f32_e32 v100, v112, v113
	ds_bpermute_b32 v101, v176, v100
	v_cvt_pk_bf16_f32 v97, v102, v103
	v_cvt_pk_bf16_f32 v98, v98, v99
	v_cvt_pk_bf16_f32 v99, v108, v109
	global_store_dwordx4 v[110:111], v[96:99], off offset:256
	v_pk_add_f32 v[94:95], v[94:95], v[220:221]
	v_pk_add_f32 v[92:93], v[92:93], v[218:219]
	v_lshlrev_b64 v[96:97], 6, v[170:171]
	v_lshl_add_u64 v[96:97], s[8:9], 0, v[96:97]
	v_lshl_add_u64 v[96:97], v[96:97], 0, s[20:21]
	s_waitcnt lgkmcnt(0)
	v_add_f32_e32 v98, v100, v101
	v_lshl_add_u64 v[96:97], v[96:97], 0, s[4:5]
	global_store_dword v[96:97], v98, off
	v_pk_add_f32 v[98:99], v[90:91], v[216:217]
	v_pk_add_f32 v[90:91], v[88:89], v[214:215]
	v_mul_f32_e32 v88, v93, v93
	v_mul_f32_e32 v89, v95, v95
	v_fmac_f32_e32 v88, v92, v92
	v_fmac_f32_e32 v89, v94, v94
	v_add_f32_e32 v88, v88, v89
	v_mul_f32_e32 v89, v91, v91
	v_fmac_f32_e32 v89, v90, v90
	v_add_f32_e32 v88, v88, v89
	v_mul_f32_e32 v89, v99, v99
	v_fmac_f32_e32 v89, v98, v98
	v_pk_add_f32 v[86:87], v[86:87], v[228:229]
	v_pk_add_f32 v[84:85], v[84:85], v[226:227]
	v_add_f32_e32 v100, v89, v88
	v_cvt_pk_bf16_f32 v88, v92, v93
	v_pk_add_f32 v[92:93], v[82:83], v[224:225]
	v_pk_add_f32 v[82:83], v[80:81], v[222:223]
	v_mul_f32_e32 v80, v85, v85
	v_mul_f32_e32 v81, v87, v87
	v_fmac_f32_e32 v80, v84, v84
	v_fmac_f32_e32 v81, v86, v86
	v_add_f32_e32 v80, v80, v81
	v_mul_f32_e32 v81, v83, v83
	v_fmac_f32_e32 v81, v82, v82
	v_add_f32_e32 v80, v80, v81
	v_mul_f32_e32 v81, v93, v93
	v_fmac_f32_e32 v81, v92, v92
	v_add_f32_e32 v80, v81, v80
	v_cvt_pk_bf16_f32 v89, v94, v95
	v_cvt_pk_bf16_f32 v90, v90, v91
	v_cvt_pk_bf16_f32 v91, v98, v99
	v_add_f32_e32 v98, v100, v80
	ds_bpermute_b32 v99, v175, v98
	v_lshlrev_b64 v[96:97], 11, v[168:169]
	v_lshl_add_u64 v[80:81], s[6:7], 0, v[96:97]
	v_lshl_add_u64 v[94:95], v[80:81], 0, v[160:161]
	global_store_dwordx4 v[94:95], v[88:91], off
	v_cvt_pk_bf16_f32 v80, v84, v85
	s_waitcnt lgkmcnt(0)
	v_add_f32_e32 v84, v98, v99
	ds_bpermute_b32 v85, v176, v84
	v_cvt_pk_bf16_f32 v81, v86, v87
	v_cvt_pk_bf16_f32 v82, v82, v83
	v_cvt_pk_bf16_f32 v83, v92, v93
	global_store_dwordx4 v[94:95], v[80:83], off offset:256
	v_pk_add_f32 v[78:79], v[78:79], v[142:143]
	v_pk_add_f32 v[76:77], v[76:77], v[140:141]
	v_lshlrev_b64 v[80:81], 6, v[168:169]
	v_lshl_add_u64 v[80:81], s[8:9], 0, v[80:81]
	v_lshl_add_u64 v[80:81], v[80:81], 0, s[20:21]
	s_waitcnt lgkmcnt(0)
	v_add_f32_e32 v82, v84, v85
	v_lshl_add_u64 v[80:81], v[80:81], 0, s[4:5]
	global_store_dword v[80:81], v82, off
	v_pk_add_f32 v[82:83], v[74:75], v[138:139]
	v_pk_add_f32 v[74:75], v[72:73], v[136:137]
	v_mul_f32_e32 v72, v77, v77
	v_mul_f32_e32 v73, v79, v79
	v_fmac_f32_e32 v72, v76, v76
	v_fmac_f32_e32 v73, v78, v78
	v_add_f32_e32 v72, v72, v73
	v_mul_f32_e32 v73, v75, v75
	v_fmac_f32_e32 v73, v74, v74
	v_add_f32_e32 v72, v72, v73
	v_mul_f32_e32 v73, v83, v83
	v_fmac_f32_e32 v73, v82, v82
	v_pk_add_f32 v[70:71], v[70:71], v[134:135]
	v_pk_add_f32 v[68:69], v[68:69], v[132:133]
	v_add_f32_e32 v84, v73, v72
	v_cvt_pk_bf16_f32 v72, v76, v77
	v_pk_add_f32 v[76:77], v[66:67], v[130:131]
	v_pk_add_f32 v[66:67], v[64:65], v[128:129]
	v_mul_f32_e32 v64, v69, v69
	v_mul_f32_e32 v65, v71, v71
	v_fmac_f32_e32 v64, v68, v68
	v_fmac_f32_e32 v65, v70, v70
	v_add_f32_e32 v64, v64, v65
	v_mul_f32_e32 v65, v67, v67
	v_fmac_f32_e32 v65, v66, v66
	v_add_f32_e32 v64, v64, v65
	v_mul_f32_e32 v65, v77, v77
	v_fmac_f32_e32 v65, v76, v76
	v_add_f32_e32 v64, v65, v64
	v_cvt_pk_bf16_f32 v73, v78, v79
	v_cvt_pk_bf16_f32 v74, v74, v75
	v_cvt_pk_bf16_f32 v75, v82, v83
	v_add_f32_e32 v82, v84, v64
	ds_bpermute_b32 v83, v175, v82
	v_lshlrev_b64 v[80:81], 11, v[166:167]
	v_lshl_add_u64 v[64:65], s[6:7], 0, v[80:81]
	v_lshl_add_u64 v[78:79], v[64:65], 0, v[160:161]
	global_store_dwordx4 v[78:79], v[72:75], off
	v_cvt_pk_bf16_f32 v64, v68, v69
	s_waitcnt lgkmcnt(0)
	v_add_f32_e32 v68, v82, v83
	ds_bpermute_b32 v69, v176, v68
	v_cvt_pk_bf16_f32 v65, v70, v71
	v_cvt_pk_bf16_f32 v66, v66, v67
	v_cvt_pk_bf16_f32 v67, v76, v77
	global_store_dwordx4 v[78:79], v[64:67], off offset:256
	v_add_u32_e32 v132, 0x80, v162
	v_ashrrev_i32_e32 v133, 31, v132
	v_lshlrev_b64 v[64:65], 6, v[166:167]
	v_lshl_add_u64 v[64:65], s[8:9], 0, v[64:65]
	v_lshl_add_u64 v[64:65], v[64:65], 0, s[20:21]
	s_waitcnt lgkmcnt(0)
	v_add_f32_e32 v66, v68, v69
	v_lshl_add_u64 v[64:65], v[64:65], 0, s[4:5]
	global_store_dword v[64:65], v66, off
	v_lshlrev_b64 v[64:65], 12, v[132:133]
	v_lshl_add_u64 v[64:65], v[164:165], 0, v[64:65]
	global_load_dwordx4 v[92:95], v[64:65], off
	global_load_dwordx4 v[96:99], v[64:65], off offset:16
	global_load_dwordx4 v[100:103], v[64:65], off offset:512
	global_load_dwordx4 v[104:107], v[64:65], off offset:528
	v_add_u32_e32 v134, 0x90, v162
	v_ashrrev_i32_e32 v135, 31, v134
	v_lshlrev_b64 v[64:65], 12, v[134:135]
	v_lshl_add_u64 v[64:65], v[164:165], 0, v[64:65]
	global_load_dwordx4 v[108:111], v[64:65], off
	global_load_dwordx4 v[112:115], v[64:65], off offset:16
	global_load_dwordx4 v[116:119], v[64:65], off offset:528
	global_load_dwordx4 v[120:123], v[64:65], off offset:512
	v_add_u32_e32 v90, 0xa0, v162
	v_ashrrev_i32_e32 v91, 31, v90
	v_lshlrev_b64 v[64:65], 12, v[90:91]
	v_lshl_add_u64 v[64:65], v[164:165], 0, v[64:65]
	global_load_dwordx4 v[124:127], v[64:65], off offset:16
	global_load_dwordx4 v[128:131], v[64:65], off
	global_load_dwordx4 v[80:83], v[64:65], off offset:528
	global_load_dwordx4 v[84:87], v[64:65], off offset:512
	v_add_u32_e32 v88, 0xb0, v162
	v_ashrrev_i32_e32 v89, 31, v88
	v_lshlrev_b64 v[64:65], 12, v[88:89]
	v_lshl_add_u64 v[68:69], v[164:165], 0, v[64:65]
	global_load_dwordx4 v[72:75], v[68:69], off offset:16
	global_load_dwordx4 v[76:79], v[68:69], off
	global_load_dwordx4 v[64:67], v[68:69], off offset:528
	s_nop 0
	global_load_dwordx4 v[68:71], v[68:69], off offset:512
	v_lshlrev_b64 v[136:137], 11, v[132:133]
	s_waitcnt vmcnt(15)
; __device__ __forceinline__ float shx(float v, int lane, int mask) { return __int_as_float(__builtin_amdgcn_ds_bpermute((lane ^ mask) << 2, __float_as_int(v))); }
; __device__ __forceinline__ unsigned cvt_pk_bf16(float lo, float hi) { unsigned r; asm volatile("v_cvt_pk_bf16_f32 %0, %1, %2" : "=v"(r) : "v"(lo), "v"(hi)); return r; }
;     __device__ __forceinline__ void operator()(const f32x4 (&acc)[2][2][4][2], const Unit& u, int wr, int wc, int fr, int fq) const {
;     ...
;             for (int m = 0; m < 4; ++m) {
;                 const int row = row0 + ai * 128 + m * 16; float ss = 0.f;
; #pragma unroll
;                 for (int bj = 0; bj < 2; ++bj) {
;                     const size_t o = (size_t)row * 1024 + col0 + bj * 128;
;                     const f32x4 v0 = xv[m][bj][0] + acc[ai][bj][m][0], v1 = xv[m][bj][1] + acc[ai][bj][m][1];
;                     ss += (v0[0] * v0[0] + v0[1] * v0[1]) + (v0[2] * v0[2] + v0[3] * v0[3]) + (v1[0] * v1[0] + v1[1] * v1[1]) + (v1[2] * v1[2] + v1[3] * v1[3]);
;                     u32x4 w; w.x = cvt_pk_bf16(v0[0], v0[1]); w.y = cvt_pk_bf16(v0[2], v0[3]); w.z = cvt_pk_bf16(v1[0], v1[1]); w.w = cvt_pk_bf16(v1[2], v1[3]);
;                     *(u32x4*)(x1b + o) = w;
;                 }
;                 ss += shx(ss, fq * 16 + fr, 16); ss += shx(ss, fq * 16 + fr, 32);
;                 ss2[(size_t)row * 16 + u.pn * 4 + wc] = ss;
;             }
	v_pk_add_f32 v[62:63], v[62:63], v[94:95]
	v_pk_add_f32 v[60:61], v[60:61], v[92:93]
	s_waitcnt vmcnt(14)
	v_pk_add_f32 v[92:93], v[58:59], v[98:99]
	v_pk_add_f32 v[58:59], v[56:57], v[96:97]
	v_mul_f32_e32 v56, v61, v61
	v_mul_f32_e32 v57, v63, v63
	v_fmac_f32_e32 v56, v60, v60
	v_fmac_f32_e32 v57, v62, v62
	v_add_f32_e32 v56, v56, v57
	v_mul_f32_e32 v57, v59, v59
	v_fmac_f32_e32 v57, v58, v58
	v_add_f32_e32 v56, v56, v57
	v_mul_f32_e32 v57, v93, v93
	v_fmac_f32_e32 v57, v92, v92
	s_waitcnt vmcnt(13)
	v_pk_add_f32 v[54:55], v[54:55], v[102:103]
	v_pk_add_f32 v[52:53], v[52:53], v[100:101]
	v_add_f32_e32 v94, v57, v56
	v_cvt_pk_bf16_f32 v56, v60, v61
	s_waitcnt vmcnt(12)
	v_pk_add_f32 v[60:61], v[50:51], v[106:107]
	v_pk_add_f32 v[50:51], v[48:49], v[104:105]
	v_mul_f32_e32 v48, v53, v53
	v_mul_f32_e32 v49, v55, v55
	v_fmac_f32_e32 v48, v52, v52
	v_fmac_f32_e32 v49, v54, v54
	v_add_f32_e32 v48, v48, v49
	v_mul_f32_e32 v49, v51, v51
	v_fmac_f32_e32 v49, v50, v50
	v_add_f32_e32 v48, v48, v49
	v_mul_f32_e32 v49, v61, v61
	v_fmac_f32_e32 v49, v60, v60
	v_add_f32_e32 v48, v49, v48
	v_cvt_pk_bf16_f32 v57, v62, v63
	v_cvt_pk_bf16_f32 v58, v58, v59
	v_cvt_pk_bf16_f32 v59, v92, v93
	v_add_f32_e32 v92, v94, v48
	ds_bpermute_b32 v93, v175, v92
	v_lshl_add_u64 v[48:49], s[6:7], 0, v[136:137]
	v_lshl_add_u64 v[62:63], v[48:49], 0, v[160:161]
	global_store_dwordx4 v[62:63], v[56:59], off
	v_cvt_pk_bf16_f32 v48, v52, v53
	s_waitcnt lgkmcnt(0)
	v_add_f32_e32 v52, v92, v93
	ds_bpermute_b32 v53, v176, v52
	v_cvt_pk_bf16_f32 v49, v54, v55
	v_cvt_pk_bf16_f32 v50, v50, v51
	v_cvt_pk_bf16_f32 v51, v60, v61
	global_store_dwordx4 v[62:63], v[48:51], off offset:256
	s_waitcnt vmcnt(13)
	v_pk_add_f32 v[46:47], v[46:47], v[110:111]
	v_pk_add_f32 v[44:45], v[44:45], v[108:109]
	v_lshlrev_b64 v[48:49], 6, v[132:133]
	v_lshl_add_u64 v[48:49], s[8:9], 0, v[48:49]
	v_lshl_add_u64 v[48:49], v[48:49], 0, s[20:21]
	s_waitcnt lgkmcnt(0)
	v_add_f32_e32 v50, v52, v53
	v_lshl_add_u64 v[48:49], v[48:49], 0, s[4:5]
	global_store_dword v[48:49], v50, off
	s_waitcnt vmcnt(13)
	v_pk_add_f32 v[50:51], v[42:43], v[114:115]
	v_pk_add_f32 v[42:43], v[40:41], v[112:113]
	v_mul_f32_e32 v40, v45, v45
	v_mul_f32_e32 v41, v47, v47
	v_fmac_f32_e32 v40, v44, v44
	v_fmac_f32_e32 v41, v46, v46
	v_add_f32_e32 v40, v40, v41
	v_mul_f32_e32 v41, v43, v43
	v_fmac_f32_e32 v41, v42, v42
	v_add_f32_e32 v40, v40, v41
	v_mul_f32_e32 v41, v51, v51
	v_fmac_f32_e32 v41, v50, v50
	s_waitcnt vmcnt(11)
	v_pk_add_f32 v[38:39], v[38:39], v[122:123]
	v_pk_add_f32 v[36:37], v[36:37], v[120:121]
	v_add_f32_e32 v52, v41, v40
	v_cvt_pk_bf16_f32 v40, v44, v45
	v_pk_add_f32 v[44:45], v[34:35], v[118:119]
	v_pk_add_f32 v[34:35], v[32:33], v[116:117]
	v_mul_f32_e32 v32, v37, v37
	v_mul_f32_e32 v33, v39, v39
	v_fmac_f32_e32 v32, v36, v36
	v_fmac_f32_e32 v33, v38, v38
	v_add_f32_e32 v32, v32, v33
	v_mul_f32_e32 v33, v35, v35
	v_fmac_f32_e32 v33, v34, v34
	v_add_f32_e32 v32, v32, v33
	v_mul_f32_e32 v33, v45, v45
	v_fmac_f32_e32 v33, v44, v44
	v_add_f32_e32 v32, v33, v32
	v_cvt_pk_bf16_f32 v41, v46, v47
	v_cvt_pk_bf16_f32 v42, v42, v43
	v_cvt_pk_bf16_f32 v43, v50, v51
	v_add_f32_e32 v50, v52, v32
	ds_bpermute_b32 v51, v175, v50
	v_lshlrev_b64 v[48:49], 11, v[134:135]
	v_lshl_add_u64 v[32:33], s[6:7], 0, v[48:49]
	v_lshl_add_u64 v[46:47], v[32:33], 0, v[160:161]
	global_store_dwordx4 v[46:47], v[40:43], off
	v_cvt_pk_bf16_f32 v32, v36, v37
	s_waitcnt lgkmcnt(0)
	v_add_f32_e32 v36, v50, v51
	ds_bpermute_b32 v37, v176, v36
	v_cvt_pk_bf16_f32 v33, v38, v39
	v_cvt_pk_bf16_f32 v34, v34, v35
	v_cvt_pk_bf16_f32 v35, v44, v45
	global_store_dwordx4 v[46:47], v[32:35], off offset:256
	s_waitcnt vmcnt(11)
	v_pk_add_f32 v[30:31], v[30:31], v[130:131]
	v_pk_add_f32 v[28:29], v[28:29], v[128:129]
	v_lshlrev_b64 v[32:33], 6, v[134:135]
	v_lshl_add_u64 v[32:33], s[8:9], 0, v[32:33]
	v_lshl_add_u64 v[32:33], v[32:33], 0, s[20:21]
	s_waitcnt lgkmcnt(0)
; __device__ __forceinline__ float shx(float v, int lane, int mask) { return __int_as_float(__builtin_amdgcn_ds_bpermute((lane ^ mask) << 2, __float_as_int(v))); }
; __device__ __forceinline__ unsigned cvt_pk_bf16(float lo, float hi) { unsigned r; asm volatile("v_cvt_pk_bf16_f32 %0, %1, %2" : "=v"(r) : "v"(lo), "v"(hi)); return r; }
; #define PG8_WAIT_V(n) asm volatile("s_waitcnt vmcnt(" #n ")" ::: "memory")
; #define PG8_BAR __builtin_amdgcn_s_barrier()
; template <class Epi, class Sched>
; __device__ __forceinline__ void gemm_phase(const int wv, LAS unsigned char* lds, const Gemm g, const Sched& S, const Epi& E) {
;     ...
;         E(acc, cur, wr, wc, fr, fq); S.done(cur);
;         if (!has_next) break;
; #pragma unroll
;         for (int a = 0; a < 2; ++a)
; #pragma unroll
;             for (int b = 0; b < 2; ++b)
; #pragma unroll
;                 for (int m = 0; m < 4; ++m)
; #pragma unroll
;                     for (int n = 0; n < 2; ++n) acc[a][b][m][n] = (f32x4){0.f, 0.f, 0.f, 0.f};
;         cur = nxt; cA = nA; cB = nB; ++ui;
;     }
;     PG8_WAIT_V(0);
;     if (wr == 0) PG8_BAR;
;     PG8_BAR;
;     __device__ __forceinline__ void operator()(const f32x4 (&acc)[2][2][4][2], const Unit& u, int wr, int wc, int fr, int fq) const {
;     ...
;             for (int m = 0; m < 4; ++m) {
;                 const int row = row0 + ai * 128 + m * 16; float ss = 0.f;
; #pragma unroll
;                 for (int bj = 0; bj < 2; ++bj) {
;                     const size_t o = (size_t)row * 1024 + col0 + bj * 128;
;                     const f32x4 v0 = xv[m][bj][0] + acc[ai][bj][m][0], v1 = xv[m][bj][1] + acc[ai][bj][m][1];
;                     ss += (v0[0] * v0[0] + v0[1] * v0[1]) + (v0[2] * v0[2] + v0[3] * v0[3]) + (v1[0] * v1[0] + v1[1] * v1[1]) + (v1[2] * v1[2] + v1[3] * v1[3]);
;                     u32x4 w; w.x = cvt_pk_bf16(v0[0], v0[1]); w.y = cvt_pk_bf16(v0[2], v0[3]); w.z = cvt_pk_bf16(v1[0], v1[1]); w.w = cvt_pk_bf16(v1[2], v1[3]);
;                     *(u32x4*)(x1b + o) = w;
;                 }
;                 ss += shx(ss, fq * 16 + fr, 16); ss += shx(ss, fq * 16 + fr, 32);
;                 ss2[(size_t)row * 16 + u.pn * 4 + wc] = ss;
;             }
	v_add_f32_e32 v34, v36, v37
	v_lshl_add_u64 v[32:33], v[32:33], 0, s[4:5]
	global_store_dword v[32:33], v34, off
	v_pk_add_f32 v[34:35], v[26:27], v[126:127]
	v_pk_add_f32 v[26:27], v[24:25], v[124:125]
	v_mul_f32_e32 v24, v29, v29
	v_mul_f32_e32 v25, v31, v31
	v_fmac_f32_e32 v24, v28, v28
	v_fmac_f32_e32 v25, v30, v30
	v_add_f32_e32 v24, v24, v25
	v_mul_f32_e32 v25, v27, v27
	v_fmac_f32_e32 v25, v26, v26
	v_add_f32_e32 v24, v24, v25
	v_mul_f32_e32 v25, v35, v35
	v_fmac_f32_e32 v25, v34, v34
	s_waitcnt vmcnt(10)
	v_pk_add_f32 v[22:23], v[22:23], v[86:87]
	v_pk_add_f32 v[20:21], v[20:21], v[84:85]
	v_add_f32_e32 v36, v25, v24
	v_cvt_pk_bf16_f32 v24, v28, v29
	v_pk_add_f32 v[28:29], v[18:19], v[82:83]
	v_pk_add_f32 v[18:19], v[16:17], v[80:81]
	v_mul_f32_e32 v16, v21, v21
	v_mul_f32_e32 v17, v23, v23
	v_fmac_f32_e32 v16, v20, v20
	v_fmac_f32_e32 v17, v22, v22
	v_add_f32_e32 v16, v16, v17
	v_mul_f32_e32 v17, v19, v19
	v_fmac_f32_e32 v17, v18, v18
	v_add_f32_e32 v16, v16, v17
	v_mul_f32_e32 v17, v29, v29
	v_fmac_f32_e32 v17, v28, v28
	v_add_f32_e32 v16, v17, v16
	v_cvt_pk_bf16_f32 v25, v30, v31
	v_cvt_pk_bf16_f32 v26, v26, v27
	v_cvt_pk_bf16_f32 v27, v34, v35
	v_add_f32_e32 v34, v36, v16
	ds_bpermute_b32 v35, v175, v34
	v_lshlrev_b64 v[32:33], 11, v[90:91]
	v_lshl_add_u64 v[16:17], s[6:7], 0, v[32:33]
	v_lshl_add_u64 v[30:31], v[16:17], 0, v[160:161]
	global_store_dwordx4 v[30:31], v[24:27], off
	v_cvt_pk_bf16_f32 v16, v20, v21
	s_waitcnt lgkmcnt(0)
	v_add_f32_e32 v20, v34, v35
	ds_bpermute_b32 v21, v176, v20
	v_cvt_pk_bf16_f32 v17, v22, v23
	v_cvt_pk_bf16_f32 v18, v18, v19
	v_cvt_pk_bf16_f32 v19, v28, v29
	global_store_dwordx4 v[30:31], v[16:19], off offset:256
	s_waitcnt vmcnt(10)
	v_pk_add_f32 v[14:15], v[14:15], v[78:79]
	v_pk_add_f32 v[12:13], v[12:13], v[76:77]
	v_lshlrev_b64 v[16:17], 6, v[90:91]
	v_lshl_add_u64 v[16:17], s[8:9], 0, v[16:17]
	v_lshl_add_u64 v[16:17], v[16:17], 0, s[20:21]
	s_waitcnt lgkmcnt(0)
	v_add_f32_e32 v18, v20, v21
	v_lshl_add_u64 v[16:17], v[16:17], 0, s[4:5]
	global_store_dword v[16:17], v18, off
	v_pk_add_f32 v[18:19], v[10:11], v[74:75]
	v_pk_add_f32 v[10:11], v[8:9], v[72:73]
	v_mul_f32_e32 v8, v13, v13
	v_mul_f32_e32 v9, v15, v15
	v_fmac_f32_e32 v8, v12, v12
	v_fmac_f32_e32 v9, v14, v14
	v_add_f32_e32 v8, v8, v9
	v_mul_f32_e32 v9, v11, v11
	v_fmac_f32_e32 v9, v10, v10
	v_add_f32_e32 v8, v8, v9
	v_mul_f32_e32 v9, v19, v19
	v_fmac_f32_e32 v9, v18, v18
	s_waitcnt vmcnt(9)
	v_pk_add_f32 v[6:7], v[6:7], v[70:71]
	v_pk_add_f32 v[4:5], v[4:5], v[68:69]
	v_add_f32_e32 v20, v9, v8
	v_cvt_pk_bf16_f32 v8, v12, v13
	v_pk_add_f32 v[12:13], v[2:3], v[66:67]
	v_pk_add_f32 v[2:3], v[0:1], v[64:65]
	v_mul_f32_e32 v0, v5, v5
	v_mul_f32_e32 v1, v7, v7
	v_fmac_f32_e32 v0, v4, v4
	v_fmac_f32_e32 v1, v6, v6
	v_add_f32_e32 v0, v0, v1
	v_mul_f32_e32 v1, v3, v3
	v_fmac_f32_e32 v1, v2, v2
	v_add_f32_e32 v0, v0, v1
	v_mul_f32_e32 v1, v13, v13
	v_fmac_f32_e32 v1, v12, v12
	v_add_f32_e32 v0, v1, v0
	v_cvt_pk_bf16_f32 v9, v14, v15
	v_cvt_pk_bf16_f32 v10, v10, v11
	v_cvt_pk_bf16_f32 v11, v18, v19
	v_add_f32_e32 v18, v20, v0
	ds_bpermute_b32 v19, v175, v18
	v_lshlrev_b64 v[16:17], 11, v[88:89]
	v_lshl_add_u64 v[0:1], s[6:7], 0, v[16:17]
	v_lshl_add_u64 v[14:15], v[0:1], 0, v[160:161]
	global_store_dwordx4 v[14:15], v[8:11], off
	v_cvt_pk_bf16_f32 v0, v4, v5
	s_waitcnt lgkmcnt(0)
	v_add_f32_e32 v4, v18, v19
	ds_bpermute_b32 v5, v176, v4
	v_cvt_pk_bf16_f32 v1, v6, v7
	v_cvt_pk_bf16_f32 v2, v2, v3
	v_cvt_pk_bf16_f32 v3, v12, v13
	global_store_dwordx4 v[14:15], v[0:3], off offset:256
	s_nop 1
	v_lshlrev_b64 v[0:1], 6, v[88:89]
	v_lshl_add_u64 v[0:1], s[8:9], 0, v[0:1]
	v_lshl_add_u64 v[0:1], v[0:1], 0, s[20:21]
	s_waitcnt lgkmcnt(0)
	v_add_f32_e32 v2, v4, v5
	v_lshl_add_u64 v[0:1], v[0:1], 0, s[4:5]
	s_mov_b32 s21, s12
	s_mov_b32 s20, s14
	global_store_dword v[0:1], v2, off
	s_cbranch_vccz .LBB0_654
	s_waitcnt vmcnt(0)
	s_cmpk_gt_u32 s28, 0xff
	s_cbranch_scc1 .LBB0_665
	s_barrier

; #define PG8_STAGE(bufoff, gbase, voff) do { _Pragma("unroll") for (int _i = 0; _i < 2; ++_i) \
;         __builtin_amdgcn_global_load_lds((const unsigned*)((const char*)(gbase) + (voff)[_i]), (LAS unsigned*)(lds + (bufoff) + ldsw + _i * 8192), 16, 0, 0); } while (0)
; #define PG8_LDA(dst, b, h) do { _Pragma("unroll") for (int m = 0; m < 4; ++m) _Pragma("unroll") for (int k = 0; k < 2; ++k) dst[m][k] = *(const LAS bf16x8*)(lds + PG8_SA(b, h) + aoff + m * 2048 + k * 1024); } while (0)
; #define PG8_LDB(dst, b, h) do { _Pragma("unroll") for (int n = 0; n < 2; ++n) _Pragma("unroll") for (int k = 0; k < 2; ++k) dst[n][k] = *(const LAS bf16x8*)(lds + PG8_SB(b, h) + boff + n * 2048 + k * 1024); } while (0)
; #define PG8_MMA(ai, bj, At, Bt) do { __builtin_amdgcn_s_setprio(1); _Pragma("unroll") for (int m = 0; m < 4; ++m) _Pragma("unroll") for (int n = 0; n < 2; ++n) _Pragma("unroll") for (int k = 0; k < 2; ++k) \
;         acc[ai][bj][m][n] = __builtin_amdgcn_mfma_f32_16x16x32_bf16(Bt[n][k], At[m][k], acc[ai][bj][m][n], 0, 0, 0); __builtin_amdgcn_s_setprio(0); } while (0)
; template <class Epi, class Sched>
; __device__ __forceinline__ void gemm_phase(const int wv, LAS unsigned char* lds, const Gemm g, const Sched& S, const Epi& E) {
;     ...
;         const bool has_next = S.next(ui + 1, nxt);
;         const char* nA = has_next ? (const char*)g.A + (size_t)nxt.pm * tstepA : cA; const char* nB = has_next ? (const char*)g.Bt + (size_t)nxt.pn * tstepB : cB;
;         for (int t = 0; t < nt; t += 2) {
;             const bool last = (t == nt - 2);
;             const char* a1 = cA + (size_t)(t + 1) * kstepA;
;             const char* a2 = last ? nA : cA + (size_t)(t + 2) * kstepA; const char* b2 = last ? nB : cB + (size_t)(t + 2) * kstep;
;             const char* a3 = a2 + kstepA; const char* b3 = b2 + kstep;
;             if (last && has_next) S.a_ready(nxt);
;             PG8_LDB(B0, 0, 0); PG8_SCHED; PG8_LDA(At, 0, 0); PG8_STAGE(PG8_SA(1, 1), a1 + hstepA, voffA);
;             PG8_WAIT_L(8); PG8_BAR; PG8_WAIT_L(0); PG8_MMA(0, 0, At, B0); PG8_BAR; PG8_SCHED;
;             PG8_LDB(B1, 0, 1); PG8_STAGE(PG8_SB(0, 0), b2, voffB);
;             PG8_BAR; PG8_WAIT_L(0); PG8_MMA(0, 1, At, B1); PG8_BAR;
;             PG8_LDA(At, 0, 1); PG8_STAGE(PG8_SA(0, 0), a2, voffA);
;             PG8_BAR; PG8_WAIT_L(0); PG8_MMA(1, 0, At, B0); PG8_BAR; PG8_SCHED;
.LBB0_724:
	s_ashr_i32 s9, s8, 31
	v_cmp_lt_i64_e32 vcc, s[10:11], v[164:165]
	s_lshl_b64 s[10:11], s[8:9], 19
	s_add_u32 s10, s23, s10
	s_addc_u32 s11, s24, s11
	s_and_b64 s[12:13], vcc, exec
	s_cselect_b32 s9, s11, s17
	s_cselect_b32 s42, s10, s16
	s_ashr_i32 s7, s6, 31
	s_lshl_b64 s[12:13], s[6:7], 19
	s_add_u32 s12, s25, s12
	s_addc_u32 s13, s26, s13
	s_and_b64 s[20:21], vcc, exec
	s_cselect_b32 s7, s13, s19
	s_cselect_b32 s43, s12, s18
	s_add_u32 s16, s16, 0x40080
	s_addc_u32 s17, s17, 0
	s_add_u32 s44, s18, 0x100
	s_addc_u32 s45, s19, 0
	s_mov_b32 s46, -2
	ds_read_b128 v[128:131], v176
	ds_read_b128 v[132:135], v176 offset:1024
	ds_read_b128 v[136:139], v176 offset:2048
	ds_read_b128 v[140:143], v176 offset:3072
	s_add_u32 s18, s16, 0xfffc0080
	s_addc_u32 s19, s17, -1
	s_cmp_eq_u32 s46, 12
	s_cselect_b32 s21, s9, s19
	s_cselect_b32 s20, s42, s18
	s_cselect_b32 s19, s7, s45
	s_cselect_b32 s18, s43, s44
	v_lshl_add_u64 v[170:171], s[16:17], 0, v[160:161]
	s_add_i32 m0, s28, 0xc000
	ds_read_b128 v[144:147], v177
	ds_read_b128 v[182:185], v177 offset:1024
	ds_read_b128 v[186:189], v177 offset:2048
	ds_read_b128 v[190:193], v177 offset:3072
	ds_read_b128 v[194:197], v177 offset:4096
	ds_read_b128 v[198:201], v177 offset:5120
	ds_read_b128 v[202:205], v177 offset:6144
	ds_read_b128 v[206:209], v177 offset:7168
	global_load_lds_dwordx4 v[170:171], off
	v_lshl_add_u64 v[170:171], s[16:17], 0, v[162:163]
	s_add_i32 m0, s28, 0xe000
	s_nop 0
	global_load_lds_dwordx4 v[170:171], off
	s_waitcnt lgkmcnt(8)
	s_barrier
	s_waitcnt lgkmcnt(0)
	s_setprio 1
	s_waitcnt lgkmcnt(0)
	v_mfma_f32_16x16x32_bf16 v[124:127], v[128:131], v[144:147], 0
	v_mfma_f32_16x16x32_bf16 v[120:123], v[136:139], v[144:147], 0
	v_mfma_f32_16x16x32_bf16 v[108:111], v[128:131], v[186:189], 0
	v_mfma_f32_16x16x32_bf16 v[104:107], v[136:139], v[186:189], 0
	v_mfma_f32_16x16x32_bf16 v[92:95], v[128:131], v[194:197], 0
	v_mfma_f32_16x16x32_bf16 v[88:91], v[136:139], v[194:197], 0
	v_mfma_f32_16x16x32_bf16 v[76:79], v[128:131], v[202:205], 0
	v_mfma_f32_16x16x32_bf16 v[72:75], v[136:139], v[202:205], 0
	v_mfma_f32_16x16x32_bf16 v[124:127], v[132:135], v[182:185], v[124:127]
	v_mfma_f32_16x16x32_bf16 v[120:123], v[140:143], v[182:185], v[120:123]
	v_mfma_f32_16x16x32_bf16 v[108:111], v[132:135], v[190:193], v[108:111]
	v_mfma_f32_16x16x32_bf16 v[104:107], v[140:143], v[190:193], v[104:107]
	v_mfma_f32_16x16x32_bf16 v[92:95], v[132:135], v[198:201], v[92:95]
	v_mfma_f32_16x16x32_bf16 v[88:91], v[140:143], v[198:201], v[88:91]
	v_mfma_f32_16x16x32_bf16 v[76:79], v[132:135], v[206:209], v[76:79]
	v_mfma_f32_16x16x32_bf16 v[72:75], v[140:143], v[206:209], v[72:75]
	s_setprio 0
	s_barrier
	s_add_i32 s47, s39, s27
	v_lshl_add_u64 v[170:171], s[18:19], 0, v[150:151]
	s_mov_b32 m0, s47
	ds_read_b128 v[210:213], v180
	ds_read_b128 v[214:217], v180 offset:1024
	ds_read_b128 v[218:221], v180 offset:2048
	ds_read_b128 v[222:225], v180 offset:3072
	global_load_lds_dwordx4 v[170:171], off
	v_lshl_add_u64 v[226:227], s[18:19], 0, v[154:155]
	s_add_i32 m0, s47, 0x2000
	s_nop 0
	global_load_lds_dwordx4 v[226:227], off
	s_barrier
	s_waitcnt lgkmcnt(0)
	s_setprio 1
	s_waitcnt lgkmcnt(0)
	v_mfma_f32_16x16x32_bf16 v[116:119], v[210:213], v[144:147], 0
	v_mfma_f32_16x16x32_bf16 v[112:115], v[218:221], v[144:147], 0
	v_mfma_f32_16x16x32_bf16 v[100:103], v[210:213], v[186:189], 0
	v_mfma_f32_16x16x32_bf16 v[96:99], v[218:221], v[186:189], 0
	v_mfma_f32_16x16x32_bf16 v[84:87], v[210:213], v[194:197], 0
	v_mfma_f32_16x16x32_bf16 v[80:83], v[218:221], v[194:197], 0
	v_mfma_f32_16x16x32_bf16 v[68:71], v[210:213], v[202:205], 0
	v_mfma_f32_16x16x32_bf16 v[64:67], v[218:221], v[202:205], 0
	v_mfma_f32_16x16x32_bf16 v[116:119], v[214:217], v[182:185], v[116:119]
	v_mfma_f32_16x16x32_bf16 v[112:115], v[222:225], v[182:185], v[112:115]
	v_mfma_f32_16x16x32_bf16 v[100:103], v[214:217], v[190:193], v[100:103]
	v_mfma_f32_16x16x32_bf16 v[96:99], v[222:225], v[190:193], v[96:99]
	v_mfma_f32_16x16x32_bf16 v[84:87], v[214:217], v[198:201], v[84:87]
	v_mfma_f32_16x16x32_bf16 v[80:83], v[222:225], v[198:201], v[80:83]
	v_mfma_f32_16x16x32_bf16 v[68:71], v[214:217], v[206:209], v[68:71]
	v_mfma_f32_16x16x32_bf16 v[64:67], v[222:225], v[206:209], v[64:67]
	s_setprio 0
	s_mov_b32 m0, s28
	v_lshl_add_u64 v[228:229], s[20:21], 0, v[148:149]
	s_barrier
	ds_read_b128 v[144:147], v177 offset:16384
	ds_read_b128 v[182:185], v177 offset:17408
	ds_read_b128 v[186:189], v177 offset:18432
	ds_read_b128 v[190:193], v177 offset:19456
	ds_read_b128 v[194:197], v177 offset:20480
	ds_read_b128 v[198:201], v177 offset:21504
	ds_read_b128 v[202:205], v177 offset:22528
	ds_read_b128 v[206:209], v177 offset:23552
	global_load_lds_dwordx4 v[228:229], off
	v_lshl_add_u64 v[230:231], s[20:21], 0, v[152:153]
	s_mov_b32 m0, s29
	s_nop 0
	global_load_lds_dwordx4 v[230:231], off
	s_barrier
	s_waitcnt lgkmcnt(0)
	s_setprio 1
	s_waitcnt lgkmcnt(0)
	v_mfma_f32_16x16x32_bf16 v[60:63], v[128:131], v[144:147], 0
	v_mfma_f32_16x16x32_bf16 v[56:59], v[136:139], v[144:147], 0
	v_mfma_f32_16x16x32_bf16 v[44:47], v[128:131], v[186:189], 0
	v_mfma_f32_16x16x32_bf16 v[40:43], v[136:139], v[186:189], 0
	v_mfma_f32_16x16x32_bf16 v[28:31], v[128:131], v[194:197], 0
	v_mfma_f32_16x16x32_bf16 v[24:27], v[136:139], v[194:197], 0
	v_mfma_f32_16x16x32_bf16 v[12:15], v[128:131], v[202:205], 0
	v_mfma_f32_16x16x32_bf16 v[8:11], v[136:139], v[202:205], 0
	v_mfma_f32_16x16x32_bf16 v[60:63], v[132:135], v[182:185], v[60:63]
	v_mfma_f32_16x16x32_bf16 v[56:59], v[140:143], v[182:185], v[56:59]
	v_mfma_f32_16x16x32_bf16 v[44:47], v[132:135], v[190:193], v[44:47]
	v_mfma_f32_16x16x32_bf16 v[40:43], v[140:143], v[190:193], v[40:43]
	v_mfma_f32_16x16x32_bf16 v[28:31], v[132:135], v[198:201], v[28:31]
	v_mfma_f32_16x16x32_bf16 v[24:27], v[140:143], v[198:201], v[24:27]
	v_mfma_f32_16x16x32_bf16 v[12:15], v[132:135], v[206:209], v[12:15]
	v_mfma_f32_16x16x32_bf16 v[8:11], v[140:143], v[206:209], v[8:11]
	s_setprio 0
	s_barrier
; #define PG8_STAGE(bufoff, gbase, voff) do { _Pragma("unroll") for (int _i = 0; _i < 2; ++_i) \
;         __builtin_amdgcn_global_load_lds((const unsigned*)((const char*)(gbase) + (voff)[_i]), (LAS unsigned*)(lds + (bufoff) + ldsw + _i * 8192), 16, 0, 0); } while (0)
; #define PG8_LDA(dst, b, h) do { _Pragma("unroll") for (int m = 0; m < 4; ++m) _Pragma("unroll") for (int k = 0; k < 2; ++k) dst[m][k] = *(const LAS bf16x8*)(lds + PG8_SA(b, h) + aoff + m * 2048 + k * 1024); } while (0)
; #define PG8_LDB(dst, b, h) do { _Pragma("unroll") for (int n = 0; n < 2; ++n) _Pragma("unroll") for (int k = 0; k < 2; ++k) dst[n][k] = *(const LAS bf16x8*)(lds + PG8_SB(b, h) + boff + n * 2048 + k * 1024); } while (0)
; #define PG8_MMA(ai, bj, At, Bt) do { __builtin_amdgcn_s_setprio(1); _Pragma("unroll") for (int m = 0; m < 4; ++m) _Pragma("unroll") for (int n = 0; n < 2; ++n) _Pragma("unroll") for (int k = 0; k < 2; ++k) \
;         acc[ai][bj][m][n] = __builtin_amdgcn_mfma_f32_16x16x32_bf16(Bt[n][k], At[m][k], acc[ai][bj][m][n], 0, 0, 0); __builtin_amdgcn_s_setprio(0); } while (0)
; #define PG8_WAIT_V(n) asm volatile("s_waitcnt vmcnt(" #n ")" ::: "memory")
; #define PG8_WAIT_L(n) asm volatile("s_waitcnt lgkmcnt(" #n ")" ::: "memory")
; #define PG8_BAR __builtin_amdgcn_s_barrier()
; #define PG8_SCHED __builtin_amdgcn_sched_barrier(0)
; template <class Epi, class Sched>
; __device__ __forceinline__ void gemm_phase(const int wv, LAS unsigned char* lds, const Gemm g, const Sched& S, const Epi& E) {
;     ...
;             PG8_STAGE(PG8_SB(0, 1), b2 + hstepB, voffB);
;             PG8_WAIT_V(6); PG8_BAR; PG8_MMA(1, 1, At, B1); PG8_BAR;
;             PG8_LDB(B0, 1, 0); PG8_SCHED; PG8_LDA(At, 1, 0); PG8_STAGE(PG8_SA(0, 1), a2 + hstepA, voffA);
;             PG8_WAIT_L(8); PG8_BAR; PG8_WAIT_L(0); PG8_MMA(0, 0, At, B0); PG8_BAR; PG8_SCHED;
;             PG8_LDB(B1, 1, 1); PG8_STAGE(PG8_SB(1, 0), b3, voffB);
;             PG8_BAR; PG8_WAIT_L(0); PG8_MMA(0, 1, At, B1); PG8_BAR;
	s_add_u32 s48, s18, 0x40000
	s_addc_u32 s49, s19, 0
	s_add_i32 s47, s40, s27
	v_lshl_add_u64 v[128:129], s[48:49], 0, v[150:151]
	s_mov_b32 m0, s47
	s_nop 0
	global_load_lds_dwordx4 v[128:129], off
	v_lshl_add_u64 v[128:129], s[48:49], 0, v[154:155]
	s_add_i32 m0, s47, 0x2000
	s_nop 0
	global_load_lds_dwordx4 v[128:129], off
	s_waitcnt vmcnt(6)
	s_barrier
	s_setprio 1
	v_mfma_f32_16x16x32_bf16 v[52:55], v[210:213], v[144:147], 0
	v_mfma_f32_16x16x32_bf16 v[48:51], v[218:221], v[144:147], 0
	v_mfma_f32_16x16x32_bf16 v[36:39], v[210:213], v[186:189], 0
	v_mfma_f32_16x16x32_bf16 v[32:35], v[218:221], v[186:189], 0
	v_mfma_f32_16x16x32_bf16 v[20:23], v[210:213], v[194:197], 0
	v_mfma_f32_16x16x32_bf16 v[16:19], v[218:221], v[194:197], 0
	v_mfma_f32_16x16x32_bf16 v[4:7], v[210:213], v[202:205], 0
	v_mfma_f32_16x16x32_bf16 v[0:3], v[218:221], v[202:205], 0
	v_mfma_f32_16x16x32_bf16 v[52:55], v[214:217], v[182:185], v[52:55]
	v_mfma_f32_16x16x32_bf16 v[48:51], v[222:225], v[182:185], v[48:51]
	v_mfma_f32_16x16x32_bf16 v[36:39], v[214:217], v[190:193], v[36:39]
	v_mfma_f32_16x16x32_bf16 v[32:35], v[222:225], v[190:193], v[32:35]
	v_mfma_f32_16x16x32_bf16 v[20:23], v[214:217], v[198:201], v[20:23]
	v_mfma_f32_16x16x32_bf16 v[16:19], v[222:225], v[198:201], v[16:19]
	v_mfma_f32_16x16x32_bf16 v[4:7], v[214:217], v[206:209], v[4:7]
	v_mfma_f32_16x16x32_bf16 v[0:3], v[222:225], v[206:209], v[0:3]
	s_setprio 0
	s_add_i32 s47, 0, 0x18000
	v_add_u32_e32 v140, s47, v173
	s_barrier
	ds_read_b128 v[128:131], v140
	ds_read_b128 v[132:135], v140 offset:1024
	ds_read_b128 v[136:139], v140 offset:2048
	ds_read_b128 v[140:143], v140 offset:3072
	s_add_u32 s20, s20, 0x40000
	s_addc_u32 s21, s21, 0
	s_mov_b32 m0, s30
	v_lshl_add_u64 v[210:211], s[20:21], 0, v[148:149]
	ds_read_b128 v[144:147], v177 offset:32768
	ds_read_b128 v[182:185], v177 offset:33792
	ds_read_b128 v[186:189], v177 offset:34816
	ds_read_b128 v[190:193], v177 offset:35840
	ds_read_b128 v[194:197], v177 offset:36864
	ds_read_b128 v[198:201], v177 offset:37888
	ds_read_b128 v[202:205], v177 offset:38912
	ds_read_b128 v[206:209], v177 offset:39936
	global_load_lds_dwordx4 v[210:211], off
	v_lshl_add_u64 v[210:211], s[20:21], 0, v[152:153]
	s_mov_b32 m0, s31
	s_nop 0
	global_load_lds_dwordx4 v[210:211], off
	s_waitcnt lgkmcnt(8)
	s_barrier
	s_waitcnt lgkmcnt(0)
	s_setprio 1
	s_waitcnt lgkmcnt(0)
	v_mfma_f32_16x16x32_bf16 v[124:127], v[128:131], v[144:147], v[124:127]
	v_mfma_f32_16x16x32_bf16 v[120:123], v[136:139], v[144:147], v[120:123]
	v_mfma_f32_16x16x32_bf16 v[108:111], v[128:131], v[186:189], v[108:111]
	v_mfma_f32_16x16x32_bf16 v[104:107], v[136:139], v[186:189], v[104:107]
	v_mfma_f32_16x16x32_bf16 v[92:95], v[128:131], v[194:197], v[92:95]
	v_mfma_f32_16x16x32_bf16 v[88:91], v[136:139], v[194:197], v[88:91]
	v_mfma_f32_16x16x32_bf16 v[76:79], v[128:131], v[202:205], v[76:79]
	v_mfma_f32_16x16x32_bf16 v[72:75], v[136:139], v[202:205], v[72:75]
	v_mfma_f32_16x16x32_bf16 v[124:127], v[132:135], v[182:185], v[124:127]
	v_mfma_f32_16x16x32_bf16 v[120:123], v[140:143], v[182:185], v[120:123]
	v_mfma_f32_16x16x32_bf16 v[108:111], v[132:135], v[190:193], v[108:111]
	v_mfma_f32_16x16x32_bf16 v[104:107], v[140:143], v[190:193], v[104:107]
	v_mfma_f32_16x16x32_bf16 v[92:95], v[132:135], v[198:201], v[92:95]
	v_mfma_f32_16x16x32_bf16 v[88:91], v[140:143], v[198:201], v[88:91]
	v_mfma_f32_16x16x32_bf16 v[76:79], v[132:135], v[206:209], v[76:79]
	v_mfma_f32_16x16x32_bf16 v[72:75], v[140:143], v[206:209], v[72:75]
	s_setprio 0
	s_barrier
	s_add_i32 s20, 0, 0x1c000
	s_add_i32 s21, s47, s27
	v_add_u32_e32 v156, s20, v173
	v_lshl_add_u64 v[170:171], v[170:171], 0, s[4:5]
	s_mov_b32 m0, s21
	ds_read_b128 v[210:213], v156
	ds_read_b128 v[214:217], v156 offset:1024
	ds_read_b128 v[218:221], v156 offset:2048
	ds_read_b128 v[222:225], v156 offset:3072
	global_load_lds_dwordx4 v[170:171], off
	v_lshl_add_u64 v[170:171], v[226:227], 0, s[4:5]
	s_add_i32 m0, s21, 0x2000
	s_nop 0
	global_load_lds_dwordx4 v[170:171], off
	s_barrier
; #define PG8_STAGE(bufoff, gbase, voff) do { _Pragma("unroll") for (int _i = 0; _i < 2; ++_i) \
;         __builtin_amdgcn_global_load_lds((const unsigned*)((const char*)(gbase) + (voff)[_i]), (LAS unsigned*)(lds + (bufoff) + ldsw + _i * 8192), 16, 0, 0); } while (0)
; #define PG8_LDA(dst, b, h) do { _Pragma("unroll") for (int m = 0; m < 4; ++m) _Pragma("unroll") for (int k = 0; k < 2; ++k) dst[m][k] = *(const LAS bf16x8*)(lds + PG8_SA(b, h) + aoff + m * 2048 + k * 1024); } while (0)
; #define PG8_MMA(ai, bj, At, Bt) do { __builtin_amdgcn_s_setprio(1); _Pragma("unroll") for (int m = 0; m < 4; ++m) _Pragma("unroll") for (int n = 0; n < 2; ++n) _Pragma("unroll") for (int k = 0; k < 2; ++k) \
;         acc[ai][bj][m][n] = __builtin_amdgcn_mfma_f32_16x16x32_bf16(Bt[n][k], At[m][k], acc[ai][bj][m][n], 0, 0, 0); __builtin_amdgcn_s_setprio(0); } while (0)
; #define PG8_WAIT_V(n) asm volatile("s_waitcnt vmcnt(" #n ")" ::: "memory")
; #define PG8_WAIT_L(n) asm volatile("s_waitcnt lgkmcnt(" #n ")" ::: "memory")
; #define PG8_BAR __builtin_amdgcn_s_barrier()
; #define PG8_SCHED __builtin_amdgcn_sched_barrier(0)
; template <class Epi, class Sched>
; __device__ __forceinline__ void gemm_phase(const int wv, LAS unsigned char* lds, const Gemm g, const Sched& S, const Epi& E) {
;     ...
;             PG8_BAR; PG8_WAIT_L(0); PG8_MMA(0, 1, At, B1); PG8_BAR;
;             PG8_LDA(At, 1, 1); PG8_STAGE(PG8_SA(1, 0), a3, voffA);
;             PG8_BAR; PG8_WAIT_L(0); PG8_MMA(1, 0, At, B0); PG8_BAR; PG8_SCHED;
;             PG8_STAGE(PG8_SB(1, 1), b3 + hstepB, voffB);
;             PG8_WAIT_V(6); PG8_BAR; PG8_MMA(1, 1, At, B1); PG8_BAR;
;         }
	s_waitcnt lgkmcnt(0)
	s_setprio 1
	s_waitcnt lgkmcnt(0)
	v_mfma_f32_16x16x32_bf16 v[116:119], v[210:213], v[144:147], v[116:119]
	v_mfma_f32_16x16x32_bf16 v[112:115], v[218:221], v[144:147], v[112:115]
	v_mfma_f32_16x16x32_bf16 v[100:103], v[210:213], v[186:189], v[100:103]
	v_mfma_f32_16x16x32_bf16 v[96:99], v[218:221], v[186:189], v[96:99]
	v_mfma_f32_16x16x32_bf16 v[84:87], v[210:213], v[194:197], v[84:87]
	v_mfma_f32_16x16x32_bf16 v[80:83], v[218:221], v[194:197], v[80:83]
	v_mfma_f32_16x16x32_bf16 v[68:71], v[210:213], v[202:205], v[68:71]
	v_mfma_f32_16x16x32_bf16 v[64:67], v[218:221], v[202:205], v[64:67]
	v_mfma_f32_16x16x32_bf16 v[116:119], v[214:217], v[182:185], v[116:119]
	v_mfma_f32_16x16x32_bf16 v[112:115], v[222:225], v[182:185], v[112:115]
	v_mfma_f32_16x16x32_bf16 v[100:103], v[214:217], v[190:193], v[100:103]
	v_mfma_f32_16x16x32_bf16 v[96:99], v[222:225], v[190:193], v[96:99]
	v_mfma_f32_16x16x32_bf16 v[84:87], v[214:217], v[198:201], v[84:87]
	v_mfma_f32_16x16x32_bf16 v[80:83], v[222:225], v[198:201], v[80:83]
	v_mfma_f32_16x16x32_bf16 v[68:71], v[214:217], v[206:209], v[68:71]
	v_mfma_f32_16x16x32_bf16 v[64:67], v[222:225], v[206:209], v[64:67]
	s_setprio 0
	s_mov_b32 m0, s37
	v_lshl_add_u64 v[170:171], v[228:229], 0, s[4:5]
	s_barrier
	ds_read_b128 v[144:147], v177 offset:49152
	ds_read_b128 v[182:185], v177 offset:50176
	ds_read_b128 v[186:189], v177 offset:51200
	ds_read_b128 v[190:193], v177 offset:52224
	ds_read_b128 v[194:197], v177 offset:53248
	ds_read_b128 v[198:201], v177 offset:54272
	ds_read_b128 v[202:205], v177 offset:55296
	ds_read_b128 v[206:209], v177 offset:56320
	global_load_lds_dwordx4 v[170:171], off
	v_lshl_add_u64 v[170:171], v[230:231], 0, s[4:5]
	s_mov_b32 m0, s38
	s_nop 0
	global_load_lds_dwordx4 v[170:171], off
	s_barrier
	s_waitcnt lgkmcnt(0)
	s_setprio 1
	s_waitcnt lgkmcnt(0)
	v_mfma_f32_16x16x32_bf16 v[60:63], v[128:131], v[144:147], v[60:63]
	v_mfma_f32_16x16x32_bf16 v[56:59], v[136:139], v[144:147], v[56:59]
	v_mfma_f32_16x16x32_bf16 v[44:47], v[128:131], v[186:189], v[44:47]
	v_mfma_f32_16x16x32_bf16 v[40:43], v[136:139], v[186:189], v[40:43]
	v_mfma_f32_16x16x32_bf16 v[28:31], v[128:131], v[194:197], v[28:31]
	v_mfma_f32_16x16x32_bf16 v[24:27], v[136:139], v[194:197], v[24:27]
	v_mfma_f32_16x16x32_bf16 v[12:15], v[128:131], v[202:205], v[12:15]
	v_mfma_f32_16x16x32_bf16 v[8:11], v[136:139], v[202:205], v[8:11]
	v_mfma_f32_16x16x32_bf16 v[60:63], v[132:135], v[182:185], v[60:63]
	v_mfma_f32_16x16x32_bf16 v[56:59], v[140:143], v[182:185], v[56:59]
	v_mfma_f32_16x16x32_bf16 v[44:47], v[132:135], v[190:193], v[44:47]
	v_mfma_f32_16x16x32_bf16 v[40:43], v[140:143], v[190:193], v[40:43]
	v_mfma_f32_16x16x32_bf16 v[28:31], v[132:135], v[198:201], v[28:31]
	v_mfma_f32_16x16x32_bf16 v[24:27], v[140:143], v[198:201], v[24:27]
	v_mfma_f32_16x16x32_bf16 v[12:15], v[132:135], v[206:209], v[12:15]
	v_mfma_f32_16x16x32_bf16 v[8:11], v[140:143], v[206:209], v[8:11]
	s_setprio 0
	s_barrier
	s_add_u32 s18, s18, 0x40080
	s_addc_u32 s19, s19, 0
	s_add_i32 s20, s20, s27
	v_lshl_add_u64 v[128:129], s[18:19], 0, v[150:151]
	s_mov_b32 m0, s20
	s_nop 0
	global_load_lds_dwordx4 v[128:129], off
	v_lshl_add_u64 v[128:129], s[18:19], 0, v[154:155]
	s_add_i32 m0, s20, 0x2000
	s_nop 0
	global_load_lds_dwordx4 v[128:129], off
	s_waitcnt vmcnt(6)
	s_barrier
	s_setprio 1
	v_mfma_f32_16x16x32_bf16 v[52:55], v[210:213], v[144:147], v[52:55]
	v_mfma_f32_16x16x32_bf16 v[48:51], v[218:221], v[144:147], v[48:51]
	v_mfma_f32_16x16x32_bf16 v[36:39], v[210:213], v[186:189], v[36:39]
	v_mfma_f32_16x16x32_bf16 v[32:35], v[218:221], v[186:189], v[32:35]
	v_mfma_f32_16x16x32_bf16 v[20:23], v[210:213], v[194:197], v[20:23]
	v_mfma_f32_16x16x32_bf16 v[16:19], v[218:221], v[194:197], v[16:19]
	v_mfma_f32_16x16x32_bf16 v[4:7], v[210:213], v[202:205], v[4:7]
	v_mfma_f32_16x16x32_bf16 v[0:3], v[218:221], v[202:205], v[0:3]
	v_mfma_f32_16x16x32_bf16 v[52:55], v[214:217], v[182:185], v[52:55]
	v_mfma_f32_16x16x32_bf16 v[48:51], v[222:225], v[182:185], v[48:51]
	v_mfma_f32_16x16x32_bf16 v[36:39], v[214:217], v[190:193], v[36:39]
	v_mfma_f32_16x16x32_bf16 v[32:35], v[222:225], v[190:193], v[32:35]
	v_mfma_f32_16x16x32_bf16 v[20:23], v[214:217], v[198:201], v[20:23]
	v_mfma_f32_16x16x32_bf16 v[16:19], v[222:225], v[198:201], v[16:19]
	v_mfma_f32_16x16x32_bf16 v[4:7], v[214:217], v[206:209], v[4:7]
	v_mfma_f32_16x16x32_bf16 v[0:3], v[222:225], v[206:209], v[0:3]
	s_setprio 0
	s_add_i32 s46, s46, 2
	s_add_u32 s16, s16, 0x100
	s_addc_u32 s17, s17, 0
	s_add_u32 s44, s44, 0x100
	s_addc_u32 s45, s45, 0
	s_cmp_gt_u32 s46, 13
	s_barrier
	s_cbranch_scc0 .LBB0_725
	s_branch .Lpeel_exit_t725

; __device__ __forceinline__ float shx(float v, int lane, int mask) { return __int_as_float(__builtin_amdgcn_ds_bpermute((lane ^ mask) << 2, __float_as_int(v))); }
; __device__ __forceinline__ unsigned cvt_pk_bf16(float lo, float hi) { unsigned r; asm volatile("v_cvt_pk_bf16_f32 %0, %1, %2" : "=v"(r) : "v"(lo), "v"(hi)); return r; }
;     __device__ __forceinline__ void operator()(const f32x4 (&acc)[2][2][4][2], const Unit& u, int wr, int wc, int fr, int fq) const {
;         const int row0 = u.pm * 256 + wr * 64 + fr; const int col0 = u.pn * 256 + wc * 32 + 8 * fq;
;         f32x4 sq[2][4];
; #pragma unroll
;         for (int ai = 0; ai < 2; ++ai)
; #pragma unroll
;             for (int m = 0; m < 4; ++m) sq[ai][m] = *(const f32x4*)(ss2 + (size_t)(row0 + ai * 128 + m * 16) * 16 + 4 * fq);
; #pragma unroll
;         for (int ai = 0; ai < 2; ++ai)
; #pragma unroll
;             for (int m = 0; m < 4; ++m) {
;                 const int row = row0 + ai * 128 + m * 16;
;                 float ss = (sq[ai][m][0] + sq[ai][m][1]) + (sq[ai][m][2] + sq[ai][m][3]);
;                 ss += shx(ss, fq * 16 + fr, 16); ss += shx(ss, fq * 16 + fr, 32);
;                 const float rs = rsqrtf(ss * (1.0f / 1024.0f) + EPS);
; #pragma unroll
;                 for (int bj = 0; bj < 2; ++bj) {
;                     f32x4 v0 = acc[ai][bj][m][0] * rs, v1 = acc[ai][bj][m][1] * rs;
; #pragma unroll
;                     for (int j = 0; j < 4; ++j) { const float a = fmaxf(v0[j], 0.f), b = fmaxf(v1[j], 0.f); v0[j] = a * a; v1[j] = b * b; }
;                     u32x4 w; w.x = cvt_pk_bf16(v0[0], v0[1]); w.y = cvt_pk_bf16(v0[2], v0[3]); w.z = cvt_pk_bf16(v1[0], v1[1]); w.w = cvt_pk_bf16(v1[2], v1[3]);
;                     { const int col = col0 + bj * 128;
;                       *(u32x4*)(H + ((size_t)((row >> 8) * (DFF / 64) + (col >> 6)) * 256 + (row & 255)) * 64 + (col & 63)) = w; }
.Lpeel_exit_t725:
	s_lshl_b32 s7, s14, 8
	s_add_i32 s7, s7, s35
	v_or_b32_e32 v132, s7, v172
	v_ashrrev_i32_e32 v133, 31, v132
	v_lshlrev_b64 v[128:129], 6, v[132:133]
	v_lshl_add_u64 v[134:135], v[158:159], 0, v[128:129]
	global_load_dwordx4 v[128:131], v[134:135], off
	v_or_b32_e32 v136, 16, v132
	v_ashrrev_i32_e32 v137, 31, v136
	v_lshlrev_b64 v[136:137], 6, v[136:137]
	v_lshl_add_u64 v[136:137], v[158:159], 0, v[136:137]
	global_load_dwordx4 v[182:185], v[136:137], off
	v_or_b32_e32 v136, 32, v132
	v_or_b32_e32 v138, 48, v132
	v_add_u32_e32 v170, 0x80, v132
	v_lshlrev_b32_e32 v132, 7, v132
	v_ashrrev_i32_e32 v137, 31, v136
	v_ashrrev_i32_e32 v139, 31, v138
	v_and_b32_e32 v156, 0x6780, v132
	v_lshlrev_b64 v[132:133], 6, v[136:137]
	v_lshlrev_b64 v[136:137], 6, v[138:139]
	v_lshl_add_u64 v[132:133], v[158:159], 0, v[132:133]
	v_lshl_add_u64 v[136:137], v[158:159], 0, v[136:137]
	global_load_dwordx4 v[186:189], v[132:133], off
	global_load_dwordx4 v[144:147], v[136:137], off
	v_ashrrev_i32_e32 v171, 31, v170
	v_lshlrev_b64 v[138:139], 6, v[170:171]
	v_add_co_u32_e32 v190, vcc, s33, v134
	s_lshl_b32 s9, s15, 8
	s_nop 0
	v_addc_co_u32_e32 v191, vcc, 0, v135, vcc
	s_or_b32 s9, s9, s36
	s_ashr_i32 s14, s7, 2
	s_ashr_i32 s7, s9, 6
	s_and_b32 s16, s14, 0xffffffc0
	s_add_i32 s14, s16, s7
	s_ashr_i32 s15, s14, 31
	s_lshl_b64 s[14:15], s[14:15], 15
	s_add_u32 s14, s2, s14
	v_lshl_add_u64 v[138:139], v[158:159], 0, v[138:139]
	s_addc_u32 s15, s3, s15
	v_mov_b32_e32 v169, v157
	s_or_b32 s9, s7, 2
	s_add_i32 s16, s16, s9
	s_ashr_i32 s17, s16, 31
	s_lshl_b64 s[16:17], s[16:17], 15
	s_add_u32 s16, s2, s16
	s_addc_u32 s17, s3, s17
	s_mov_b64 s[18:19], s[12:13]
	s_waitcnt vmcnt(0)
	v_mov_b32_e32 v132, v129
	v_mov_b32_e32 v133, v130
	v_mov_b32_e32 v129, v131
	v_pk_add_f32 v[128:129], v[132:133], v[128:129]
	v_mov_b32_e32 v193, v184
	v_add_f32_e32 v171, v128, v129
	ds_bpermute_b32 v192, v174, v171
	global_load_dwordx4 v[140:143], v[138:139], off
	s_nop 0
	global_load_dwordx4 v[136:139], v[190:191], off offset:1024
	global_load_dwordx4 v[132:135], v[190:191], off offset:2048
	global_load_dwordx4 v[128:131], v[190:191], off offset:3072
	v_lshl_add_u64 v[190:191], s[14:15], 0, v[156:157]
	v_lshl_add_u64 v[190:191], v[190:191], 0, v[168:169]
	s_waitcnt lgkmcnt(0)
	v_add_f32_e32 v171, v171, v192
	ds_bpermute_b32 v192, v175, v171
	s_waitcnt lgkmcnt(0)
	v_add_f32_e32 v171, v171, v192
	v_fmamk_f32 v171, v171, 0x3a800000, v181
	v_mul_f32_e32 v192, 0x4b800000, v171
	v_cmp_gt_f32_e32 vcc, s41, v171
	s_nop 1
	v_cndmask_b32_e32 v171, v171, v192, vcc
	v_rsq_f32_e32 v171, v171
	v_mov_b32_e32 v192, v183
	v_mov_b32_e32 v183, v185
	v_mul_f32_e32 v184, 0x45800000, v171
	v_cndmask_b32_e32 v184, v171, v184, vcc
	v_pk_mul_f32 v[126:127], v[126:127], v[184:185] op_sel_hi:[1,0]
	v_pk_mul_f32 v[124:125], v[124:125], v[184:185] op_sel_hi:[1,0]
	v_pk_mul_f32 v[122:123], v[122:123], v[184:185] op_sel_hi:[1,0]
	v_pk_mul_f32 v[120:121], v[120:121], v[184:185] op_sel_hi:[1,0]
	v_pk_mul_f32 v[114:115], v[114:115], v[184:185] op_sel_hi:[1,0]
	v_pk_mul_f32 v[112:113], v[112:113], v[184:185] op_sel_hi:[1,0]
	v_pk_mul_f32 v[116:117], v[116:117], v[184:185] op_sel_hi:[1,0]
	v_max_f32_e32 v124, 0, v124
	v_max_f32_e32 v120, 0, v120
	v_max_f32_e32 v125, 0, v125
	v_max_f32_e32 v121, 0, v121
	v_max_f32_e32 v126, 0, v126
	v_max_f32_e32 v122, 0, v122
	v_max_f32_e32 v127, 0, v127
	v_max_f32_e32 v123, 0, v123
	v_max_f32_e32 v112, 0, v112
	v_max_f32_e32 v113, 0, v113
	v_max_f32_e32 v114, 0, v114
	v_max_f32_e32 v115, 0, v115
	v_pk_mul_f32 v[118:119], v[118:119], v[184:185] op_sel_hi:[1,0]
	v_max_f32_e32 v116, 0, v116
	v_mul_f32_e32 v124, v124, v124
	v_mul_f32_e32 v120, v120, v120
	v_mul_f32_e32 v125, v125, v125
	v_mul_f32_e32 v121, v121, v121
	v_mul_f32_e32 v126, v126, v126
	v_mul_f32_e32 v122, v122, v122
	v_mul_f32_e32 v127, v127, v127
	v_mul_f32_e32 v123, v123, v123
	v_mul_f32_e32 v171, v112, v112
	v_mul_f32_e32 v184, v113, v113
	v_mul_f32_e32 v185, v114, v114
	v_mul_f32_e32 v194, v115, v115
	v_cvt_pk_bf16_f32 v112, v124, v125
	v_cvt_pk_bf16_f32 v113, v126, v127
	v_cvt_pk_bf16_f32 v114, v120, v121
	v_cvt_pk_bf16_f32 v115, v122, v123
	v_max_f32_e32 v117, 0, v117
	v_mul_f32_e32 v116, v116, v116
	global_store_dwordx4 v[190:191], v[112:115], off
	v_mul_f32_e32 v117, v117, v117
	v_max_f32_e32 v118, 0, v118
	v_pk_add_f32 v[114:115], v[192:193], v[182:183]
	v_cvt_pk_bf16_f32 v112, v116, v117
	v_max_f32_e32 v119, 0, v119
	v_add_f32_e32 v116, v114, v115
	ds_bpermute_b32 v117, v174, v116
	v_mul_f32_e32 v118, v118, v118
	v_mul_f32_e32 v119, v119, v119
	v_cvt_pk_bf16_f32 v113, v118, v119
	v_cvt_pk_bf16_f32 v114, v171, v184
	s_waitcnt lgkmcnt(0)
	v_add_f32_e32 v116, v116, v117
	ds_bpermute_b32 v117, v175, v116
	v_cvt_pk_bf16_f32 v115, v185, v194
	s_waitcnt lgkmcnt(0)
; __device__ __forceinline__ float shx(float v, int lane, int mask) { return __int_as_float(__builtin_amdgcn_ds_bpermute((lane ^ mask) << 2, __float_as_int(v))); }
; __device__ __forceinline__ unsigned cvt_pk_bf16(float lo, float hi) { unsigned r; asm volatile("v_cvt_pk_bf16_f32 %0, %1, %2" : "=v"(r) : "v"(lo), "v"(hi)); return r; }
;     __device__ __forceinline__ void operator()(const f32x4 (&acc)[2][2][4][2], const Unit& u, int wr, int wc, int fr, int fq) const {
;     ...
;             for (int m = 0; m < 4; ++m) {
;                 const int row = row0 + ai * 128 + m * 16;
;                 float ss = (sq[ai][m][0] + sq[ai][m][1]) + (sq[ai][m][2] + sq[ai][m][3]);
;                 ss += shx(ss, fq * 16 + fr, 16); ss += shx(ss, fq * 16 + fr, 32);
;                 const float rs = rsqrtf(ss * (1.0f / 1024.0f) + EPS);
; #pragma unroll
;                 for (int bj = 0; bj < 2; ++bj) {
;                     f32x4 v0 = acc[ai][bj][m][0] * rs, v1 = acc[ai][bj][m][1] * rs;
; #pragma unroll
;                     for (int j = 0; j < 4; ++j) { const float a = fmaxf(v0[j], 0.f), b = fmaxf(v1[j], 0.f); v0[j] = a * a; v1[j] = b * b; }
;                     u32x4 w; w.x = cvt_pk_bf16(v0[0], v0[1]); w.y = cvt_pk_bf16(v0[2], v0[3]); w.z = cvt_pk_bf16(v1[0], v1[1]); w.w = cvt_pk_bf16(v1[2], v1[3]);
;                     { const int col = col0 + bj * 128;
;                       *(u32x4*)(H + ((size_t)((row >> 8) * (DFF / 64) + (col >> 6)) * 256 + (row & 255)) * 64 + (col & 63)) = w; }
;                 }
	v_add_f32_e32 v116, v116, v117
	v_fmamk_f32 v116, v116, 0x3a800000, v181
	v_mul_f32_e32 v117, 0x4b800000, v116
	v_cmp_gt_f32_e32 vcc, s41, v116
	s_nop 1
	v_cndmask_b32_e32 v116, v116, v117, vcc
	v_rsq_f32_e32 v118, v116
	v_lshl_add_u64 v[116:117], s[16:17], 0, v[156:157]
	v_lshl_add_u64 v[116:117], v[116:117], 0, v[168:169]
	global_store_dwordx4 v[116:117], v[112:115], off
	s_nop 1
	v_mul_f32_e32 v112, 0x45800000, v118
	v_cndmask_b32_e32 v112, v118, v112, vcc
	v_pk_mul_f32 v[104:105], v[104:105], v[112:113] op_sel_hi:[1,0]
	v_pk_mul_f32 v[108:109], v[108:109], v[112:113] op_sel_hi:[1,0]
	v_pk_mul_f32 v[106:107], v[106:107], v[112:113] op_sel_hi:[1,0]
	v_max_f32_e32 v104, 0, v104
	v_pk_mul_f32 v[110:111], v[110:111], v[112:113] op_sel_hi:[1,0]
	v_mul_f32_e32 v113, v104, v104
	v_max_f32_e32 v104, 0, v109
	v_max_f32_e32 v105, 0, v105
	v_max_f32_e32 v106, 0, v106
	v_max_f32_e32 v108, 0, v108
	v_mul_f32_e32 v104, v104, v104
	v_mul_f32_e32 v109, v105, v105
	v_max_f32_e32 v105, 0, v110
	v_mul_f32_e32 v110, v106, v106
	v_max_f32_e32 v106, 0, v111
	v_max_f32_e32 v107, 0, v107
	v_pk_mul_f32 v[96:97], v[96:97], v[112:113] op_sel_hi:[1,0]
	v_mul_f32_e32 v108, v108, v108
	v_mul_f32_e32 v105, v105, v105
	v_mul_f32_e32 v106, v106, v106
	v_mul_f32_e32 v107, v107, v107
	v_cvt_pk_bf16_f32 v104, v108, v104
	v_pk_mul_f32 v[100:101], v[100:101], v[112:113] op_sel_hi:[1,0]
	v_max_f32_e32 v96, 0, v96
	v_cvt_pk_bf16_f32 v105, v105, v106
	v_cvt_pk_bf16_f32 v106, v113, v109
	v_cvt_pk_bf16_f32 v107, v110, v107
	global_store_dwordx4 v[190:191], v[104:107], off offset:2048
	v_max_f32_e32 v97, 0, v97
	v_pk_mul_f32 v[98:99], v[98:99], v[112:113] op_sel_hi:[1,0]
	v_mul_f32_e32 v104, v96, v96
	v_max_f32_e32 v96, 0, v101
	v_mul_f32_e32 v101, v96, v96
	v_mul_f32_e32 v105, v97, v97
	v_mov_b32_e32 v96, v187
	v_mov_b32_e32 v97, v188
	v_mov_b32_e32 v187, v189
	v_pk_add_f32 v[96:97], v[96:97], v[186:187]
	v_pk_mul_f32 v[102:103], v[102:103], v[112:113] op_sel_hi:[1,0]
	v_add_f32_e32 v96, v96, v97
	ds_bpermute_b32 v97, v174, v96
	v_max_f32_e32 v98, 0, v98
	v_mul_f32_e32 v106, v98, v98
	v_max_f32_e32 v98, 0, v103
	v_max_f32_e32 v100, 0, v100
	s_waitcnt lgkmcnt(0)
	v_add_f32_e32 v103, v96, v97
	ds_bpermute_b32 v107, v175, v103
	v_mul_f32_e32 v97, v98, v98
	v_mul_f32_e32 v100, v100, v100
	v_cvt_pk_bf16_f32 v96, v100, v101
	v_max_f32_e32 v99, 0, v99
	s_waitcnt lgkmcnt(0)
	v_add_f32_e32 v98, v103, v107
	v_fmamk_f32 v98, v98, 0x3a800000, v181
	v_mul_f32_e32 v100, 0x4b800000, v98
	v_cmp_gt_f32_e32 vcc, s41, v98
	v_max_f32_e32 v102, 0, v102
	v_mul_f32_e32 v99, v99, v99
	v_cndmask_b32_e32 v98, v98, v100, vcc
	v_rsq_f32_e32 v100, v98
	v_mul_f32_e32 v102, v102, v102
	v_cvt_pk_bf16_f32 v97, v102, v97
	v_cvt_pk_bf16_f32 v98, v104, v105
	v_cvt_pk_bf16_f32 v99, v106, v99
	global_store_dwordx4 v[116:117], v[96:99], off offset:2048
	s_nop 1
	v_mul_f32_e32 v96, 0x45800000, v100
	v_cndmask_b32_e32 v96, v100, v96, vcc
	v_pk_mul_f32 v[90:91], v[90:91], v[96:97] op_sel_hi:[1,0]
	v_pk_mul_f32 v[88:89], v[88:89], v[96:97] op_sel_hi:[1,0]
	v_pk_mul_f32 v[94:95], v[94:95], v[96:97] op_sel_hi:[1,0]
	v_pk_mul_f32 v[92:93], v[92:93], v[96:97] op_sel_hi:[1,0]
	v_max_f32_e32 v88, 0, v88
	v_max_f32_e32 v89, 0, v89
	v_max_f32_e32 v90, 0, v90
	v_max_f32_e32 v92, 0, v92
	v_mul_f32_e32 v97, v88, v88
	v_max_f32_e32 v88, 0, v93
	v_mul_f32_e32 v93, v89, v89
	v_max_f32_e32 v89, 0, v94
	v_mul_f32_e32 v94, v90, v90
	v_max_f32_e32 v90, 0, v95
	v_mul_f32_e32 v92, v92, v92
	v_mul_f32_e32 v88, v88, v88
	v_mul_f32_e32 v89, v89, v89
	v_max_f32_e32 v91, 0, v91
	v_mul_f32_e32 v90, v90, v90
	v_mul_f32_e32 v91, v91, v91
	v_cvt_pk_bf16_f32 v88, v92, v88
	v_cvt_pk_bf16_f32 v89, v89, v90
	v_cvt_pk_bf16_f32 v90, v97, v93
	v_or_b32_e32 v92, 0x1000, v156
	v_mov_b32_e32 v93, v157
	v_cvt_pk_bf16_f32 v91, v94, v91
	v_lshl_add_u64 v[94:95], s[14:15], 0, v[92:93]
	v_pk_mul_f32 v[80:81], v[80:81], v[96:97] op_sel_hi:[1,0]
	v_lshl_add_u64 v[94:95], v[94:95], 0, v[168:169]
	v_pk_mul_f32 v[84:85], v[84:85], v[96:97] op_sel_hi:[1,0]
	v_max_f32_e32 v80, 0, v80
	global_store_dwordx4 v[94:95], v[88:91], off
	v_pk_mul_f32 v[86:87], v[86:87], v[96:97] op_sel_hi:[1,0]
	v_pk_mul_f32 v[82:83], v[82:83], v[96:97] op_sel_hi:[1,0]
	v_mul_f32_e32 v88, v80, v80
	v_max_f32_e32 v80, 0, v85
	v_max_f32_e32 v81, 0, v81
	v_mul_f32_e32 v85, v80, v80
	v_mul_f32_e32 v89, v81, v81
	v_max_f32_e32 v80, 0, v86
	v_max_f32_e32 v81, 0, v82
	v_mul_f32_e32 v82, v80, v80
	v_mul_f32_e32 v86, v81, v81
	v_mov_b32_e32 v80, v145
	v_mov_b32_e32 v81, v146
	v_mov_b32_e32 v145, v147
	v_pk_add_f32 v[80:81], v[80:81], v[144:145]
	v_max_f32_e32 v84, 0, v84
	v_add_f32_e32 v80, v80, v81
	ds_bpermute_b32 v81, v174, v80
	v_mul_f32_e32 v84, v84, v84
	v_max_f32_e32 v83, 0, v83
	v_max_f32_e32 v87, 0, v87
	v_mul_f32_e32 v83, v83, v83
	s_waitcnt lgkmcnt(0)
	v_add_f32_e32 v90, v80, v81
	ds_bpermute_b32 v91, v175, v90
	v_cvt_pk_bf16_f32 v80, v84, v85
	v_mul_f32_e32 v87, v87, v87
	v_cvt_pk_bf16_f32 v81, v82, v87
	v_cvt_pk_bf16_f32 v82, v88, v89
	s_waitcnt lgkmcnt(0)
; __device__ __forceinline__ float shx(float v, int lane, int mask) { return __int_as_float(__builtin_amdgcn_ds_bpermute((lane ^ mask) << 2, __float_as_int(v))); }
; __device__ __forceinline__ unsigned cvt_pk_bf16(float lo, float hi) { unsigned r; asm volatile("v_cvt_pk_bf16_f32 %0, %1, %2" : "=v"(r) : "v"(lo), "v"(hi)); return r; }
;     __device__ __forceinline__ void operator()(const f32x4 (&acc)[2][2][4][2], const Unit& u, int wr, int wc, int fr, int fq) const {
;     ...
;             for (int m = 0; m < 4; ++m) {
;                 const int row = row0 + ai * 128 + m * 16;
;                 float ss = (sq[ai][m][0] + sq[ai][m][1]) + (sq[ai][m][2] + sq[ai][m][3]);
;                 ss += shx(ss, fq * 16 + fr, 16); ss += shx(ss, fq * 16 + fr, 32);
;                 const float rs = rsqrtf(ss * (1.0f / 1024.0f) + EPS);
; #pragma unroll
;                 for (int bj = 0; bj < 2; ++bj) {
;                     f32x4 v0 = acc[ai][bj][m][0] * rs, v1 = acc[ai][bj][m][1] * rs;
; #pragma unroll
;                     for (int j = 0; j < 4; ++j) { const float a = fmaxf(v0[j], 0.f), b = fmaxf(v1[j], 0.f); v0[j] = a * a; v1[j] = b * b; }
;                     u32x4 w; w.x = cvt_pk_bf16(v0[0], v0[1]); w.y = cvt_pk_bf16(v0[2], v0[3]); w.z = cvt_pk_bf16(v1[0], v1[1]); w.w = cvt_pk_bf16(v1[2], v1[3]);
;                     { const int col = col0 + bj * 128;
;                       *(u32x4*)(H + ((size_t)((row >> 8) * (DFF / 64) + (col >> 6)) * 256 + (row & 255)) * 64 + (col & 63)) = w; }
;                 }
	v_add_f32_e32 v84, v90, v91
	v_fmamk_f32 v84, v84, 0x3a800000, v181
	v_mul_f32_e32 v85, 0x4b800000, v84
	v_cmp_gt_f32_e32 vcc, s41, v84
	v_cvt_pk_bf16_f32 v83, v86, v83
	v_or_b32_e32 v156, 0x1800, v156
	s_nop 0
	v_cndmask_b32_e32 v84, v84, v85, vcc
	v_rsq_f32_e32 v86, v84
	v_lshl_add_u64 v[84:85], s[16:17], 0, v[92:93]
	v_lshl_add_u64 v[84:85], v[84:85], 0, v[168:169]
	global_store_dwordx4 v[84:85], v[80:83], off
	s_nop 1
	v_mul_f32_e32 v80, 0x45800000, v86
	v_cndmask_b32_e32 v80, v86, v80, vcc
	v_pk_mul_f32 v[74:75], v[74:75], v[80:81] op_sel_hi:[1,0]
	v_pk_mul_f32 v[72:73], v[72:73], v[80:81] op_sel_hi:[1,0]
	v_pk_mul_f32 v[78:79], v[78:79], v[80:81] op_sel_hi:[1,0]
	v_pk_mul_f32 v[76:77], v[76:77], v[80:81] op_sel_hi:[1,0]
	v_max_f32_e32 v72, 0, v72
	v_max_f32_e32 v73, 0, v73
	v_max_f32_e32 v74, 0, v74
	v_max_f32_e32 v76, 0, v76
	v_mul_f32_e32 v81, v72, v72
	v_max_f32_e32 v72, 0, v77
	v_mul_f32_e32 v77, v73, v73
	v_max_f32_e32 v73, 0, v78
	v_mul_f32_e32 v78, v74, v74
	v_max_f32_e32 v74, 0, v79
	v_mul_f32_e32 v76, v76, v76
	v_mul_f32_e32 v72, v72, v72
	v_mul_f32_e32 v73, v73, v73
	v_mul_f32_e32 v74, v74, v74
	v_max_f32_e32 v75, 0, v75
	v_cvt_pk_bf16_f32 v72, v76, v72
	v_cvt_pk_bf16_f32 v73, v73, v74
	v_cvt_pk_bf16_f32 v74, v81, v77
	v_lshl_add_u64 v[76:77], s[14:15], 0, v[156:157]
	v_pk_mul_f32 v[64:65], v[64:65], v[80:81] op_sel_hi:[1,0]
	v_mul_f32_e32 v75, v75, v75
	v_lshl_add_u64 v[76:77], v[76:77], 0, v[168:169]
	v_pk_mul_f32 v[68:69], v[68:69], v[80:81] op_sel_hi:[1,0]
	v_max_f32_e32 v64, 0, v64
	v_cvt_pk_bf16_f32 v75, v78, v75
	global_store_dwordx4 v[76:77], v[72:75], off
	v_pk_mul_f32 v[70:71], v[70:71], v[80:81] op_sel_hi:[1,0]
	v_pk_mul_f32 v[66:67], v[66:67], v[80:81] op_sel_hi:[1,0]
	v_mul_f32_e32 v72, v64, v64
	v_max_f32_e32 v64, 0, v69
	v_max_f32_e32 v65, 0, v65
	v_mul_f32_e32 v69, v64, v64
	v_mul_f32_e32 v73, v65, v65
	v_max_f32_e32 v64, 0, v70
	v_max_f32_e32 v65, 0, v66
	v_mul_f32_e32 v66, v64, v64
	v_mul_f32_e32 v70, v65, v65
	s_waitcnt vmcnt(10)
	v_mov_b32_e32 v64, v141
	v_mov_b32_e32 v65, v142
	v_mov_b32_e32 v141, v143
	v_pk_add_f32 v[64:65], v[64:65], v[140:141]
	v_max_f32_e32 v71, 0, v71
	v_add_f32_e32 v74, v64, v65
	ds_bpermute_b32 v75, v174, v74
	v_mul_f32_e32 v65, v71, v71
	v_max_f32_e32 v67, 0, v67
	v_max_f32_e32 v68, 0, v68
	v_mul_f32_e32 v67, v67, v67
	s_waitcnt lgkmcnt(0)
	v_add_f32_e32 v71, v74, v75
	ds_bpermute_b32 v74, v175, v71
	v_mul_f32_e32 v68, v68, v68
	v_cvt_pk_bf16_f32 v64, v68, v69
	v_cvt_pk_bf16_f32 v65, v66, v65
	v_cvt_pk_bf16_f32 v66, v72, v73
	v_cvt_pk_bf16_f32 v67, v70, v67
	s_waitcnt lgkmcnt(0)
	v_add_f32_e32 v70, v71, v74
	v_fmamk_f32 v70, v70, 0x3a800000, v181
	v_mul_f32_e32 v71, 0x4b800000, v70
	v_cmp_gt_f32_e32 vcc, s41, v70
	v_lshl_add_u64 v[68:69], s[16:17], 0, v[156:157]
	v_lshl_add_u64 v[68:69], v[68:69], 0, v[168:169]
	v_cndmask_b32_e32 v70, v70, v71, vcc
	v_rsq_f32_e32 v70, v70
	global_store_dwordx4 v[68:69], v[64:67], off
	s_mov_b32 s15, s6
	s_mov_b32 s14, s8
	v_ashrrev_i32_e32 v64, 2, v170
	v_and_b32_e32 v65, 0xffffffc0, v64
	v_mul_f32_e32 v64, 0x45800000, v70
	v_cndmask_b32_e32 v64, v70, v64, vcc
	v_pk_mul_f32 v[60:61], v[60:61], v[64:65] op_sel_hi:[1,0]
	v_pk_mul_f32 v[58:59], v[58:59], v[64:65] op_sel_hi:[1,0]
	v_pk_mul_f32 v[56:57], v[56:57], v[64:65] op_sel_hi:[1,0]
	v_pk_mul_f32 v[62:63], v[62:63], v[64:65] op_sel_hi:[1,0]
	v_max_f32_e32 v60, 0, v60
	v_max_f32_e32 v56, 0, v56
	v_max_f32_e32 v58, 0, v58
	v_mul_f32_e32 v60, v60, v60
	v_mul_f32_e32 v56, v56, v56
	v_max_f32_e32 v61, 0, v61
	v_max_f32_e32 v57, 0, v57
	v_max_f32_e32 v62, 0, v62
	v_mul_f32_e32 v66, v58, v58
	v_max_f32_e32 v58, 0, v63
	v_max_f32_e32 v59, 0, v59
	v_mul_f32_e32 v61, v61, v61
	v_mul_f32_e32 v57, v57, v57
	v_mul_f32_e32 v62, v62, v62
	v_mul_f32_e32 v63, v58, v58
	v_mul_f32_e32 v67, v59, v59
	v_cvt_pk_bf16_f32 v58, v60, v61
	v_cvt_pk_bf16_f32 v59, v62, v63
	v_cvt_pk_bf16_f32 v60, v56, v57
	v_add_u32_e32 v56, s7, v65
	v_ashrrev_i32_e32 v57, 31, v56
	v_lshlrev_b64 v[56:57], 15, v[56:57]
	v_lshlrev_b32_e32 v62, 7, v170
	v_lshl_add_u64 v[56:57], s[2:3], 0, v[56:57]
	v_and_b32_e32 v156, 0x6780, v62
	v_lshl_add_u64 v[62:63], v[56:57], 0, v[156:157]
	v_pk_mul_f32 v[48:49], v[48:49], v[64:65] op_sel_hi:[1,0]
	v_lshl_add_u64 v[62:63], v[62:63], 0, v[168:169]
	v_pk_mul_f32 v[52:53], v[52:53], v[64:65] op_sel_hi:[1,0]
	v_max_f32_e32 v48, 0, v48
	v_cvt_pk_bf16_f32 v61, v66, v67
	global_store_dwordx4 v[62:63], v[58:61], off
	v_pk_mul_f32 v[54:55], v[54:55], v[64:65] op_sel_hi:[1,0]
	v_pk_mul_f32 v[50:51], v[50:51], v[64:65] op_sel_hi:[1,0]
	v_mul_f32_e32 v58, v48, v48
	v_max_f32_e32 v48, 0, v53
	v_max_f32_e32 v49, 0, v49
	v_mul_f32_e32 v53, v48, v48
	v_mul_f32_e32 v59, v49, v49
	v_max_f32_e32 v48, 0, v54
	v_max_f32_e32 v49, 0, v50
	v_mul_f32_e32 v54, v48, v48
	v_mul_f32_e32 v60, v49, v49
	v_max_f32_e32 v48, 0, v55
	v_max_f32_e32 v49, 0, v51
	v_mul_f32_e32 v51, v48, v48
	v_mul_f32_e32 v55, v49, v49
	s_waitcnt vmcnt(11)
	v_mov_b32_e32 v48, v137
	v_mov_b32_e32 v49, v138
	v_mov_b32_e32 v137, v139
	v_pk_add_f32 v[48:49], v[48:49], v[136:137]
	v_max_f32_e32 v52, 0, v52
	v_add_f32_e32 v48, v48, v49
	ds_bpermute_b32 v49, v174, v48
	v_mul_f32_e32 v52, v52, v52
	v_cvt_pk_bf16_f32 v50, v52, v53
	v_cvt_pk_bf16_f32 v51, v54, v51
	v_cvt_pk_bf16_f32 v52, v58, v59
	s_waitcnt lgkmcnt(0)
	v_add_f32_e32 v54, v48, v49
	v_cvt_pk_bf16_f32 v53, v60, v55
	ds_bpermute_b32 v55, v175, v54
	v_add_u32_e32 v48, s9, v65
	v_ashrrev_i32_e32 v49, 31, v48
	v_lshlrev_b64 v[48:49], 15, v[48:49]
	v_lshl_add_u64 v[48:49], s[2:3], 0, v[48:49]
	s_waitcnt lgkmcnt(0)
; __device__ __forceinline__ float shx(float v, int lane, int mask) { return __int_as_float(__builtin_amdgcn_ds_bpermute((lane ^ mask) << 2, __float_as_int(v))); }
; __device__ __forceinline__ unsigned cvt_pk_bf16(float lo, float hi) { unsigned r; asm volatile("v_cvt_pk_bf16_f32 %0, %1, %2" : "=v"(r) : "v"(lo), "v"(hi)); return r; }
;     __device__ __forceinline__ void operator()(const f32x4 (&acc)[2][2][4][2], const Unit& u, int wr, int wc, int fr, int fq) const {
;     ...
;             for (int m = 0; m < 4; ++m) {
;                 const int row = row0 + ai * 128 + m * 16;
;                 float ss = (sq[ai][m][0] + sq[ai][m][1]) + (sq[ai][m][2] + sq[ai][m][3]);
;                 ss += shx(ss, fq * 16 + fr, 16); ss += shx(ss, fq * 16 + fr, 32);
;                 const float rs = rsqrtf(ss * (1.0f / 1024.0f) + EPS);
; #pragma unroll
;                 for (int bj = 0; bj < 2; ++bj) {
;                     f32x4 v0 = acc[ai][bj][m][0] * rs, v1 = acc[ai][bj][m][1] * rs;
; #pragma unroll
;                     for (int j = 0; j < 4; ++j) { const float a = fmaxf(v0[j], 0.f), b = fmaxf(v1[j], 0.f); v0[j] = a * a; v1[j] = b * b; }
;                     u32x4 w; w.x = cvt_pk_bf16(v0[0], v0[1]); w.y = cvt_pk_bf16(v0[2], v0[3]); w.z = cvt_pk_bf16(v1[0], v1[1]); w.w = cvt_pk_bf16(v1[2], v1[3]);
;                     { const int col = col0 + bj * 128;
;                       *(u32x4*)(H + ((size_t)((row >> 8) * (DFF / 64) + (col >> 6)) * 256 + (row & 255)) * 64 + (col & 63)) = w; }
;                 }
	v_add_f32_e32 v54, v54, v55
	v_fmamk_f32 v54, v54, 0x3a800000, v181
	v_mul_f32_e32 v55, 0x4b800000, v54
	v_cmp_gt_f32_e32 vcc, s41, v54
	s_mov_b64 s[16:17], s[10:11]
	s_nop 0
	v_cndmask_b32_e32 v54, v54, v55, vcc
	v_rsq_f32_e32 v58, v54
	v_lshl_add_u64 v[54:55], v[48:49], 0, v[156:157]
	v_lshl_add_u64 v[54:55], v[54:55], 0, v[168:169]
	global_store_dwordx4 v[54:55], v[50:53], off
	s_nop 1
	v_mul_f32_e32 v50, 0x45800000, v58
	v_cndmask_b32_e32 v50, v58, v50, vcc
	v_pk_mul_f32 v[40:41], v[40:41], v[50:51] op_sel_hi:[1,0]
	v_pk_mul_f32 v[44:45], v[44:45], v[50:51] op_sel_hi:[1,0]
	v_pk_mul_f32 v[42:43], v[42:43], v[50:51] op_sel_hi:[1,0]
	v_max_f32_e32 v40, 0, v40
	v_pk_mul_f32 v[46:47], v[46:47], v[50:51] op_sel_hi:[1,0]
	v_mul_f32_e32 v51, v40, v40
	v_max_f32_e32 v40, 0, v45
	v_max_f32_e32 v41, 0, v41
	v_max_f32_e32 v42, 0, v42
	v_max_f32_e32 v44, 0, v44
	v_mul_f32_e32 v40, v40, v40
	v_mul_f32_e32 v45, v41, v41
	v_max_f32_e32 v41, 0, v46
	v_mul_f32_e32 v46, v42, v42
	v_max_f32_e32 v42, 0, v47
	v_max_f32_e32 v43, 0, v43
	v_pk_mul_f32 v[32:33], v[32:33], v[50:51] op_sel_hi:[1,0]
	v_mul_f32_e32 v44, v44, v44
	v_mul_f32_e32 v41, v41, v41
	v_mul_f32_e32 v42, v42, v42
	v_mul_f32_e32 v43, v43, v43
	v_cvt_pk_bf16_f32 v40, v44, v40
	v_pk_mul_f32 v[36:37], v[36:37], v[50:51] op_sel_hi:[1,0]
	v_max_f32_e32 v32, 0, v32
	v_cvt_pk_bf16_f32 v41, v41, v42
	v_cvt_pk_bf16_f32 v42, v51, v45
	v_cvt_pk_bf16_f32 v43, v46, v43
	global_store_dwordx4 v[62:63], v[40:43], off offset:2048
	v_max_f32_e32 v33, 0, v33
	v_pk_mul_f32 v[34:35], v[34:35], v[50:51] op_sel_hi:[1,0]
	v_mul_f32_e32 v40, v32, v32
	v_max_f32_e32 v32, 0, v37
	v_mul_f32_e32 v37, v32, v32
	v_mul_f32_e32 v41, v33, v33
	s_waitcnt vmcnt(12)
	v_mov_b32_e32 v32, v133
	v_mov_b32_e32 v33, v134
	v_mov_b32_e32 v133, v135
	v_pk_add_f32 v[32:33], v[32:33], v[132:133]
	v_pk_mul_f32 v[38:39], v[38:39], v[50:51] op_sel_hi:[1,0]
	v_add_f32_e32 v32, v32, v33
	ds_bpermute_b32 v33, v174, v32
	v_max_f32_e32 v34, 0, v34
	v_mul_f32_e32 v42, v34, v34
	v_max_f32_e32 v34, 0, v39
	v_max_f32_e32 v36, 0, v36
	s_waitcnt lgkmcnt(0)
	v_add_f32_e32 v39, v32, v33
	ds_bpermute_b32 v43, v175, v39
	v_mul_f32_e32 v33, v34, v34
	v_mul_f32_e32 v36, v36, v36
	v_cvt_pk_bf16_f32 v32, v36, v37
	v_max_f32_e32 v35, 0, v35
	s_waitcnt lgkmcnt(0)
	v_add_f32_e32 v34, v39, v43
	v_fmamk_f32 v34, v34, 0x3a800000, v181
	v_mul_f32_e32 v36, 0x4b800000, v34
	v_cmp_gt_f32_e32 vcc, s41, v34
	v_max_f32_e32 v38, 0, v38
	v_mul_f32_e32 v35, v35, v35
	v_cndmask_b32_e32 v34, v34, v36, vcc
	v_rsq_f32_e32 v36, v34
	v_mul_f32_e32 v38, v38, v38
	v_cvt_pk_bf16_f32 v33, v38, v33
	v_cvt_pk_bf16_f32 v34, v40, v41
	v_cvt_pk_bf16_f32 v35, v42, v35
	global_store_dwordx4 v[54:55], v[32:35], off offset:2048
	s_nop 1
	v_mul_f32_e32 v32, 0x45800000, v36
	v_cndmask_b32_e32 v32, v36, v32, vcc
	v_pk_mul_f32 v[26:27], v[26:27], v[32:33] op_sel_hi:[1,0]
	v_pk_mul_f32 v[24:25], v[24:25], v[32:33] op_sel_hi:[1,0]
	v_pk_mul_f32 v[30:31], v[30:31], v[32:33] op_sel_hi:[1,0]
	v_pk_mul_f32 v[28:29], v[28:29], v[32:33] op_sel_hi:[1,0]
	v_max_f32_e32 v24, 0, v24
	v_max_f32_e32 v25, 0, v25
	v_max_f32_e32 v26, 0, v26
	v_max_f32_e32 v28, 0, v28
	v_mul_f32_e32 v33, v24, v24
	v_max_f32_e32 v24, 0, v29
	v_mul_f32_e32 v29, v25, v25
	v_max_f32_e32 v25, 0, v30
	v_mul_f32_e32 v30, v26, v26
	v_max_f32_e32 v26, 0, v31
	v_mul_f32_e32 v28, v28, v28
	v_mul_f32_e32 v24, v24, v24
	v_mul_f32_e32 v25, v25, v25
	v_max_f32_e32 v27, 0, v27
	v_mul_f32_e32 v26, v26, v26
	v_mul_f32_e32 v27, v27, v27
	v_cvt_pk_bf16_f32 v24, v28, v24
	v_cvt_pk_bf16_f32 v25, v25, v26
	v_cvt_pk_bf16_f32 v26, v33, v29
	v_or_b32_e32 v28, 0x1000, v156
	v_mov_b32_e32 v29, v157
	v_cvt_pk_bf16_f32 v27, v30, v27
	v_lshl_add_u64 v[30:31], v[56:57], 0, v[28:29]
	v_pk_mul_f32 v[16:17], v[16:17], v[32:33] op_sel_hi:[1,0]
	v_lshl_add_u64 v[30:31], v[30:31], 0, v[168:169]
	v_pk_mul_f32 v[20:21], v[20:21], v[32:33] op_sel_hi:[1,0]
	v_max_f32_e32 v16, 0, v16
	global_store_dwordx4 v[30:31], v[24:27], off
	v_pk_mul_f32 v[22:23], v[22:23], v[32:33] op_sel_hi:[1,0]
	v_pk_mul_f32 v[18:19], v[18:19], v[32:33] op_sel_hi:[1,0]
	v_mul_f32_e32 v24, v16, v16
	v_max_f32_e32 v16, 0, v21
	v_max_f32_e32 v17, 0, v17
	v_mul_f32_e32 v21, v16, v16
	v_mul_f32_e32 v25, v17, v17
	v_max_f32_e32 v16, 0, v22
	v_max_f32_e32 v17, 0, v18
	v_mul_f32_e32 v18, v16, v16
	v_mul_f32_e32 v22, v17, v17
	s_waitcnt vmcnt(13)
; __device__ __forceinline__ float shx(float v, int lane, int mask) { return __int_as_float(__builtin_amdgcn_ds_bpermute((lane ^ mask) << 2, __float_as_int(v))); }
; __device__ __forceinline__ unsigned cvt_pk_bf16(float lo, float hi) { unsigned r; asm volatile("v_cvt_pk_bf16_f32 %0, %1, %2" : "=v"(r) : "v"(lo), "v"(hi)); return r; }
; #define PG8_WAIT_V(n) asm volatile("s_waitcnt vmcnt(" #n ")" ::: "memory")
; #define PG8_BAR __builtin_amdgcn_s_barrier()
; template <class Epi, class Sched>
; __device__ __forceinline__ void gemm_phase(const int wv, LAS unsigned char* lds, const Gemm g, const Sched& S, const Epi& E) {
;     ...
;         E(acc, cur, wr, wc, fr, fq); S.done(cur);
;         if (!has_next) break;
; #pragma unroll
;         for (int a = 0; a < 2; ++a)
; #pragma unroll
;             for (int b = 0; b < 2; ++b)
; #pragma unroll
;                 for (int m = 0; m < 4; ++m)
; #pragma unroll
;                     for (int n = 0; n < 2; ++n) acc[a][b][m][n] = (f32x4){0.f, 0.f, 0.f, 0.f};
;         cur = nxt; cA = nA; cB = nB; ++ui;
;     }
;     PG8_WAIT_V(0);
;     if (wr == 0) PG8_BAR;
;     __device__ __forceinline__ void operator()(const f32x4 (&acc)[2][2][4][2], const Unit& u, int wr, int wc, int fr, int fq) const {
;     ...
;             for (int m = 0; m < 4; ++m) {
;                 const int row = row0 + ai * 128 + m * 16;
;                 float ss = (sq[ai][m][0] + sq[ai][m][1]) + (sq[ai][m][2] + sq[ai][m][3]);
;                 ss += shx(ss, fq * 16 + fr, 16); ss += shx(ss, fq * 16 + fr, 32);
;                 const float rs = rsqrtf(ss * (1.0f / 1024.0f) + EPS);
; #pragma unroll
;                 for (int bj = 0; bj < 2; ++bj) {
;                     f32x4 v0 = acc[ai][bj][m][0] * rs, v1 = acc[ai][bj][m][1] * rs;
; #pragma unroll
;                     for (int j = 0; j < 4; ++j) { const float a = fmaxf(v0[j], 0.f), b = fmaxf(v1[j], 0.f); v0[j] = a * a; v1[j] = b * b; }
;                     u32x4 w; w.x = cvt_pk_bf16(v0[0], v0[1]); w.y = cvt_pk_bf16(v0[2], v0[3]); w.z = cvt_pk_bf16(v1[0], v1[1]); w.w = cvt_pk_bf16(v1[2], v1[3]);
;                     { const int col = col0 + bj * 128;
;                       *(u32x4*)(H + ((size_t)((row >> 8) * (DFF / 64) + (col >> 6)) * 256 + (row & 255)) * 64 + (col & 63)) = w; }
;                 }
	v_mov_b32_e32 v16, v129
	v_mov_b32_e32 v17, v130
	v_mov_b32_e32 v129, v131
	v_pk_add_f32 v[16:17], v[16:17], v[128:129]
	v_max_f32_e32 v20, 0, v20
	v_add_f32_e32 v16, v16, v17
	ds_bpermute_b32 v17, v174, v16
	v_mul_f32_e32 v20, v20, v20
	v_max_f32_e32 v19, 0, v19
	v_max_f32_e32 v23, 0, v23
	v_mul_f32_e32 v19, v19, v19
	s_waitcnt lgkmcnt(0)
	v_add_f32_e32 v26, v16, v17
	ds_bpermute_b32 v27, v175, v26
	v_cvt_pk_bf16_f32 v16, v20, v21
	v_mul_f32_e32 v23, v23, v23
	v_cvt_pk_bf16_f32 v17, v18, v23
	v_cvt_pk_bf16_f32 v18, v24, v25
	s_waitcnt lgkmcnt(0)
	v_add_f32_e32 v20, v26, v27
	v_fmamk_f32 v20, v20, 0x3a800000, v181
	v_mul_f32_e32 v21, 0x4b800000, v20
	v_cmp_gt_f32_e32 vcc, s41, v20
	v_cvt_pk_bf16_f32 v19, v22, v19
	v_or_b32_e32 v156, 0x1800, v156
	s_nop 0
	v_cndmask_b32_e32 v20, v20, v21, vcc
	v_rsq_f32_e32 v22, v20
	v_lshl_add_u64 v[20:21], v[48:49], 0, v[28:29]
	v_lshl_add_u64 v[20:21], v[20:21], 0, v[168:169]
	global_store_dwordx4 v[20:21], v[16:19], off
	s_nop 1
	v_mul_f32_e32 v16, 0x45800000, v22
	v_cndmask_b32_e32 v16, v22, v16, vcc
	v_pk_mul_f32 v[10:11], v[10:11], v[16:17] op_sel_hi:[1,0]
	v_pk_mul_f32 v[8:9], v[8:9], v[16:17] op_sel_hi:[1,0]
	v_pk_mul_f32 v[14:15], v[14:15], v[16:17] op_sel_hi:[1,0]
	v_pk_mul_f32 v[12:13], v[12:13], v[16:17] op_sel_hi:[1,0]
	v_max_f32_e32 v8, 0, v8
	v_max_f32_e32 v9, 0, v9
	v_max_f32_e32 v10, 0, v10
	v_max_f32_e32 v12, 0, v12
	v_mul_f32_e32 v17, v8, v8
	v_max_f32_e32 v8, 0, v13
	v_mul_f32_e32 v13, v9, v9
	v_max_f32_e32 v9, 0, v14
	v_mul_f32_e32 v14, v10, v10
	v_max_f32_e32 v10, 0, v15
	v_mul_f32_e32 v12, v12, v12
	v_mul_f32_e32 v8, v8, v8
	v_mul_f32_e32 v9, v9, v9
	v_mul_f32_e32 v10, v10, v10
	v_max_f32_e32 v11, 0, v11
	v_cvt_pk_bf16_f32 v8, v12, v8
	v_cvt_pk_bf16_f32 v9, v9, v10
	v_cvt_pk_bf16_f32 v10, v17, v13
	v_lshl_add_u64 v[12:13], v[56:57], 0, v[156:157]
	v_pk_mul_f32 v[2:3], v[2:3], v[16:17] op_sel_hi:[1,0]
	v_pk_mul_f32 v[0:1], v[0:1], v[16:17] op_sel_hi:[1,0]
	v_mul_f32_e32 v11, v11, v11
	v_lshl_add_u64 v[12:13], v[12:13], 0, v[168:169]
	v_pk_mul_f32 v[6:7], v[6:7], v[16:17] op_sel_hi:[1,0]
	v_pk_mul_f32 v[4:5], v[4:5], v[16:17] op_sel_hi:[1,0]
	v_max_f32_e32 v0, 0, v0
	v_max_f32_e32 v1, 0, v1
	v_max_f32_e32 v2, 0, v2
	v_cvt_pk_bf16_f32 v11, v14, v11
	global_store_dwordx4 v[12:13], v[8:11], off
	v_max_f32_e32 v4, 0, v4
	v_mul_f32_e32 v4, v4, v4
	v_mul_f32_e32 v8, v0, v0
	v_max_f32_e32 v0, 0, v5
	v_mul_f32_e32 v5, v1, v1
	v_max_f32_e32 v1, 0, v6
	v_mul_f32_e32 v6, v2, v2
	v_max_f32_e32 v2, 0, v7
	v_mul_f32_e32 v0, v0, v0
	v_mul_f32_e32 v1, v1, v1
	v_mul_f32_e32 v2, v2, v2
	v_max_f32_e32 v3, 0, v3
	v_cvt_pk_bf16_f32 v0, v4, v0
	v_cvt_pk_bf16_f32 v1, v1, v2
	v_cvt_pk_bf16_f32 v2, v8, v5
	v_lshl_add_u64 v[4:5], v[48:49], 0, v[156:157]
	v_mul_f32_e32 v3, v3, v3
	v_lshl_add_u64 v[4:5], v[4:5], 0, v[168:169]
	s_and_b64 vcc, exec, s[0:1]
	v_cvt_pk_bf16_f32 v3, v6, v3
	global_store_dwordx4 v[4:5], v[0:3], off
	s_cbranch_vccz .LBB0_718
	s_waitcnt vmcnt(0)
	s_cmpk_gt_u32 s22, 0xff
	s_cbranch_scc1 .LBB0_729
	s_barrier

; #define PG8_STAGE(bufoff, gbase, voff) do { _Pragma("unroll") for (int _i = 0; _i < 2; ++_i) \
;         __builtin_amdgcn_global_load_lds((const unsigned*)((const char*)(gbase) + (voff)[_i]), (LAS unsigned*)(lds + (bufoff) + ldsw + _i * 8192), 16, 0, 0); } while (0)
; #define PG8_WAIT_V(n) asm volatile("s_waitcnt vmcnt(" #n ")" ::: "memory")
; #define PG8_BAR __builtin_amdgcn_s_barrier()
; template <class Epi, class Sched>
; __device__ __forceinline__ void gemm_phase(const int wv, LAS unsigned char* lds, const Gemm g, const Sched& S, const Epi& E) {
;     ...
;     const char* cA = (const char*)g.A + (size_t)cur.pm * tstepA; const char* cB = (const char*)g.Bt + (size_t)cur.pn * tstepB;
;     S.a_ready(cur);
;     PG8_STAGE(PG8_SB(0, 0), cB, voffB); PG8_STAGE(PG8_SA(0, 0), cA, voffA); PG8_STAGE(PG8_SB(0, 1), cB + hstepB, voffB); PG8_STAGE(PG8_SA(0, 1), cA + hstepA, voffA);
;     if (wr == 1) PG8_BAR;
;     PG8_WAIT_V(4); PG8_BAR;
;     PG8_STAGE(PG8_SB(1, 0), cB + kstep, voffB); PG8_STAGE(PG8_SA(1, 0), cA + kstepA, voffA); PG8_STAGE(PG8_SB(1, 1), cB + hstepB + kstep, voffB);
;     PG8_WAIT_V(6); PG8_BAR;
;     for (;;) {
;         const bool has_next = S.next(ui + 1, nxt);
;         const char* nA = has_next ? (const char*)g.A + (size_t)nxt.pm * tstepA : cA; const char* nB = has_next ? (const char*)g.Bt + (size_t)nxt.pn * tstepB : cB;
;         for (int t = 0; t < nt; t += 2) {
;             const bool last = (t == nt - 2);
;             const char* a1 = cA + (size_t)(t + 1) * kstepA;
;             const char* a2 = last ? nA : cA + (size_t)(t + 2) * kstepA; const char* b2 = last ? nB : cB + (size_t)(t + 2) * kstep;
;             const char* a3 = a2 + kstepA; const char* b3 = b2 + kstep;
;             if (last && has_next) S.a_ready(nxt);
;             PG8_LDB(B0, 0, 0); PG8_SCHED; PG8_LDA(At, 0, 0); PG8_STAGE(PG8_SA(1, 1), a1 + hstepA, voffA);
;             PG8_WAIT_L(8); PG8_BAR; PG8_WAIT_L(0); PG8_MMA(0, 0, At, B0); PG8_BAR; PG8_SCHED;
;             PG8_LDB(B1, 0, 1); PG8_STAGE(PG8_SB(0, 0), b2, voffB);
;             PG8_BAR; PG8_WAIT_L(0); PG8_MMA(0, 1, At, B1); PG8_BAR;
;             PG8_LDA(At, 0, 1); PG8_STAGE(PG8_SA(0, 0), a2, voffA);
;             PG8_BAR; PG8_WAIT_L(0); PG8_MMA(1, 0, At, B0); PG8_BAR; PG8_SCHED;
;             PG8_STAGE(PG8_SB(0, 1), b2 + hstepB, voffB);
;             PG8_WAIT_V(6); PG8_BAR; PG8_MMA(1, 1, At, B1); PG8_BAR;
.LBB0_788:
	s_sub_i32 s10, 0x7f, s10
	s_ashr_i32 s11, s10, 31
	v_cmp_lt_i64_e32 vcc, s[12:13], v[140:141]
	s_lshl_b64 s[12:13], s[10:11], 21
	s_add_u32 s12, s27, s12
	s_addc_u32 s13, s28, s13
	s_and_b64 s[14:15], vcc, exec
	s_cselect_b32 s11, s13, s21
	s_cselect_b32 s42, s12, s20
	s_ashr_i32 s9, s8, 31
	s_lshl_b64 s[14:15], s[8:9], 21
	s_add_u32 s14, s29, s14
	s_addc_u32 s15, s30, s15
	s_and_b64 s[22:23], vcc, exec
	s_cselect_b32 s9, s15, s19
	s_cselect_b32 s43, s14, s18
	s_add_u32 s44, s18, 0x100
	s_addc_u32 s45, s19, 0
	s_add_u32 s18, s20, 0xc000
	s_addc_u32 s19, s21, 0
	s_mov_b32 s46, -2
	ds_read_b128 v[144:147], v199
	ds_read_b128 v[148:151], v199 offset:1024
	ds_read_b128 v[152:155], v199 offset:2048
	ds_read_b128 v[156:159], v199 offset:3072
	s_add_u32 s20, s18, 0x4000
	s_addc_u32 s21, s19, 0
	s_cmp_eq_u32 s46, 60
	s_cselect_b32 s24, s42, s20
	s_cselect_b32 s25, s11, s21
	s_cselect_b32 s20, s43, s44
	s_cselect_b32 s21, s9, s45
	s_add_u32 s22, s24, 0x8000
	s_addc_u32 s23, s25, 0
	v_lshl_add_u64 v[192:193], s[18:19], 0, v[136:137]
	s_add_i32 m0, s17, 0xc000
	ds_read_b128 v[160:163], v200
	ds_read_b128 v[164:167], v200 offset:1024
	ds_read_b128 v[168:171], v200 offset:2048
	ds_read_b128 v[172:175], v200 offset:3072
	ds_read_b128 v[176:179], v200 offset:4096
	ds_read_b128 v[180:183], v200 offset:5120
	ds_read_b128 v[184:187], v200 offset:6144
	ds_read_b128 v[188:191], v200 offset:7168
	global_load_lds_dwordx4 v[192:193], off
	v_lshl_add_u64 v[192:193], s[18:19], 0, v[138:139]
	s_add_i32 m0, s17, 0xe000
	s_nop 0
	global_load_lds_dwordx4 v[192:193], off
	s_waitcnt lgkmcnt(8)
	s_barrier
	s_waitcnt lgkmcnt(0)
	s_setprio 1
	s_waitcnt lgkmcnt(0)
	v_mfma_f32_16x16x32_bf16 v[124:127], v[144:147], v[160:163], 0
	v_mfma_f32_16x16x32_bf16 v[120:123], v[152:155], v[160:163], 0
	v_mfma_f32_16x16x32_bf16 v[112:115], v[144:147], v[168:171], 0
	v_mfma_f32_16x16x32_bf16 v[104:107], v[152:155], v[168:171], 0
	v_mfma_f32_16x16x32_bf16 v[96:99], v[144:147], v[176:179], 0
	v_mfma_f32_16x16x32_bf16 v[88:91], v[152:155], v[176:179], 0
	v_mfma_f32_16x16x32_bf16 v[80:83], v[144:147], v[184:187], 0
	v_mfma_f32_16x16x32_bf16 v[72:75], v[152:155], v[184:187], 0
	v_mfma_f32_16x16x32_bf16 v[124:127], v[148:151], v[164:167], v[124:127]
	v_mfma_f32_16x16x32_bf16 v[120:123], v[156:159], v[164:167], v[120:123]
	v_mfma_f32_16x16x32_bf16 v[112:115], v[148:151], v[172:175], v[112:115]
	v_mfma_f32_16x16x32_bf16 v[104:107], v[156:159], v[172:175], v[104:107]
	v_mfma_f32_16x16x32_bf16 v[96:99], v[148:151], v[180:183], v[96:99]
	v_mfma_f32_16x16x32_bf16 v[88:91], v[156:159], v[180:183], v[88:91]
	v_mfma_f32_16x16x32_bf16 v[80:83], v[148:151], v[188:191], v[80:83]
	v_mfma_f32_16x16x32_bf16 v[72:75], v[156:159], v[188:191], v[72:75]
	s_setprio 0
	s_barrier
	s_add_i32 s47, s39, s31
	v_lshl_add_u64 v[214:215], s[20:21], 0, v[130:131]
	s_mov_b32 m0, s47
	ds_read_b128 v[192:195], v201
	ds_read_b128 v[202:205], v201 offset:1024
	ds_read_b128 v[206:209], v201 offset:2048
	ds_read_b128 v[210:213], v201 offset:3072
	global_load_lds_dwordx4 v[214:215], off
	v_lshl_add_u64 v[216:217], s[20:21], 0, v[134:135]
	s_add_i32 m0, s47, 0x2000
	s_nop 0
	global_load_lds_dwordx4 v[216:217], off
	s_barrier
	s_waitcnt lgkmcnt(0)
	s_setprio 1
	s_waitcnt lgkmcnt(0)
	v_mfma_f32_16x16x32_bf16 v[116:119], v[192:195], v[160:163], 0
	v_mfma_f32_16x16x32_bf16 v[108:111], v[206:209], v[160:163], 0
	v_mfma_f32_16x16x32_bf16 v[100:103], v[192:195], v[168:171], 0
	v_mfma_f32_16x16x32_bf16 v[92:95], v[206:209], v[168:171], 0
	v_mfma_f32_16x16x32_bf16 v[84:87], v[192:195], v[176:179], 0
	v_mfma_f32_16x16x32_bf16 v[76:79], v[206:209], v[176:179], 0
	v_mfma_f32_16x16x32_bf16 v[68:71], v[192:195], v[184:187], 0
	v_mfma_f32_16x16x32_bf16 v[64:67], v[206:209], v[184:187], 0
	v_mfma_f32_16x16x32_bf16 v[116:119], v[202:205], v[164:167], v[116:119]
	v_mfma_f32_16x16x32_bf16 v[108:111], v[210:213], v[164:167], v[108:111]
	v_mfma_f32_16x16x32_bf16 v[100:103], v[202:205], v[172:175], v[100:103]
	v_mfma_f32_16x16x32_bf16 v[92:95], v[210:213], v[172:175], v[92:95]
	v_mfma_f32_16x16x32_bf16 v[84:87], v[202:205], v[180:183], v[84:87]
	v_mfma_f32_16x16x32_bf16 v[76:79], v[210:213], v[180:183], v[76:79]
	v_mfma_f32_16x16x32_bf16 v[68:71], v[202:205], v[188:191], v[68:71]
	v_mfma_f32_16x16x32_bf16 v[64:67], v[210:213], v[188:191], v[64:67]
	s_setprio 0
	s_mov_b32 m0, s17
	v_lshl_add_u64 v[218:219], s[24:25], 0, v[128:129]
	s_barrier
	ds_read_b128 v[160:163], v200 offset:16384
	ds_read_b128 v[164:167], v200 offset:17408
	ds_read_b128 v[168:171], v200 offset:18432
	ds_read_b128 v[172:175], v200 offset:19456
	ds_read_b128 v[176:179], v200 offset:20480
	ds_read_b128 v[180:183], v200 offset:21504
	ds_read_b128 v[184:187], v200 offset:22528
	ds_read_b128 v[188:191], v200 offset:23552
	global_load_lds_dwordx4 v[218:219], off
	v_lshl_add_u64 v[218:219], s[24:25], 0, v[132:133]
	s_mov_b32 m0, s33
	s_nop 0
	global_load_lds_dwordx4 v[218:219], off
	s_barrier
	s_waitcnt lgkmcnt(0)
	s_setprio 1
	s_waitcnt lgkmcnt(0)
	v_mfma_f32_16x16x32_bf16 v[60:63], v[144:147], v[160:163], 0
	v_mfma_f32_16x16x32_bf16 v[56:59], v[152:155], v[160:163], 0
	v_mfma_f32_16x16x32_bf16 v[48:51], v[144:147], v[168:171], 0
	v_mfma_f32_16x16x32_bf16 v[40:43], v[152:155], v[168:171], 0
	v_mfma_f32_16x16x32_bf16 v[32:35], v[144:147], v[176:179], 0
	v_mfma_f32_16x16x32_bf16 v[24:27], v[152:155], v[176:179], 0
	v_mfma_f32_16x16x32_bf16 v[16:19], v[144:147], v[184:187], 0
	v_mfma_f32_16x16x32_bf16 v[8:11], v[152:155], v[184:187], 0
	v_mfma_f32_16x16x32_bf16 v[60:63], v[148:151], v[164:167], v[60:63]
	v_mfma_f32_16x16x32_bf16 v[56:59], v[156:159], v[164:167], v[56:59]
	v_mfma_f32_16x16x32_bf16 v[48:51], v[148:151], v[172:175], v[48:51]
	v_mfma_f32_16x16x32_bf16 v[40:43], v[156:159], v[172:175], v[40:43]
	v_mfma_f32_16x16x32_bf16 v[32:35], v[148:151], v[180:183], v[32:35]
	v_mfma_f32_16x16x32_bf16 v[24:27], v[156:159], v[180:183], v[24:27]
	v_mfma_f32_16x16x32_bf16 v[16:19], v[148:151], v[188:191], v[16:19]
	v_mfma_f32_16x16x32_bf16 v[8:11], v[156:159], v[188:191], v[8:11]
	s_setprio 0
	s_barrier
; #define PG8_STAGE(bufoff, gbase, voff) do { _Pragma("unroll") for (int _i = 0; _i < 2; ++_i) \
;         __builtin_amdgcn_global_load_lds((const unsigned*)((const char*)(gbase) + (voff)[_i]), (LAS unsigned*)(lds + (bufoff) + ldsw + _i * 8192), 16, 0, 0); } while (0)
; #define PG8_LDA(dst, b, h) do { _Pragma("unroll") for (int m = 0; m < 4; ++m) _Pragma("unroll") for (int k = 0; k < 2; ++k) dst[m][k] = *(const LAS bf16x8*)(lds + PG8_SA(b, h) + aoff + m * 2048 + k * 1024); } while (0)
; #define PG8_LDB(dst, b, h) do { _Pragma("unroll") for (int n = 0; n < 2; ++n) _Pragma("unroll") for (int k = 0; k < 2; ++k) dst[n][k] = *(const LAS bf16x8*)(lds + PG8_SB(b, h) + boff + n * 2048 + k * 1024); } while (0)
; #define PG8_MMA(ai, bj, At, Bt) do { __builtin_amdgcn_s_setprio(1); _Pragma("unroll") for (int m = 0; m < 4; ++m) _Pragma("unroll") for (int n = 0; n < 2; ++n) _Pragma("unroll") for (int k = 0; k < 2; ++k) \
;         acc[ai][bj][m][n] = __builtin_amdgcn_mfma_f32_16x16x32_bf16(Bt[n][k], At[m][k], acc[ai][bj][m][n], 0, 0, 0); __builtin_amdgcn_s_setprio(0); } while (0)
; #define PG8_WAIT_V(n) asm volatile("s_waitcnt vmcnt(" #n ")" ::: "memory")
; #define PG8_WAIT_L(n) asm volatile("s_waitcnt lgkmcnt(" #n ")" ::: "memory")
; #define PG8_BAR __builtin_amdgcn_s_barrier()
; #define PG8_SCHED __builtin_amdgcn_sched_barrier(0)
; template <class Epi, class Sched>
; __device__ __forceinline__ void gemm_phase(const int wv, LAS unsigned char* lds, const Gemm g, const Sched& S, const Epi& E) {
;     ...
;             PG8_STAGE(PG8_SB(0, 1), b2 + hstepB, voffB);
;             PG8_WAIT_V(6); PG8_BAR; PG8_MMA(1, 1, At, B1); PG8_BAR;
;             PG8_LDB(B0, 1, 0); PG8_SCHED; PG8_LDA(At, 1, 0); PG8_STAGE(PG8_SA(0, 1), a2 + hstepA, voffA);
;             PG8_WAIT_L(8); PG8_BAR; PG8_WAIT_L(0); PG8_MMA(0, 0, At, B0); PG8_BAR; PG8_SCHED;
;             PG8_LDB(B1, 1, 1); PG8_STAGE(PG8_SB(1, 0), b3, voffB);
;             PG8_BAR; PG8_WAIT_L(0); PG8_MMA(0, 1, At, B1); PG8_BAR;
;             PG8_LDA(At, 1, 1); PG8_STAGE(PG8_SA(1, 0), a3, voffA);
;             PG8_BAR; PG8_WAIT_L(0); PG8_MMA(1, 0, At, B0); PG8_BAR; PG8_SCHED;
	s_add_u32 s48, s20, 0x100000
	s_addc_u32 s49, s21, 0
	s_add_i32 s47, s40, s31
	v_lshl_add_u64 v[144:145], s[48:49], 0, v[130:131]
	s_mov_b32 m0, s47
	s_nop 0
	global_load_lds_dwordx4 v[144:145], off
	v_lshl_add_u64 v[144:145], s[48:49], 0, v[134:135]
	s_add_i32 m0, s47, 0x2000
	s_nop 0
	global_load_lds_dwordx4 v[144:145], off
	s_waitcnt vmcnt(6)
	s_barrier
	s_setprio 1
	v_mfma_f32_16x16x32_bf16 v[52:55], v[192:195], v[160:163], 0
	v_mfma_f32_16x16x32_bf16 v[44:47], v[206:209], v[160:163], 0
	v_mfma_f32_16x16x32_bf16 v[36:39], v[192:195], v[168:171], 0
	v_mfma_f32_16x16x32_bf16 v[28:31], v[206:209], v[168:171], 0
	v_mfma_f32_16x16x32_bf16 v[20:23], v[192:195], v[176:179], 0
	v_mfma_f32_16x16x32_bf16 v[12:15], v[206:209], v[176:179], 0
	v_mfma_f32_16x16x32_bf16 v[4:7], v[192:195], v[184:187], 0
	v_mfma_f32_16x16x32_bf16 v[0:3], v[206:209], v[184:187], 0
	v_mfma_f32_16x16x32_bf16 v[52:55], v[202:205], v[164:167], v[52:55]
	v_mfma_f32_16x16x32_bf16 v[44:47], v[210:213], v[164:167], v[44:47]
	v_mfma_f32_16x16x32_bf16 v[36:39], v[202:205], v[172:175], v[36:39]
	v_mfma_f32_16x16x32_bf16 v[28:31], v[210:213], v[172:175], v[28:31]
	v_mfma_f32_16x16x32_bf16 v[20:23], v[202:205], v[180:183], v[20:23]
	v_mfma_f32_16x16x32_bf16 v[12:15], v[210:213], v[180:183], v[12:15]
	v_mfma_f32_16x16x32_bf16 v[4:7], v[202:205], v[188:191], v[4:7]
	v_mfma_f32_16x16x32_bf16 v[0:3], v[210:213], v[188:191], v[0:3]
	s_setprio 0
	s_add_i32 s47, 0, 0x18000
	v_add_u32_e32 v156, s47, v197
	s_barrier
	ds_read_b128 v[144:147], v156
	ds_read_b128 v[148:151], v156 offset:1024
	ds_read_b128 v[152:155], v156 offset:2048
	ds_read_b128 v[156:159], v156 offset:3072
	s_add_u32 s24, s24, 0x4000
	s_addc_u32 s25, s25, 0
	s_mov_b32 m0, s34
	v_lshl_add_u64 v[192:193], s[24:25], 0, v[128:129]
	ds_read_b128 v[160:163], v200 offset:32768
	ds_read_b128 v[164:167], v200 offset:33792
	ds_read_b128 v[168:171], v200 offset:34816
	ds_read_b128 v[172:175], v200 offset:35840
	ds_read_b128 v[176:179], v200 offset:36864
	ds_read_b128 v[180:183], v200 offset:37888
	ds_read_b128 v[184:187], v200 offset:38912
	ds_read_b128 v[188:191], v200 offset:39936
	global_load_lds_dwordx4 v[192:193], off
	v_lshl_add_u64 v[192:193], s[24:25], 0, v[132:133]
	s_mov_b32 m0, s35
	s_nop 0
	global_load_lds_dwordx4 v[192:193], off
	s_waitcnt lgkmcnt(8)
	s_barrier
	s_waitcnt lgkmcnt(0)
	s_setprio 1
	s_waitcnt lgkmcnt(0)
	v_mfma_f32_16x16x32_bf16 v[124:127], v[144:147], v[160:163], v[124:127]
	v_mfma_f32_16x16x32_bf16 v[120:123], v[152:155], v[160:163], v[120:123]
	v_mfma_f32_16x16x32_bf16 v[112:115], v[144:147], v[168:171], v[112:115]
	v_mfma_f32_16x16x32_bf16 v[104:107], v[152:155], v[168:171], v[104:107]
	v_mfma_f32_16x16x32_bf16 v[96:99], v[144:147], v[176:179], v[96:99]
	v_mfma_f32_16x16x32_bf16 v[88:91], v[152:155], v[176:179], v[88:91]
	v_mfma_f32_16x16x32_bf16 v[80:83], v[144:147], v[184:187], v[80:83]
	v_mfma_f32_16x16x32_bf16 v[72:75], v[152:155], v[184:187], v[72:75]
	v_mfma_f32_16x16x32_bf16 v[124:127], v[148:151], v[164:167], v[124:127]
	v_mfma_f32_16x16x32_bf16 v[120:123], v[156:159], v[164:167], v[120:123]
	v_mfma_f32_16x16x32_bf16 v[112:115], v[148:151], v[172:175], v[112:115]
	v_mfma_f32_16x16x32_bf16 v[104:107], v[156:159], v[172:175], v[104:107]
	v_mfma_f32_16x16x32_bf16 v[96:99], v[148:151], v[180:183], v[96:99]
	v_mfma_f32_16x16x32_bf16 v[88:91], v[156:159], v[180:183], v[88:91]
	v_mfma_f32_16x16x32_bf16 v[80:83], v[148:151], v[188:191], v[80:83]
	v_mfma_f32_16x16x32_bf16 v[72:75], v[156:159], v[188:191], v[72:75]
	s_setprio 0
	s_barrier
	s_add_i32 s24, 0, 0x1c000
	s_add_i32 s25, s47, s31
	v_add_u32_e32 v210, s24, v197
	v_lshl_add_u64 v[214:215], v[214:215], 0, s[6:7]
	s_mov_b32 m0, s25
	ds_read_b128 v[192:195], v210
	ds_read_b128 v[202:205], v210 offset:1024
	ds_read_b128 v[206:209], v210 offset:2048
	ds_read_b128 v[210:213], v210 offset:3072
	global_load_lds_dwordx4 v[214:215], off
	v_lshl_add_u64 v[214:215], v[216:217], 0, s[6:7]
	s_add_i32 m0, s25, 0x2000
	s_nop 0
	global_load_lds_dwordx4 v[214:215], off
	s_barrier
; #define PG8_STAGE(bufoff, gbase, voff) do { _Pragma("unroll") for (int _i = 0; _i < 2; ++_i) \
;         __builtin_amdgcn_global_load_lds((const unsigned*)((const char*)(gbase) + (voff)[_i]), (LAS unsigned*)(lds + (bufoff) + ldsw + _i * 8192), 16, 0, 0); } while (0)
; #define PG8_LDA(dst, b, h) do { _Pragma("unroll") for (int m = 0; m < 4; ++m) _Pragma("unroll") for (int k = 0; k < 2; ++k) dst[m][k] = *(const LAS bf16x8*)(lds + PG8_SA(b, h) + aoff + m * 2048 + k * 1024); } while (0)
; #define PG8_MMA(ai, bj, At, Bt) do { __builtin_amdgcn_s_setprio(1); _Pragma("unroll") for (int m = 0; m < 4; ++m) _Pragma("unroll") for (int n = 0; n < 2; ++n) _Pragma("unroll") for (int k = 0; k < 2; ++k) \
;         acc[ai][bj][m][n] = __builtin_amdgcn_mfma_f32_16x16x32_bf16(Bt[n][k], At[m][k], acc[ai][bj][m][n], 0, 0, 0); __builtin_amdgcn_s_setprio(0); } while (0)
; #define PG8_WAIT_V(n) asm volatile("s_waitcnt vmcnt(" #n ")" ::: "memory")
; #define PG8_WAIT_L(n) asm volatile("s_waitcnt lgkmcnt(" #n ")" ::: "memory")
; #define PG8_BAR __builtin_amdgcn_s_barrier()
; #define PG8_SCHED __builtin_amdgcn_sched_barrier(0)
; template <class Epi, class Sched>
; __device__ __forceinline__ void gemm_phase(const int wv, LAS unsigned char* lds, const Gemm g, const Sched& S, const Epi& E) {
;     ...
;             PG8_LDA(At, 1, 1); PG8_STAGE(PG8_SA(1, 0), a3, voffA);
;             PG8_BAR; PG8_WAIT_L(0); PG8_MMA(1, 0, At, B0); PG8_BAR; PG8_SCHED;
;             PG8_STAGE(PG8_SB(1, 1), b3 + hstepB, voffB);
;             PG8_WAIT_V(6); PG8_BAR; PG8_MMA(1, 1, At, B1); PG8_BAR;
;         }
	s_waitcnt lgkmcnt(0)
	s_setprio 1
	s_waitcnt lgkmcnt(0)
	v_mfma_f32_16x16x32_bf16 v[116:119], v[192:195], v[160:163], v[116:119]
	v_mfma_f32_16x16x32_bf16 v[108:111], v[206:209], v[160:163], v[108:111]
	v_mfma_f32_16x16x32_bf16 v[100:103], v[192:195], v[168:171], v[100:103]
	v_mfma_f32_16x16x32_bf16 v[92:95], v[206:209], v[168:171], v[92:95]
	v_mfma_f32_16x16x32_bf16 v[84:87], v[192:195], v[176:179], v[84:87]
	v_mfma_f32_16x16x32_bf16 v[76:79], v[206:209], v[176:179], v[76:79]
	v_mfma_f32_16x16x32_bf16 v[68:71], v[192:195], v[184:187], v[68:71]
	v_mfma_f32_16x16x32_bf16 v[64:67], v[206:209], v[184:187], v[64:67]
	v_mfma_f32_16x16x32_bf16 v[116:119], v[202:205], v[164:167], v[116:119]
	v_mfma_f32_16x16x32_bf16 v[108:111], v[210:213], v[164:167], v[108:111]
	v_mfma_f32_16x16x32_bf16 v[100:103], v[202:205], v[172:175], v[100:103]
	v_mfma_f32_16x16x32_bf16 v[92:95], v[210:213], v[172:175], v[92:95]
	v_mfma_f32_16x16x32_bf16 v[84:87], v[202:205], v[180:183], v[84:87]
	v_mfma_f32_16x16x32_bf16 v[76:79], v[210:213], v[180:183], v[76:79]
	v_mfma_f32_16x16x32_bf16 v[68:71], v[202:205], v[188:191], v[68:71]
	v_mfma_f32_16x16x32_bf16 v[64:67], v[210:213], v[188:191], v[64:67]
	s_setprio 0
	s_mov_b32 m0, s37
	v_lshl_add_u64 v[214:215], s[22:23], 0, v[128:129]
	s_barrier
	ds_read_b128 v[160:163], v200 offset:49152
	ds_read_b128 v[164:167], v200 offset:50176
	ds_read_b128 v[168:171], v200 offset:51200
	ds_read_b128 v[172:175], v200 offset:52224
	ds_read_b128 v[176:179], v200 offset:53248
	ds_read_b128 v[180:183], v200 offset:54272
	ds_read_b128 v[184:187], v200 offset:55296
	ds_read_b128 v[188:191], v200 offset:56320
	global_load_lds_dwordx4 v[214:215], off
	v_lshl_add_u64 v[214:215], s[22:23], 0, v[132:133]
	s_mov_b32 m0, s38
	s_nop 0
	global_load_lds_dwordx4 v[214:215], off
	s_barrier
	s_waitcnt lgkmcnt(0)
	s_setprio 1
	s_waitcnt lgkmcnt(0)
	v_mfma_f32_16x16x32_bf16 v[60:63], v[144:147], v[160:163], v[60:63]
	v_mfma_f32_16x16x32_bf16 v[56:59], v[152:155], v[160:163], v[56:59]
	v_mfma_f32_16x16x32_bf16 v[48:51], v[144:147], v[168:171], v[48:51]
	v_mfma_f32_16x16x32_bf16 v[40:43], v[152:155], v[168:171], v[40:43]
	v_mfma_f32_16x16x32_bf16 v[32:35], v[144:147], v[176:179], v[32:35]
	v_mfma_f32_16x16x32_bf16 v[24:27], v[152:155], v[176:179], v[24:27]
	v_mfma_f32_16x16x32_bf16 v[16:19], v[144:147], v[184:187], v[16:19]
	v_mfma_f32_16x16x32_bf16 v[8:11], v[152:155], v[184:187], v[8:11]
	v_mfma_f32_16x16x32_bf16 v[60:63], v[148:151], v[164:167], v[60:63]
	v_mfma_f32_16x16x32_bf16 v[56:59], v[156:159], v[164:167], v[56:59]
	v_mfma_f32_16x16x32_bf16 v[48:51], v[148:151], v[172:175], v[48:51]
	v_mfma_f32_16x16x32_bf16 v[40:43], v[156:159], v[172:175], v[40:43]
	v_mfma_f32_16x16x32_bf16 v[32:35], v[148:151], v[180:183], v[32:35]
	v_mfma_f32_16x16x32_bf16 v[24:27], v[156:159], v[180:183], v[24:27]
	v_mfma_f32_16x16x32_bf16 v[16:19], v[148:151], v[188:191], v[16:19]
	v_mfma_f32_16x16x32_bf16 v[8:11], v[156:159], v[188:191], v[8:11]
	s_setprio 0
	s_barrier
	s_add_u32 s20, s20, 0x100080
	s_addc_u32 s21, s21, 0
	s_add_i32 s22, s24, s31
	v_lshl_add_u64 v[144:145], s[20:21], 0, v[130:131]
	s_mov_b32 m0, s22
	s_nop 0
	global_load_lds_dwordx4 v[144:145], off
	v_lshl_add_u64 v[144:145], s[20:21], 0, v[134:135]
	s_add_i32 m0, s22, 0x2000
	s_nop 0
	global_load_lds_dwordx4 v[144:145], off
	s_waitcnt vmcnt(6)
	s_barrier
	s_setprio 1
	v_mfma_f32_16x16x32_bf16 v[52:55], v[192:195], v[160:163], v[52:55]
	v_mfma_f32_16x16x32_bf16 v[44:47], v[206:209], v[160:163], v[44:47]
	v_mfma_f32_16x16x32_bf16 v[36:39], v[192:195], v[168:171], v[36:39]
	v_mfma_f32_16x16x32_bf16 v[28:31], v[206:209], v[168:171], v[28:31]
	v_mfma_f32_16x16x32_bf16 v[20:23], v[192:195], v[176:179], v[20:23]
	v_mfma_f32_16x16x32_bf16 v[12:15], v[206:209], v[176:179], v[12:15]
	v_mfma_f32_16x16x32_bf16 v[4:7], v[192:195], v[184:187], v[4:7]
	v_mfma_f32_16x16x32_bf16 v[0:3], v[206:209], v[184:187], v[0:3]
	v_mfma_f32_16x16x32_bf16 v[52:55], v[202:205], v[164:167], v[52:55]
	v_mfma_f32_16x16x32_bf16 v[44:47], v[210:213], v[164:167], v[44:47]
	v_mfma_f32_16x16x32_bf16 v[36:39], v[202:205], v[172:175], v[36:39]
	v_mfma_f32_16x16x32_bf16 v[28:31], v[210:213], v[172:175], v[28:31]
	v_mfma_f32_16x16x32_bf16 v[20:23], v[202:205], v[180:183], v[20:23]
	v_mfma_f32_16x16x32_bf16 v[12:15], v[210:213], v[180:183], v[12:15]
	v_mfma_f32_16x16x32_bf16 v[4:7], v[202:205], v[188:191], v[4:7]
	v_mfma_f32_16x16x32_bf16 v[0:3], v[210:213], v[188:191], v[0:3]
	s_setprio 0
	s_add_i32 s46, s46, 2
	s_add_u32 s44, s44, 0x100
	s_addc_u32 s45, s45, 0
	s_add_u32 s18, s18, 0x10000
	s_addc_u32 s19, s19, 0
	s_cmp_gt_u32 s46, 61
	s_barrier
	s_cbranch_scc0 .LBB0_789
	s_branch .Lpeel_exit_t789

; __device__ __forceinline__ float bflo(unsigned u) { return __uint_as_float(u << 16); }
; __device__ __forceinline__ float bfhi(unsigned u) { return __uint_as_float(u & 0xffff0000u); }
;     __device__ __forceinline__ void operator()(const f32x4 (&acc)[2][2][4][2], const Unit& u, int wr, int wc, int fr, int fq) const {
;         const int row0 = u.pm * 256 + wr * 64 + fr; const int col0 = u.pn * 256 + wc * 32 + 4 * fq;
;         u32x2 xv[2][4][2][2];
; #pragma unroll
;         for (int ai = 0; ai < 2; ++ai)
; #pragma unroll
;             for (int m = 0; m < 4; ++m)
; #pragma unroll
;                 for (int bj = 0; bj < 2; ++bj)
; #pragma unroll
;                     for (int n = 0; n < 2; ++n) xv[ai][m][bj][n] = *(const u32x2*)(x1b + (size_t)(row0 + ai * 128 + m * 16) * 1024 + col0 + bj * 128 + n * 16);
; #pragma unroll
;         for (int ai = 0; ai < 2; ++ai)
; #pragma unroll
;             for (int m = 0; m < 4; ++m)
; #pragma unroll
;                 for (int bj = 0; bj < 2; ++bj)
; #pragma unroll
;                     for (int n = 0; n < 2; ++n) {
;                         const size_t o = (size_t)(row0 + ai * 128 + m * 16) * 1024 + col0 + bj * 128 + n * 16;
;                         const u32x2 v = xv[ai][m][bj][n]; const f32x4 a = acc[ai][bj][m][n];
;                         *(f32x4*)(out + o) = (f32x4){bflo(v.x) + a[0], bfhi(v.x) + a[1], bflo(v.y) + a[2], bfhi(v.y) + a[3]};
.Lpeel_exit_t789:
	v_lshl_add_u32 v146, s16, 8, v196
	v_lshl_or_b32 v148, s41, 8, v198
	v_ashrrev_i32_e32 v149, 31, v148
	v_ashrrev_i32_e32 v147, 31, v146
	v_lshl_add_u64 v[150:151], v[148:149], 1, s[2:3]
	v_lshlrev_b64 v[144:145], 11, v[146:147]
	v_lshl_add_u64 v[144:145], v[150:151], 0, v[144:145]
	global_load_dwordx2 v[202:203], v[144:145], off
	global_load_dwordx2 v[204:205], v[144:145], off offset:32
	global_load_dwordx2 v[206:207], v[144:145], off offset:256
	v_or_b32_e32 v208, 16, v146
	global_load_dwordx2 v[210:211], v[144:145], off offset:288
	v_ashrrev_i32_e32 v209, 31, v208
	v_lshlrev_b64 v[144:145], 11, v[208:209]
	v_lshl_add_u64 v[152:153], v[150:151], 0, v[144:145]
	global_load_dwordx2 v[212:213], v[152:153], off
	global_load_dwordx2 v[214:215], v[152:153], off offset:32
	global_load_dwordx2 v[216:217], v[152:153], off offset:256
	global_load_dwordx2 v[218:219], v[152:153], off offset:288
	v_or_b32_e32 v192, 32, v146
	v_or_b32_e32 v182, 48, v146
	v_add_u32_e32 v174, 0x80, v146
	v_add_u32_e32 v164, 0x90, v146
	v_add_u32_e32 v154, 0xa0, v146
	v_add_u32_e32 v144, 0xb0, v146
	v_ashrrev_i32_e32 v193, 31, v192
	v_ashrrev_i32_e32 v183, 31, v182
	v_ashrrev_i32_e32 v175, 31, v174
	v_ashrrev_i32_e32 v165, 31, v164
	v_ashrrev_i32_e32 v155, 31, v154
	v_ashrrev_i32_e32 v145, 31, v144
	v_lshlrev_b64 v[146:147], 12, v[146:147]
	v_lshlrev_b64 v[156:157], 11, v[192:193]
	v_lshlrev_b64 v[158:159], 11, v[182:183]
	v_lshlrev_b64 v[160:161], 11, v[174:175]
	v_lshlrev_b64 v[162:163], 11, v[164:165]
	v_lshlrev_b64 v[166:167], 11, v[154:155]
	v_lshlrev_b64 v[148:149], 2, v[148:149]
	v_lshlrev_b64 v[168:169], 11, v[144:145]
	v_lshl_add_u64 v[146:147], s[4:5], 0, v[146:147]
	v_lshl_add_u64 v[156:157], v[150:151], 0, v[156:157]
	v_lshl_add_u64 v[158:159], v[150:151], 0, v[158:159]
	v_lshl_add_u64 v[160:161], v[150:151], 0, v[160:161]
	v_lshl_add_u64 v[162:163], v[150:151], 0, v[162:163]
	v_lshl_add_u64 v[152:153], v[150:151], 0, v[166:167]
	v_lshl_add_u64 v[220:221], v[150:151], 0, v[168:169]
	v_lshl_add_u64 v[222:223], v[146:147], 0, v[148:149]
	global_load_dwordx2 v[224:225], v[156:157], off
	global_load_dwordx2 v[226:227], v[156:157], off offset:32
	global_load_dwordx2 v[228:229], v[156:157], off offset:256
	global_load_dwordx2 v[230:231], v[156:157], off offset:288
	global_load_dwordx2 v[232:233], v[158:159], off
	global_load_dwordx2 v[194:195], v[158:159], off offset:32
	global_load_dwordx2 v[190:191], v[158:159], off offset:256
	global_load_dwordx2 v[188:189], v[158:159], off offset:288
	global_load_dwordx2 v[186:187], v[160:161], off
	global_load_dwordx2 v[184:185], v[160:161], off offset:32
	global_load_dwordx2 v[180:181], v[160:161], off offset:256
	global_load_dwordx2 v[178:179], v[160:161], off offset:288
	global_load_dwordx2 v[176:177], v[162:163], off
	global_load_dwordx2 v[172:173], v[162:163], off offset:32
	global_load_dwordx2 v[170:171], v[162:163], off offset:256
	global_load_dwordx2 v[168:169], v[162:163], off offset:288
	global_load_dwordx2 v[166:167], v[152:153], off
	s_nop 0
	global_load_dwordx2 v[162:163], v[152:153], off offset:32
	global_load_dwordx2 v[160:161], v[152:153], off offset:256
	global_load_dwordx2 v[158:159], v[152:153], off offset:288
	global_load_dwordx2 v[156:157], v[220:221], off
	s_nop 0
	global_load_dwordx2 v[152:153], v[220:221], off offset:32
	global_load_dwordx2 v[150:151], v[220:221], off offset:256
	global_load_dwordx2 v[146:147], v[220:221], off offset:288
	s_and_b64 vcc, exec, s[0:1]
	s_mov_b32 s41, s8
	s_mov_b32 s16, s10
	s_mov_b64 s[18:19], s[14:15]
	s_mov_b64 s[20:21], s[12:13]
	s_waitcnt vmcnt(0)
	v_lshlrev_b32_e32 v220, 16, v202
	v_and_b32_e32 v221, 0xffff0000, v202
	v_lshlrev_b32_e32 v202, 16, v203
	v_and_b32_e32 v203, 0xffff0000, v203
	v_lshlrev_b32_e32 v234, 16, v204
	v_and_b32_e32 v235, 0xffff0000, v204
	v_lshlrev_b32_e32 v204, 16, v205
	v_and_b32_e32 v205, 0xffff0000, v205
	v_pk_add_f32 v[124:125], v[124:125], v[220:221]
	v_pk_add_f32 v[126:127], v[126:127], v[202:203]
	v_pk_add_f32 v[120:121], v[120:121], v[234:235]
	v_lshlrev_b32_e32 v236, 16, v206
	v_and_b32_e32 v237, 0xffff0000, v206
	v_pk_add_f32 v[122:123], v[122:123], v[204:205]
	global_store_dwordx4 v[222:223], v[124:127], off
	global_store_dwordx4 v[222:223], v[120:123], off offset:64
	v_pk_add_f32 v[116:117], v[116:117], v[236:237]
	s_nop 0
	v_lshlrev_b32_e32 v120, 16, v207
	v_and_b32_e32 v121, 0xffff0000, v207
	v_pk_add_f32 v[118:119], v[118:119], v[120:121]
	global_store_dwordx4 v[222:223], v[116:119], off offset:512
	s_nop 1
	v_lshlrev_b32_e32 v116, 16, v210
	v_and_b32_e32 v117, 0xffff0000, v210
	v_pk_add_f32 v[108:109], v[108:109], v[116:117]
	v_lshlrev_b32_e32 v116, 16, v211
	v_and_b32_e32 v117, 0xffff0000, v211
	v_pk_add_f32 v[110:111], v[110:111], v[116:117]
	global_store_dwordx4 v[222:223], v[108:111], off offset:576
	v_lshlrev_b64 v[116:117], 12, v[208:209]
	s_nop 0
	v_lshlrev_b32_e32 v108, 16, v212
	v_and_b32_e32 v109, 0xffff0000, v212
	v_pk_add_f32 v[108:109], v[112:113], v[108:109]
	v_lshlrev_b32_e32 v110, 16, v213
	v_and_b32_e32 v111, 0xffff0000, v213
	v_lshl_add_u64 v[112:113], s[4:5], 0, v[116:117]
	v_pk_add_f32 v[110:111], v[114:115], v[110:111]
	v_lshl_add_u64 v[112:113], v[112:113], 0, v[148:149]
	global_store_dwordx4 v[112:113], v[108:111], off
	s_nop 1
	v_lshlrev_b32_e32 v108, 16, v214
	v_and_b32_e32 v109, 0xffff0000, v214
	v_pk_add_f32 v[104:105], v[104:105], v[108:109]
	v_lshlrev_b32_e32 v108, 16, v215
	v_and_b32_e32 v109, 0xffff0000, v215
	v_pk_add_f32 v[106:107], v[106:107], v[108:109]
	global_store_dwordx4 v[112:113], v[104:107], off offset:64
	s_nop 1
	v_lshlrev_b32_e32 v104, 16, v216
; __device__ __forceinline__ float bflo(unsigned u) { return __uint_as_float(u << 16); }
; __device__ __forceinline__ float bfhi(unsigned u) { return __uint_as_float(u & 0xffff0000u); }
;     __device__ __forceinline__ void operator()(const f32x4 (&acc)[2][2][4][2], const Unit& u, int wr, int wc, int fr, int fq) const {
;     ...
;         for (int ai = 0; ai < 2; ++ai)
; #pragma unroll
;             for (int m = 0; m < 4; ++m)
; #pragma unroll
;                 for (int bj = 0; bj < 2; ++bj)
; #pragma unroll
;                     for (int n = 0; n < 2; ++n) {
;                         const size_t o = (size_t)(row0 + ai * 128 + m * 16) * 1024 + col0 + bj * 128 + n * 16;
;                         const u32x2 v = xv[ai][m][bj][n]; const f32x4 a = acc[ai][bj][m][n];
;                         *(f32x4*)(out + o) = (f32x4){bflo(v.x) + a[0], bfhi(v.x) + a[1], bflo(v.y) + a[2], bfhi(v.y) + a[3]};
	v_and_b32_e32 v105, 0xffff0000, v216
	v_pk_add_f32 v[100:101], v[100:101], v[104:105]
	v_lshlrev_b32_e32 v104, 16, v217
	v_and_b32_e32 v105, 0xffff0000, v217
	v_pk_add_f32 v[102:103], v[102:103], v[104:105]
	global_store_dwordx4 v[112:113], v[100:103], off offset:512
	s_nop 1
	v_lshlrev_b32_e32 v100, 16, v218
	v_and_b32_e32 v101, 0xffff0000, v218
	v_pk_add_f32 v[92:93], v[92:93], v[100:101]
	v_lshlrev_b32_e32 v100, 16, v219
	v_and_b32_e32 v101, 0xffff0000, v219
	v_pk_add_f32 v[94:95], v[94:95], v[100:101]
	global_store_dwordx4 v[112:113], v[92:95], off offset:576
	v_lshlrev_b64 v[100:101], 12, v[192:193]
	s_nop 0
	v_lshlrev_b32_e32 v92, 16, v224
	v_and_b32_e32 v93, 0xffff0000, v224
	v_pk_add_f32 v[92:93], v[96:97], v[92:93]
	v_lshlrev_b32_e32 v94, 16, v225
	v_and_b32_e32 v95, 0xffff0000, v225
	v_lshl_add_u64 v[96:97], s[4:5], 0, v[100:101]
	v_pk_add_f32 v[94:95], v[98:99], v[94:95]
	v_lshl_add_u64 v[96:97], v[96:97], 0, v[148:149]
	global_store_dwordx4 v[96:97], v[92:95], off
	s_nop 1
	v_lshlrev_b32_e32 v92, 16, v226
	v_and_b32_e32 v93, 0xffff0000, v226
	v_pk_add_f32 v[88:89], v[88:89], v[92:93]
	v_lshlrev_b32_e32 v92, 16, v227
	v_and_b32_e32 v93, 0xffff0000, v227
	v_pk_add_f32 v[90:91], v[90:91], v[92:93]
	global_store_dwordx4 v[96:97], v[88:91], off offset:64
	s_nop 1
	v_lshlrev_b32_e32 v88, 16, v228
	v_and_b32_e32 v89, 0xffff0000, v228
	v_pk_add_f32 v[84:85], v[84:85], v[88:89]
	v_lshlrev_b32_e32 v88, 16, v229
	v_and_b32_e32 v89, 0xffff0000, v229
	v_pk_add_f32 v[86:87], v[86:87], v[88:89]
	global_store_dwordx4 v[96:97], v[84:87], off offset:512
	s_nop 1
	v_lshlrev_b32_e32 v84, 16, v230
	v_and_b32_e32 v85, 0xffff0000, v230
	v_pk_add_f32 v[76:77], v[76:77], v[84:85]
	v_lshlrev_b32_e32 v84, 16, v231
	v_and_b32_e32 v85, 0xffff0000, v231
	v_pk_add_f32 v[78:79], v[78:79], v[84:85]
	global_store_dwordx4 v[96:97], v[76:79], off offset:576
	v_lshlrev_b64 v[84:85], 12, v[182:183]
	s_nop 0
	v_lshlrev_b32_e32 v76, 16, v232
	v_and_b32_e32 v77, 0xffff0000, v232
	v_pk_add_f32 v[76:77], v[80:81], v[76:77]
	v_lshlrev_b32_e32 v78, 16, v233
	v_and_b32_e32 v79, 0xffff0000, v233
	v_lshl_add_u64 v[80:81], s[4:5], 0, v[84:85]
	v_pk_add_f32 v[78:79], v[82:83], v[78:79]
	v_lshl_add_u64 v[80:81], v[80:81], 0, v[148:149]
	global_store_dwordx4 v[80:81], v[76:79], off
	s_nop 1
	v_lshlrev_b32_e32 v76, 16, v194
	v_and_b32_e32 v77, 0xffff0000, v194
	v_pk_add_f32 v[72:73], v[72:73], v[76:77]
	v_lshlrev_b32_e32 v76, 16, v195
	v_and_b32_e32 v77, 0xffff0000, v195
	v_pk_add_f32 v[74:75], v[74:75], v[76:77]
	global_store_dwordx4 v[80:81], v[72:75], off offset:64
	s_nop 1
	v_lshlrev_b32_e32 v72, 16, v190
	v_and_b32_e32 v73, 0xffff0000, v190
	v_pk_add_f32 v[68:69], v[68:69], v[72:73]
	v_lshlrev_b32_e32 v72, 16, v191
	v_and_b32_e32 v73, 0xffff0000, v191
	v_pk_add_f32 v[70:71], v[70:71], v[72:73]
	global_store_dwordx4 v[80:81], v[68:71], off offset:512
	s_nop 1
	v_lshlrev_b32_e32 v68, 16, v188
	v_and_b32_e32 v69, 0xffff0000, v188
	v_pk_add_f32 v[64:65], v[64:65], v[68:69]
	v_lshlrev_b32_e32 v68, 16, v189
	v_and_b32_e32 v69, 0xffff0000, v189
	v_pk_add_f32 v[66:67], v[66:67], v[68:69]
	global_store_dwordx4 v[80:81], v[64:67], off offset:576
	s_nop 1
	v_lshlrev_b64 v[64:65], 12, v[174:175]
	v_lshlrev_b32_e32 v66, 16, v186
	v_and_b32_e32 v67, 0xffff0000, v186
	v_pk_add_f32 v[60:61], v[60:61], v[66:67]
	v_lshlrev_b32_e32 v66, 16, v187
	v_and_b32_e32 v67, 0xffff0000, v187
	v_lshl_add_u64 v[64:65], s[4:5], 0, v[64:65]
	v_pk_add_f32 v[62:63], v[62:63], v[66:67]
	v_lshl_add_u64 v[64:65], v[64:65], 0, v[148:149]
	global_store_dwordx4 v[64:65], v[60:63], off
	s_nop 1
	v_lshlrev_b32_e32 v60, 16, v184
	v_and_b32_e32 v61, 0xffff0000, v184
	v_pk_add_f32 v[56:57], v[56:57], v[60:61]
	v_lshlrev_b32_e32 v60, 16, v185
	v_and_b32_e32 v61, 0xffff0000, v185
	v_pk_add_f32 v[58:59], v[58:59], v[60:61]
	global_store_dwordx4 v[64:65], v[56:59], off offset:64
	s_nop 1
	v_lshlrev_b32_e32 v56, 16, v180
	v_and_b32_e32 v57, 0xffff0000, v180
	v_pk_add_f32 v[52:53], v[52:53], v[56:57]
	v_lshlrev_b32_e32 v56, 16, v181
	v_and_b32_e32 v57, 0xffff0000, v181
	v_pk_add_f32 v[54:55], v[54:55], v[56:57]
	global_store_dwordx4 v[64:65], v[52:55], off offset:512
	s_nop 1
	v_lshlrev_b32_e32 v52, 16, v178
; __device__ __forceinline__ float bflo(unsigned u) { return __uint_as_float(u << 16); }
; __device__ __forceinline__ float bfhi(unsigned u) { return __uint_as_float(u & 0xffff0000u); }
; #define PG8_WAIT_V(n) asm volatile("s_waitcnt vmcnt(" #n ")" ::: "memory")
; #define PG8_BAR __builtin_amdgcn_s_barrier()
; template <class Epi, class Sched>
; __device__ __forceinline__ void gemm_phase(const int wv, LAS unsigned char* lds, const Gemm g, const Sched& S, const Epi& E) {
;     ...
;         E(acc, cur, wr, wc, fr, fq); S.done(cur);
;         if (!has_next) break;
; #pragma unroll
;         for (int a = 0; a < 2; ++a)
; #pragma unroll
;             for (int b = 0; b < 2; ++b)
; #pragma unroll
;                 for (int m = 0; m < 4; ++m)
; #pragma unroll
;                     for (int n = 0; n < 2; ++n) acc[a][b][m][n] = (f32x4){0.f, 0.f, 0.f, 0.f};
;         cur = nxt; cA = nA; cB = nB; ++ui;
;     }
;     PG8_WAIT_V(0);
;     if (wr == 0) PG8_BAR;
;     __device__ __forceinline__ void operator()(const f32x4 (&acc)[2][2][4][2], const Unit& u, int wr, int wc, int fr, int fq) const {
;     ...
;         for (int ai = 0; ai < 2; ++ai)
; #pragma unroll
;             for (int m = 0; m < 4; ++m)
; #pragma unroll
;                 for (int bj = 0; bj < 2; ++bj)
; #pragma unroll
;                     for (int n = 0; n < 2; ++n) {
;                         const size_t o = (size_t)(row0 + ai * 128 + m * 16) * 1024 + col0 + bj * 128 + n * 16;
;                         const u32x2 v = xv[ai][m][bj][n]; const f32x4 a = acc[ai][bj][m][n];
;                         *(f32x4*)(out + o) = (f32x4){bflo(v.x) + a[0], bfhi(v.x) + a[1], bflo(v.y) + a[2], bfhi(v.y) + a[3]};
	v_and_b32_e32 v53, 0xffff0000, v178
	v_pk_add_f32 v[44:45], v[44:45], v[52:53]
	v_lshlrev_b32_e32 v52, 16, v179
	v_and_b32_e32 v53, 0xffff0000, v179
	v_pk_add_f32 v[46:47], v[46:47], v[52:53]
	global_store_dwordx4 v[64:65], v[44:47], off offset:576
	v_lshlrev_b64 v[52:53], 12, v[164:165]
	s_nop 0
	v_lshlrev_b32_e32 v44, 16, v176
	v_and_b32_e32 v45, 0xffff0000, v176
	v_pk_add_f32 v[44:45], v[48:49], v[44:45]
	v_lshlrev_b32_e32 v46, 16, v177
	v_and_b32_e32 v47, 0xffff0000, v177
	v_lshl_add_u64 v[48:49], s[4:5], 0, v[52:53]
	v_pk_add_f32 v[46:47], v[50:51], v[46:47]
	v_lshl_add_u64 v[48:49], v[48:49], 0, v[148:149]
	global_store_dwordx4 v[48:49], v[44:47], off
	s_nop 1
	v_lshlrev_b32_e32 v44, 16, v172
	v_and_b32_e32 v45, 0xffff0000, v172
	v_pk_add_f32 v[40:41], v[40:41], v[44:45]
	v_lshlrev_b32_e32 v44, 16, v173
	v_and_b32_e32 v45, 0xffff0000, v173
	v_pk_add_f32 v[42:43], v[42:43], v[44:45]
	global_store_dwordx4 v[48:49], v[40:43], off offset:64
	s_nop 1
	v_lshlrev_b32_e32 v40, 16, v170
	v_and_b32_e32 v41, 0xffff0000, v170
	v_pk_add_f32 v[36:37], v[36:37], v[40:41]
	v_lshlrev_b32_e32 v40, 16, v171
	v_and_b32_e32 v41, 0xffff0000, v171
	v_pk_add_f32 v[38:39], v[38:39], v[40:41]
	global_store_dwordx4 v[48:49], v[36:39], off offset:512
	s_nop 1
	v_lshlrev_b32_e32 v36, 16, v168
	v_and_b32_e32 v37, 0xffff0000, v168
	v_pk_add_f32 v[28:29], v[28:29], v[36:37]
	v_lshlrev_b32_e32 v36, 16, v169
	v_and_b32_e32 v37, 0xffff0000, v169
	v_pk_add_f32 v[30:31], v[30:31], v[36:37]
	global_store_dwordx4 v[48:49], v[28:31], off offset:576
	v_lshlrev_b64 v[36:37], 12, v[154:155]
	s_nop 0
	v_lshlrev_b32_e32 v28, 16, v166
	v_and_b32_e32 v29, 0xffff0000, v166
	v_pk_add_f32 v[28:29], v[32:33], v[28:29]
	v_lshlrev_b32_e32 v30, 16, v167
	v_and_b32_e32 v31, 0xffff0000, v167
	v_lshl_add_u64 v[32:33], s[4:5], 0, v[36:37]
	v_pk_add_f32 v[30:31], v[34:35], v[30:31]
	v_lshl_add_u64 v[32:33], v[32:33], 0, v[148:149]
	global_store_dwordx4 v[32:33], v[28:31], off
	s_nop 1
	v_lshlrev_b32_e32 v28, 16, v162
	v_and_b32_e32 v29, 0xffff0000, v162
	v_pk_add_f32 v[24:25], v[24:25], v[28:29]
	v_lshlrev_b32_e32 v28, 16, v163
	v_and_b32_e32 v29, 0xffff0000, v163
	v_pk_add_f32 v[26:27], v[26:27], v[28:29]
	global_store_dwordx4 v[32:33], v[24:27], off offset:64
	s_nop 1
	v_lshlrev_b32_e32 v24, 16, v160
	v_and_b32_e32 v25, 0xffff0000, v160
	v_pk_add_f32 v[20:21], v[20:21], v[24:25]
	v_lshlrev_b32_e32 v24, 16, v161
	v_and_b32_e32 v25, 0xffff0000, v161
	v_pk_add_f32 v[22:23], v[22:23], v[24:25]
	global_store_dwordx4 v[32:33], v[20:23], off offset:512
	s_nop 1
	v_lshlrev_b32_e32 v20, 16, v158
	v_and_b32_e32 v21, 0xffff0000, v158
	v_pk_add_f32 v[12:13], v[12:13], v[20:21]
	v_lshlrev_b32_e32 v20, 16, v159
	v_and_b32_e32 v21, 0xffff0000, v159
	v_pk_add_f32 v[14:15], v[14:15], v[20:21]
	global_store_dwordx4 v[32:33], v[12:15], off offset:576
	v_lshlrev_b64 v[20:21], 12, v[144:145]
	s_nop 0
	v_lshlrev_b32_e32 v12, 16, v156
	v_and_b32_e32 v13, 0xffff0000, v156
	v_pk_add_f32 v[12:13], v[16:17], v[12:13]
	v_lshlrev_b32_e32 v14, 16, v157
	v_and_b32_e32 v15, 0xffff0000, v157
	v_lshl_add_u64 v[16:17], s[4:5], 0, v[20:21]
	v_pk_add_f32 v[14:15], v[18:19], v[14:15]
	v_lshl_add_u64 v[16:17], v[16:17], 0, v[148:149]
	global_store_dwordx4 v[16:17], v[12:15], off
	s_nop 1
	v_lshlrev_b32_e32 v12, 16, v152
	v_and_b32_e32 v13, 0xffff0000, v152
	v_pk_add_f32 v[8:9], v[8:9], v[12:13]
	v_lshlrev_b32_e32 v12, 16, v153
	v_and_b32_e32 v13, 0xffff0000, v153
	v_pk_add_f32 v[10:11], v[10:11], v[12:13]
	global_store_dwordx4 v[16:17], v[8:11], off offset:64
	s_nop 1
	v_lshlrev_b32_e32 v8, 16, v150
	v_and_b32_e32 v9, 0xffff0000, v150
	v_pk_add_f32 v[4:5], v[4:5], v[8:9]
	v_lshlrev_b32_e32 v8, 16, v151
	v_and_b32_e32 v9, 0xffff0000, v151
	v_pk_add_f32 v[6:7], v[6:7], v[8:9]
	global_store_dwordx4 v[16:17], v[4:7], off offset:512
	s_nop 1
	v_lshlrev_b32_e32 v4, 16, v146
	v_and_b32_e32 v5, 0xffff0000, v146
	v_pk_add_f32 v[0:1], v[0:1], v[4:5]
	v_lshlrev_b32_e32 v4, 16, v147
	v_and_b32_e32 v5, 0xffff0000, v147
	v_pk_add_f32 v[2:3], v[2:3], v[4:5]
	global_store_dwordx4 v[16:17], v[0:3], off offset:576
	s_cbranch_vccz .LBB0_782
	s_waitcnt vmcnt(0)
	s_cmpk_gt_u32 s26, 0xff
	s_cbranch_scc1 .LBB0_793
	s_barrier
